# hand-written ConvFFN up-projection epilogue: packed f32 math, conv taps as fused DPP row-shift fmacs (no cndmask/mov), next-column weights prefetched into dead accumulators
# speedup vs baseline: 1.0530x; 1.0304x over previous
.LBB0_359:
	s_or_b64 exec, exec, s[0:1]
	s_and_b64 vcc, exec, s[4:5]
	s_mov_b64 s[6:7], s[34:35]
	s_mov_b64 s[8:9], s[36:37]
	s_mov_b32 s1, s28
	s_mov_b32 s0, s30
	s_cbranch_vccnz .LBB0_374

.LBB0_363:
	ds_read_b128 v[76:79], v231
	v_xor_b32_e32 v91, 64, v231
	ds_read_b128 v[80:83], v91
	ds_read_b128 v[84:87], v231 offset:2048
	ds_read_b128 v[88:91], v91 offset:2048
	s_add_u32 s8, s6, 0x100
	s_addc_u32 s9, s7, 0
	s_cmp_eq_u32 s65, 28
	s_cselect_b32 s39, s31, s9
	s_cselect_b32 s38, s33, s8
	s_cselect_b32 s11, s29, s64
	s_cselect_b32 s10, s62, s63
	v_lshl_add_u64 v[108:109], s[6:7], 0, v[172:173]
	s_add_i32 m0, s44, 0xc000
	ds_read_b128 v[92:95], v241
	v_xor_b32_e32 v195, 64, v241
	ds_read_b128 v[96:99], v195
	ds_read_b128 v[100:103], v241 offset:2048
	ds_read_b128 v[104:107], v195 offset:2048
	ds_read_b128 v[180:183], v241 offset:4096
	ds_read_b128 v[184:187], v195 offset:4096
	ds_read_b128 v[188:191], v241 offset:6144
	ds_read_b128 v[192:195], v195 offset:6144
	global_load_lds_dwordx4 v[108:109], off
	v_lshl_add_u64 v[108:109], s[6:7], 0, v[174:175]
	s_add_i32 m0, s44, 0xe000
	s_nop 0
	global_load_lds_dwordx4 v[108:109], off
	s_waitcnt lgkmcnt(8)
	s_barrier
	s_waitcnt lgkmcnt(0)
	s_setprio 1
	s_waitcnt lgkmcnt(0)
	v_mfma_f32_16x16x32_bf16 v[158:161], v[76:79], v[92:95], v[158:161]
	v_mfma_f32_16x16x32_bf16 v[158:161], v[80:83], v[96:99], v[158:161]
	v_mfma_f32_16x16x32_bf16 v[60:63], v[88:91], v[96:99], v[60:63]
	v_mfma_f32_16x16x32_bf16 v[60:63], v[84:87], v[92:95], v[60:63]
	v_mfma_f32_16x16x32_bf16 v[52:55], v[84:87], v[100:103], v[52:55]
	v_mfma_f32_16x16x32_bf16 v[52:55], v[88:91], v[104:107], v[52:55]
	v_mfma_f32_16x16x32_bf16 v[150:153], v[80:83], v[104:107], v[150:153]
	v_mfma_f32_16x16x32_bf16 v[150:153], v[76:79], v[100:103], v[150:153]
	v_mfma_f32_16x16x32_bf16 v[146:149], v[76:79], v[180:183], v[146:149]
	v_mfma_f32_16x16x32_bf16 v[146:149], v[80:83], v[184:187], v[146:149]
	v_mfma_f32_16x16x32_bf16 v[48:51], v[88:91], v[184:187], v[48:51]
	v_mfma_f32_16x16x32_bf16 v[48:51], v[84:87], v[180:183], v[48:51]
	v_mfma_f32_16x16x32_bf16 v[40:43], v[84:87], v[188:191], v[40:43]
	v_mfma_f32_16x16x32_bf16 v[40:43], v[88:91], v[192:195], v[40:43]
	v_mfma_f32_16x16x32_bf16 v[138:141], v[80:83], v[192:195], v[138:141]
	v_mfma_f32_16x16x32_bf16 v[138:141], v[76:79], v[188:191], v[138:141]
	s_setprio 0
	s_barrier
	s_add_i32 s6, s58, s42
	v_lshl_add_u64 v[216:217], s[10:11], 0, v[164:165]
	s_mov_b32 m0, s6
	ds_read_b128 v[196:199], v242
	v_xor_b32_e32 v211, 64, v242
	ds_read_b128 v[200:203], v211
	ds_read_b128 v[204:207], v242 offset:2048
	ds_read_b128 v[208:211], v211 offset:2048
	global_load_lds_dwordx4 v[216:217], off
	v_lshl_add_u64 v[244:245], s[10:11], 0, v[166:167]
	s_add_i32 m0, s6, 0x2000
	s_nop 0
	global_load_lds_dwordx4 v[244:245], off
	s_barrier
	s_waitcnt lgkmcnt(0)
	s_setprio 1
	s_waitcnt lgkmcnt(0)
	v_mfma_f32_16x16x32_bf16 v[154:157], v[196:199], v[92:95], v[154:157]
	v_mfma_f32_16x16x32_bf16 v[154:157], v[200:203], v[96:99], v[154:157]
	v_mfma_f32_16x16x32_bf16 v[56:59], v[208:211], v[96:99], v[56:59]
	v_mfma_f32_16x16x32_bf16 v[56:59], v[204:207], v[92:95], v[56:59]
	v_mfma_f32_16x16x32_bf16 v[44:47], v[204:207], v[100:103], v[44:47]
	v_mfma_f32_16x16x32_bf16 v[44:47], v[208:211], v[104:107], v[44:47]
	v_mfma_f32_16x16x32_bf16 v[36:39], v[208:211], v[184:187], v[36:39]
	v_mfma_f32_16x16x32_bf16 v[36:39], v[204:207], v[180:183], v[36:39]
	v_mfma_f32_16x16x32_bf16 v[32:35], v[204:207], v[188:191], v[32:35]
	v_mfma_f32_16x16x32_bf16 v[32:35], v[208:211], v[192:195], v[32:35]
	v_mfma_f32_16x16x32_bf16 v[92:95], v[196:199], v[100:103], v[142:145]
	v_mfma_f32_16x16x32_bf16 v[92:95], v[200:203], v[104:107], v[92:95]
	v_mfma_f32_16x16x32_bf16 v[96:99], v[200:203], v[184:187], v[134:137]
	v_mfma_f32_16x16x32_bf16 v[96:99], v[196:199], v[180:183], v[96:99]
	v_mfma_f32_16x16x32_bf16 v[100:103], v[196:199], v[188:191], v[130:133]
	v_mfma_f32_16x16x32_bf16 v[100:103], v[200:203], v[192:195], v[100:103]
	s_setprio 0
	s_mov_b32 m0, s44
	v_lshl_add_u64 v[246:247], s[38:39], 0, v[170:171]
	s_barrier
	ds_read_b128 v[104:107], v241 offset:16384
	v_xor_b32_e32 v195, 64, v241
	ds_read_b128 v[130:133], v195 offset:16384
	ds_read_b128 v[134:137], v241 offset:18432
	ds_read_b128 v[142:145], v195 offset:18432
	ds_read_b128 v[180:183], v241 offset:20480
	ds_read_b128 v[184:187], v195 offset:20480
	ds_read_b128 v[188:191], v241 offset:22528
	ds_read_b128 v[192:195], v195 offset:22528
	global_load_lds_dwordx4 v[246:247], off
	v_lshl_add_u64 v[248:249], s[38:39], 0, v[168:169]
	s_mov_b32 m0, s45
	s_nop 0
	global_load_lds_dwordx4 v[248:249], off
	s_barrier
	s_waitcnt lgkmcnt(0)
	s_setprio 1
	s_waitcnt lgkmcnt(0)
	v_mfma_f32_16x16x32_bf16 v[126:129], v[76:79], v[104:107], v[126:129]
	v_mfma_f32_16x16x32_bf16 v[126:129], v[80:83], v[130:133], v[126:129]
	v_mfma_f32_16x16x32_bf16 v[28:31], v[88:91], v[130:133], v[28:31]
	v_mfma_f32_16x16x32_bf16 v[28:31], v[84:87], v[104:107], v[28:31]
	v_mfma_f32_16x16x32_bf16 v[24:27], v[84:87], v[134:137], v[24:27]
	v_mfma_f32_16x16x32_bf16 v[24:27], v[88:91], v[142:145], v[24:27]
	v_mfma_f32_16x16x32_bf16 v[122:125], v[80:83], v[142:145], v[122:125]
	v_mfma_f32_16x16x32_bf16 v[122:125], v[76:79], v[134:137], v[122:125]
	v_mfma_f32_16x16x32_bf16 v[114:117], v[76:79], v[180:183], v[114:117]
	v_mfma_f32_16x16x32_bf16 v[114:117], v[80:83], v[184:187], v[114:117]
	v_mfma_f32_16x16x32_bf16 v[20:23], v[88:91], v[184:187], v[20:23]
	v_mfma_f32_16x16x32_bf16 v[20:23], v[84:87], v[180:183], v[20:23]
	v_mfma_f32_16x16x32_bf16 v[4:7], v[84:87], v[188:191], v[4:7]
	v_mfma_f32_16x16x32_bf16 v[4:7], v[88:91], v[192:195], v[4:7]
	v_mfma_f32_16x16x32_bf16 v[72:75], v[80:83], v[192:195], v[72:75]
	v_mfma_f32_16x16x32_bf16 v[72:75], v[76:79], v[188:191], v[72:75]
	s_setprio 0
	s_barrier
	s_add_u32 s6, s10, 0x1600000
	s_addc_u32 s7, s11, 0
	s_add_i32 s66, s59, s42
	v_lshl_add_u64 v[76:77], s[6:7], 0, v[164:165]
	s_mov_b32 m0, s66
	s_nop 0
	global_load_lds_dwordx4 v[76:77], off
	v_lshl_add_u64 v[76:77], s[6:7], 0, v[166:167]
	s_add_i32 m0, s66, 0x2000
	s_nop 0
	global_load_lds_dwordx4 v[76:77], off
	s_waitcnt vmcnt(6)
	s_barrier
	s_setprio 1
	v_mfma_f32_16x16x32_bf16 v[16:19], v[204:207], v[104:107], v[16:19]
	v_mfma_f32_16x16x32_bf16 v[16:19], v[208:211], v[130:133], v[16:19]
	v_mfma_f32_16x16x32_bf16 v[12:15], v[208:211], v[142:145], v[12:15]
	v_mfma_f32_16x16x32_bf16 v[12:15], v[204:207], v[134:137], v[12:15]
	v_mfma_f32_16x16x32_bf16 v[8:11], v[204:207], v[180:183], v[8:11]
	v_mfma_f32_16x16x32_bf16 v[8:11], v[208:211], v[184:187], v[8:11]
	v_mfma_f32_16x16x32_bf16 v[68:71], v[200:203], v[184:187], v[68:71]
	v_mfma_f32_16x16x32_bf16 v[68:71], v[196:199], v[180:183], v[68:71]
	v_mfma_f32_16x16x32_bf16 v[64:67], v[196:199], v[188:191], v[64:67]
	v_mfma_f32_16x16x32_bf16 v[64:67], v[200:203], v[192:195], v[64:67]
	v_mfma_f32_16x16x32_bf16 v[0:3], v[208:211], v[192:195], v[0:3]
	v_mfma_f32_16x16x32_bf16 v[0:3], v[204:207], v[188:191], v[0:3]
	v_mfma_f32_16x16x32_bf16 v[76:79], v[196:199], v[104:107], v[118:121]
	v_mfma_f32_16x16x32_bf16 v[76:79], v[200:203], v[130:133], v[76:79]
	v_mfma_f32_16x16x32_bf16 v[80:83], v[200:203], v[142:145], v[110:113]
	v_mfma_f32_16x16x32_bf16 v[80:83], v[196:199], v[134:137], v[80:83]
	s_setprio 0
	s_add_i32 s66, 0, 0x18000
	v_add_u32_e32 v108, s66, v229
	s_barrier
	ds_read_b128 v[84:87], v108
	v_xor_b32_e32 v111, 64, v108
	ds_read_b128 v[88:91], v111
	ds_read_b128 v[104:107], v108 offset:2048
	ds_read_b128 v[108:111], v111 offset:2048
	s_add_u32 s6, s38, 0x40000
	s_addc_u32 s7, s39, 0
	s_mov_b32 m0, s46
	v_lshl_add_u64 v[112:113], s[6:7], 0, v[170:171]
	ds_read_b128 v[118:121], v241 offset:32768
	v_xor_b32_e32 v199, 64, v241
	ds_read_b128 v[130:133], v199 offset:32768
	ds_read_b128 v[134:137], v241 offset:34816
	ds_read_b128 v[180:183], v199 offset:34816
	ds_read_b128 v[184:187], v241 offset:36864
	ds_read_b128 v[188:191], v199 offset:36864
	ds_read_b128 v[192:195], v241 offset:38912
	ds_read_b128 v[196:199], v199 offset:38912
	global_load_lds_dwordx4 v[112:113], off
	v_lshl_add_u64 v[112:113], s[6:7], 0, v[168:169]
	s_mov_b32 m0, s47
	s_nop 0
	global_load_lds_dwordx4 v[112:113], off
	s_waitcnt lgkmcnt(8)
	s_barrier
	s_waitcnt lgkmcnt(0)
	s_setprio 1
	s_waitcnt lgkmcnt(0)
	v_mfma_f32_16x16x32_bf16 v[142:145], v[84:87], v[118:121], v[158:161]
	v_mfma_f32_16x16x32_bf16 v[158:161], v[88:91], v[130:133], v[142:145]
	v_mfma_f32_16x16x32_bf16 v[60:63], v[108:111], v[130:133], v[60:63]
	v_mfma_f32_16x16x32_bf16 v[60:63], v[104:107], v[118:121], v[60:63]
	v_mfma_f32_16x16x32_bf16 v[52:55], v[104:107], v[134:137], v[52:55]
	v_mfma_f32_16x16x32_bf16 v[52:55], v[108:111], v[180:183], v[52:55]
	v_mfma_f32_16x16x32_bf16 v[48:51], v[108:111], v[188:191], v[48:51]
	v_mfma_f32_16x16x32_bf16 v[48:51], v[104:107], v[184:187], v[48:51]
	v_mfma_f32_16x16x32_bf16 v[40:43], v[104:107], v[192:195], v[40:43]
	v_mfma_f32_16x16x32_bf16 v[40:43], v[108:111], v[196:199], v[40:43]
	v_mfma_f32_16x16x32_bf16 v[138:141], v[88:91], v[196:199], v[138:141]
	v_mfma_f32_16x16x32_bf16 v[138:141], v[84:87], v[192:195], v[138:141]
	v_mfma_f32_16x16x32_bf16 v[142:145], v[84:87], v[134:137], v[150:153]
	v_mfma_f32_16x16x32_bf16 v[150:153], v[88:91], v[180:183], v[142:145]
	v_mfma_f32_16x16x32_bf16 v[142:145], v[84:87], v[184:187], v[146:149]
	v_mfma_f32_16x16x32_bf16 v[146:149], v[88:91], v[188:191], v[142:145]
	s_setprio 0
	s_barrier
	s_add_i32 s38, 0, 0x1c000
	v_add_u32_e32 v112, s38, v229
	s_add_i32 s6, s66, s42
	ds_read_b128 v[200:203], v112
	v_xor_b32_e32 v215, 64, v112
	ds_read_b128 v[204:207], v215
	ds_read_b128 v[208:211], v112 offset:2048
	ds_read_b128 v[212:215], v215 offset:2048
	v_lshl_add_u64 v[112:113], v[216:217], 0, s[14:15]
	s_mov_b32 m0, s6
	s_nop 0
	global_load_lds_dwordx4 v[112:113], off
	v_lshl_add_u64 v[112:113], v[244:245], 0, s[14:15]
	s_add_i32 m0, s6, 0x2000
	s_nop 0
	global_load_lds_dwordx4 v[112:113], off
	s_barrier
	s_waitcnt lgkmcnt(0)
	s_setprio 1
	s_waitcnt lgkmcnt(0)
	v_mfma_f32_16x16x32_bf16 v[142:145], v[200:203], v[118:121], v[154:157]
	v_mfma_f32_16x16x32_bf16 v[154:157], v[204:207], v[130:133], v[142:145]
	v_mfma_f32_16x16x32_bf16 v[56:59], v[212:215], v[130:133], v[56:59]
	v_mfma_f32_16x16x32_bf16 v[56:59], v[208:211], v[118:121], v[56:59]
	v_mfma_f32_16x16x32_bf16 v[44:47], v[208:211], v[134:137], v[44:47]
	v_mfma_f32_16x16x32_bf16 v[44:47], v[212:215], v[180:183], v[44:47]
	v_mfma_f32_16x16x32_bf16 v[36:39], v[212:215], v[188:191], v[36:39]
	v_mfma_f32_16x16x32_bf16 v[36:39], v[208:211], v[184:187], v[36:39]
	v_mfma_f32_16x16x32_bf16 v[32:35], v[208:211], v[192:195], v[32:35]
	v_mfma_f32_16x16x32_bf16 v[32:35], v[212:215], v[196:199], v[32:35]
	v_mfma_f32_16x16x32_bf16 v[92:95], v[200:203], v[134:137], v[92:95]
	v_mfma_f32_16x16x32_bf16 v[142:145], v[204:207], v[180:183], v[92:95]
	v_mfma_f32_16x16x32_bf16 v[92:95], v[200:203], v[184:187], v[96:99]
	v_mfma_f32_16x16x32_bf16 v[134:137], v[204:207], v[188:191], v[92:95]
	v_mfma_f32_16x16x32_bf16 v[92:95], v[200:203], v[192:195], v[100:103]
	v_mfma_f32_16x16x32_bf16 v[130:133], v[204:207], v[196:199], v[92:95]
	s_setprio 0
	s_mov_b32 m0, s52
	v_lshl_add_u64 v[112:113], v[246:247], 0, s[14:15]
	s_barrier
	ds_read_b128 v[92:95], v241 offset:49152
	v_xor_b32_e32 v199, 64, v241
	ds_read_b128 v[96:99], v199 offset:49152
	ds_read_b128 v[100:103], v241 offset:51200
	ds_read_b128 v[180:183], v199 offset:51200
	ds_read_b128 v[184:187], v241 offset:53248
	ds_read_b128 v[188:191], v199 offset:53248
	ds_read_b128 v[192:195], v241 offset:55296
	ds_read_b128 v[196:199], v199 offset:55296
	global_load_lds_dwordx4 v[112:113], off
	v_lshl_add_u64 v[112:113], v[248:249], 0, s[14:15]
	s_mov_b32 m0, s53
	s_nop 0
	global_load_lds_dwordx4 v[112:113], off
	s_barrier
	s_waitcnt lgkmcnt(0)
	s_setprio 1
	s_waitcnt lgkmcnt(0)
	v_mfma_f32_16x16x32_bf16 v[118:121], v[84:87], v[92:95], v[126:129]
	v_mfma_f32_16x16x32_bf16 v[126:129], v[88:91], v[96:99], v[118:121]
	v_mfma_f32_16x16x32_bf16 v[28:31], v[108:111], v[96:99], v[28:31]
	v_mfma_f32_16x16x32_bf16 v[28:31], v[104:107], v[92:95], v[28:31]
	v_mfma_f32_16x16x32_bf16 v[24:27], v[104:107], v[100:103], v[24:27]
	v_mfma_f32_16x16x32_bf16 v[24:27], v[108:111], v[180:183], v[24:27]
	v_mfma_f32_16x16x32_bf16 v[20:23], v[108:111], v[188:191], v[20:23]
	v_mfma_f32_16x16x32_bf16 v[20:23], v[104:107], v[184:187], v[20:23]
	v_mfma_f32_16x16x32_bf16 v[112:115], v[84:87], v[184:187], v[114:117]
	v_mfma_f32_16x16x32_bf16 v[114:117], v[88:91], v[188:191], v[112:115]
	v_mfma_f32_16x16x32_bf16 v[72:75], v[88:91], v[196:199], v[72:75]
	v_mfma_f32_16x16x32_bf16 v[72:75], v[84:87], v[192:195], v[72:75]
	v_mfma_f32_16x16x32_bf16 v[118:121], v[84:87], v[100:103], v[122:125]
	v_mfma_f32_16x16x32_bf16 v[122:125], v[88:91], v[180:183], v[118:121]
	v_mfma_f32_16x16x32_bf16 v[4:7], v[104:107], v[192:195], v[4:7]
	v_mfma_f32_16x16x32_bf16 v[4:7], v[108:111], v[196:199], v[4:7]
	s_setprio 0
	s_barrier
	s_add_u32 s6, s10, 0x1600080
	s_addc_u32 s7, s11, 0
	s_add_i32 s10, s38, s42
	v_lshl_add_u64 v[84:85], s[6:7], 0, v[164:165]
	s_mov_b32 m0, s10
	s_nop 0
	global_load_lds_dwordx4 v[84:85], off
	v_lshl_add_u64 v[84:85], s[6:7], 0, v[166:167]
	s_add_i32 m0, s10, 0x2000
	s_nop 0
	global_load_lds_dwordx4 v[84:85], off
	s_waitcnt vmcnt(6)
	s_barrier
	s_setprio 1
	v_mfma_f32_16x16x32_bf16 v[76:79], v[200:203], v[92:95], v[76:79]
	v_mfma_f32_16x16x32_bf16 v[118:121], v[204:207], v[96:99], v[76:79]
	v_mfma_f32_16x16x32_bf16 v[16:19], v[212:215], v[96:99], v[16:19]
	v_mfma_f32_16x16x32_bf16 v[16:19], v[208:211], v[92:95], v[16:19]
	v_mfma_f32_16x16x32_bf16 v[12:15], v[208:211], v[100:103], v[12:15]
	v_mfma_f32_16x16x32_bf16 v[12:15], v[212:215], v[180:183], v[12:15]
	v_mfma_f32_16x16x32_bf16 v[8:11], v[212:215], v[188:191], v[8:11]
	v_mfma_f32_16x16x32_bf16 v[8:11], v[208:211], v[184:187], v[8:11]
	v_mfma_f32_16x16x32_bf16 v[68:71], v[200:203], v[184:187], v[68:71]
	v_mfma_f32_16x16x32_bf16 v[68:71], v[204:207], v[188:191], v[68:71]
	v_mfma_f32_16x16x32_bf16 v[64:67], v[204:207], v[196:199], v[64:67]
	v_mfma_f32_16x16x32_bf16 v[64:67], v[200:203], v[192:195], v[64:67]
	v_mfma_f32_16x16x32_bf16 v[76:79], v[200:203], v[100:103], v[80:83]
	v_mfma_f32_16x16x32_bf16 v[110:113], v[204:207], v[180:183], v[76:79]
	v_mfma_f32_16x16x32_bf16 v[0:3], v[208:211], v[192:195], v[0:3]
	v_mfma_f32_16x16x32_bf16 v[0:3], v[212:215], v[196:199], v[0:3]
	s_setprio 0
	s_add_i32 s65, s65, 2
	s_add_u32 s63, s63, 0x100
	s_addc_u32 s64, s64, 0
	s_cmp_gt_u32 s65, 29
	s_mov_b64 s[6:7], s[8:9]
	s_barrier
	s_cbranch_scc0 .LBB0_363
	s_lshl_b32 s8, s0, 8
	s_add_i32 s8, s8, s56
	s_lshl_b32 s9, s1, 7
	s_add_i32 s9, s9, s49
	s_lshl_b32 s10, s0, 3
	s_lshr_b32 s11, s56, 5
	s_add_i32 s10, s10, s11
	v_add_u32_e32 v200, s8, v163
	v_lshlrev_b32_e32 v213, 2, v200
	global_load_dword v188, v213, s[12:13]
	global_load_dword v189, v213, s[12:13] offset:64
	global_load_dword v190, v213, s[12:13] offset:128
	global_load_dword v191, v213, s[12:13] offset:192
	global_load_dword v192, v213, s[12:13] offset:256
	global_load_dword v193, v213, s[12:13] offset:320
	global_load_dword v194, v213, s[12:13] offset:384
	global_load_dword v195, v213, s[12:13] offset:448
	v_lshl_add_u32 v201, v225, 3, s9
	v_lshlrev_b32_e32 v212, 2, v201
	global_load_dwordx4 v[76:79], v212, s[82:83]
	v_add_u32_e32 v213, 0xb000, v212
	global_load_dwordx4 v[80:83], v213, s[82:83]
	v_add_u32_e32 v213, 0x16000, v212
	global_load_dwordx4 v[84:87], v213, s[82:83]
	global_load_dwordx4 v[88:91], v212, s[84:85]
	v_add_u32_e32 v213, 0x5800, v212
	global_load_dwordx4 v[92:95], v213, s[82:83]
	v_add_u32_e32 v213, 0x10800, v212
	global_load_dwordx4 v[96:99], v213, s[82:83]
	v_add_u32_e32 v213, 0x1b800, v212
	global_load_dwordx4 v[100:103], v213, s[82:83]
	v_add_u32_e32 v213, 0x5800, v212
	global_load_dwordx4 v[104:107], v213, s[84:85]
	v_mul_u32_u24_e32 v215, 0x2c00, v200
	v_lshl_add_u32 v215, v201, 1, v215
	v_add_u32_e32 v213, s10, v163
	v_mul_u32_u24_e32 v217, 0xb000, v213
	v_add_u32_e32 v217, v217, v212
	v_cmp_gt_u32_e64 s[8:9], 2, v163
	v_cmp_lt_u32_e64 s[10:11], 13, v163
	v_cmp_lt_u32_e32 vcc, 1, v163
	v_mov_b32_e32 v214, 1.0
	v_mov_b32_e32 v216, 0xbfb8aa3b
	v_mov_b32_e32 v108, 0x3727c5ac
	s_waitcnt vmcnt(8)
	v_fmamk_f32 v188, v188, 0x3a000000, v108
	v_fmamk_f32 v189, v189, 0x3a000000, v108
	v_fmamk_f32 v190, v190, 0x3a000000, v108
	v_fmamk_f32 v191, v191, 0x3a000000, v108
	v_fmamk_f32 v192, v192, 0x3a000000, v108
	v_fmamk_f32 v193, v193, 0x3a000000, v108
	v_fmamk_f32 v194, v194, 0x3a000000, v108
	v_fmamk_f32 v195, v195, 0x3a000000, v108
	v_rsq_f32_e32 v188, v188
	v_rsq_f32_e32 v189, v189
	v_rsq_f32_e32 v190, v190
	v_rsq_f32_e32 v191, v191
	v_rsq_f32_e32 v192, v192
	v_rsq_f32_e32 v193, v193
	v_rsq_f32_e32 v194, v194
	v_rsq_f32_e32 v195, v195
	v_pk_mul_f32 v[158:159], v[158:159], v[188:189] op_sel_hi:[1,0]
	v_pk_mul_f32 v[160:161], v[160:161], v[188:189] op_sel_hi:[1,0]
	v_pk_mul_f32 v[60:61], v[60:61], v[188:189] op_sel_hi:[1,0]
	v_pk_mul_f32 v[62:63], v[62:63], v[188:189] op_sel_hi:[1,0]
	v_pk_mul_f32 v[154:155], v[154:155], v[188:189] op_sel_hi:[1,0]
	v_pk_mul_f32 v[156:157], v[156:157], v[188:189] op_sel_hi:[1,0]
	v_pk_mul_f32 v[56:57], v[56:57], v[188:189] op_sel_hi:[1,0]
	v_pk_mul_f32 v[58:59], v[58:59], v[188:189] op_sel_hi:[1,0]
	v_pk_mul_f32 v[150:151], v[150:151], v[188:189] op_sel:[0,1] op_sel_hi:[1,1]
	v_pk_mul_f32 v[152:153], v[152:153], v[188:189] op_sel:[0,1] op_sel_hi:[1,1]
	v_pk_mul_f32 v[52:53], v[52:53], v[188:189] op_sel:[0,1] op_sel_hi:[1,1]
	v_pk_mul_f32 v[54:55], v[54:55], v[188:189] op_sel:[0,1] op_sel_hi:[1,1]
	v_pk_mul_f32 v[142:143], v[142:143], v[188:189] op_sel:[0,1] op_sel_hi:[1,1]
	v_pk_mul_f32 v[144:145], v[144:145], v[188:189] op_sel:[0,1] op_sel_hi:[1,1]
	v_pk_mul_f32 v[44:45], v[44:45], v[188:189] op_sel:[0,1] op_sel_hi:[1,1]
	v_pk_mul_f32 v[46:47], v[46:47], v[188:189] op_sel:[0,1] op_sel_hi:[1,1]
	v_pk_mul_f32 v[146:147], v[146:147], v[190:191] op_sel_hi:[1,0]
	v_pk_mul_f32 v[148:149], v[148:149], v[190:191] op_sel_hi:[1,0]
	v_pk_mul_f32 v[48:49], v[48:49], v[190:191] op_sel_hi:[1,0]
	v_pk_mul_f32 v[50:51], v[50:51], v[190:191] op_sel_hi:[1,0]
	v_pk_mul_f32 v[134:135], v[134:135], v[190:191] op_sel_hi:[1,0]
	v_pk_mul_f32 v[136:137], v[136:137], v[190:191] op_sel_hi:[1,0]
	v_pk_mul_f32 v[36:37], v[36:37], v[190:191] op_sel_hi:[1,0]
	v_pk_mul_f32 v[38:39], v[38:39], v[190:191] op_sel_hi:[1,0]
	v_pk_mul_f32 v[138:139], v[138:139], v[190:191] op_sel:[0,1] op_sel_hi:[1,1]
	v_pk_mul_f32 v[140:141], v[140:141], v[190:191] op_sel:[0,1] op_sel_hi:[1,1]
	v_pk_mul_f32 v[40:41], v[40:41], v[190:191] op_sel:[0,1] op_sel_hi:[1,1]
	v_pk_mul_f32 v[42:43], v[42:43], v[190:191] op_sel:[0,1] op_sel_hi:[1,1]
	v_pk_mul_f32 v[130:131], v[130:131], v[190:191] op_sel:[0,1] op_sel_hi:[1,1]
	v_pk_mul_f32 v[132:133], v[132:133], v[190:191] op_sel:[0,1] op_sel_hi:[1,1]
	v_pk_mul_f32 v[32:33], v[32:33], v[190:191] op_sel:[0,1] op_sel_hi:[1,1]
	v_pk_mul_f32 v[34:35], v[34:35], v[190:191] op_sel:[0,1] op_sel_hi:[1,1]
	v_pk_mul_f32 v[126:127], v[126:127], v[192:193] op_sel_hi:[1,0]
	v_pk_mul_f32 v[128:129], v[128:129], v[192:193] op_sel_hi:[1,0]
	v_pk_mul_f32 v[28:29], v[28:29], v[192:193] op_sel_hi:[1,0]
	v_pk_mul_f32 v[30:31], v[30:31], v[192:193] op_sel_hi:[1,0]
	v_pk_mul_f32 v[118:119], v[118:119], v[192:193] op_sel_hi:[1,0]
	v_pk_mul_f32 v[120:121], v[120:121], v[192:193] op_sel_hi:[1,0]
	v_pk_mul_f32 v[16:17], v[16:17], v[192:193] op_sel_hi:[1,0]
	v_pk_mul_f32 v[18:19], v[18:19], v[192:193] op_sel_hi:[1,0]
	v_pk_mul_f32 v[122:123], v[122:123], v[192:193] op_sel:[0,1] op_sel_hi:[1,1]
	v_pk_mul_f32 v[124:125], v[124:125], v[192:193] op_sel:[0,1] op_sel_hi:[1,1]
	v_pk_mul_f32 v[24:25], v[24:25], v[192:193] op_sel:[0,1] op_sel_hi:[1,1]
	v_pk_mul_f32 v[26:27], v[26:27], v[192:193] op_sel:[0,1] op_sel_hi:[1,1]
	v_pk_mul_f32 v[110:111], v[110:111], v[192:193] op_sel:[0,1] op_sel_hi:[1,1]
	v_pk_mul_f32 v[112:113], v[112:113], v[192:193] op_sel:[0,1] op_sel_hi:[1,1]
	v_pk_mul_f32 v[12:13], v[12:13], v[192:193] op_sel:[0,1] op_sel_hi:[1,1]
	v_pk_mul_f32 v[14:15], v[14:15], v[192:193] op_sel:[0,1] op_sel_hi:[1,1]
	v_pk_mul_f32 v[114:115], v[114:115], v[194:195] op_sel_hi:[1,0]
	v_pk_mul_f32 v[116:117], v[116:117], v[194:195] op_sel_hi:[1,0]
	v_pk_mul_f32 v[20:21], v[20:21], v[194:195] op_sel_hi:[1,0]
	v_pk_mul_f32 v[22:23], v[22:23], v[194:195] op_sel_hi:[1,0]
	v_pk_mul_f32 v[68:69], v[68:69], v[194:195] op_sel_hi:[1,0]
	v_pk_mul_f32 v[70:71], v[70:71], v[194:195] op_sel_hi:[1,0]
	v_pk_mul_f32 v[8:9], v[8:9], v[194:195] op_sel_hi:[1,0]
	v_pk_mul_f32 v[10:11], v[10:11], v[194:195] op_sel_hi:[1,0]
	v_pk_mul_f32 v[72:73], v[72:73], v[194:195] op_sel:[0,1] op_sel_hi:[1,1]
	v_pk_mul_f32 v[74:75], v[74:75], v[194:195] op_sel:[0,1] op_sel_hi:[1,1]
	v_pk_mul_f32 v[4:5], v[4:5], v[194:195] op_sel:[0,1] op_sel_hi:[1,1]
	v_pk_mul_f32 v[6:7], v[6:7], v[194:195] op_sel:[0,1] op_sel_hi:[1,1]
	v_pk_mul_f32 v[64:65], v[64:65], v[194:195] op_sel:[0,1] op_sel_hi:[1,1]
	v_pk_mul_f32 v[66:67], v[66:67], v[194:195] op_sel:[0,1] op_sel_hi:[1,1]
	v_pk_mul_f32 v[0:1], v[0:1], v[194:195] op_sel:[0,1] op_sel_hi:[1,1]
	v_pk_mul_f32 v[2:3], v[2:3], v[194:195] op_sel:[0,1] op_sel_hi:[1,1]
	s_nop 1
	s_mov_b64 exec, s[8:9]
	v_add_u32_e32 v213, 0x5800, v217
	global_store_dwordx4 v217, v[158:161], s[70:71]
	global_store_dwordx4 v213, v[154:157], s[70:71]
	global_store_dwordx4 v217, v[60:63], s[70:71] offset:16
	global_store_dwordx4 v213, v[56:59], s[70:71] offset:16
	s_mov_b64 exec, s[10:11]
	v_add_u32_e32 v213, 0xfff7c000, v217
	global_store_dwordx4 v213, v[72:75], s[70:71]
	global_store_dwordx4 v213, v[4:7], s[70:71] offset:16
	v_add_u32_e32 v213, 0xfff81800, v217
	global_store_dwordx4 v213, v[64:67], s[70:71]
	global_store_dwordx4 v213, v[0:3], s[70:71] offset:16
	s_mov_b64 exec, -1
	v_add_u32_e32 v213, 0x1b800, v212
	global_load_dwordx4 v[204:207], v213, s[82:83] offset:16
	v_add_u32_e32 v213, 0x5800, v212
	global_load_dwordx4 v[208:211], v213, s[84:85] offset:16
	s_waitcnt vmcnt(10)
	v_pk_fma_f32 v[188:189], v[158:159], v[84:85], v[88:89]
	v_pk_fma_f32 v[190:191], v[160:161], v[86:87], v[90:91]
	v_pk_fma_f32 v[192:193], v[154:155], v[100:101], v[104:105]
	v_pk_fma_f32 v[194:195], v[156:157], v[102:103], v[106:107]
	v_fmac_f32_dpp v188, v158, v80 row_shr:1 row_mask:0xf bank_mask:0xf
	v_fmac_f32_dpp v189, v159, v81 row_shr:1 row_mask:0xf bank_mask:0xf
	v_fmac_f32_dpp v190, v160, v82 row_shr:1 row_mask:0xf bank_mask:0xf
	v_fmac_f32_dpp v191, v161, v83 row_shr:1 row_mask:0xf bank_mask:0xf
	v_fmac_f32_dpp v192, v154, v96 row_shr:1 row_mask:0xf bank_mask:0xf
	v_fmac_f32_dpp v193, v155, v97 row_shr:1 row_mask:0xf bank_mask:0xf
	v_fmac_f32_dpp v194, v156, v98 row_shr:1 row_mask:0xf bank_mask:0xf
	v_fmac_f32_dpp v195, v157, v99 row_shr:1 row_mask:0xf bank_mask:0xf
	v_fmac_f32_dpp v188, v158, v76 row_shr:2 row_mask:0xf bank_mask:0xf
	v_fmac_f32_dpp v189, v159, v77 row_shr:2 row_mask:0xf bank_mask:0xf
	v_fmac_f32_dpp v190, v160, v78 row_shr:2 row_mask:0xf bank_mask:0xf
	v_fmac_f32_dpp v191, v161, v79 row_shr:2 row_mask:0xf bank_mask:0xf
	v_fmac_f32_dpp v192, v154, v92 row_shr:2 row_mask:0xf bank_mask:0xf
	v_fmac_f32_dpp v193, v155, v93 row_shr:2 row_mask:0xf bank_mask:0xf
	v_fmac_f32_dpp v194, v156, v94 row_shr:2 row_mask:0xf bank_mask:0xf
	v_fmac_f32_dpp v195, v157, v95 row_shr:2 row_mask:0xf bank_mask:0xf
	v_pk_mul_f32 v[196:197], v[188:189], v[216:217] op_sel_hi:[1,0]
	v_pk_mul_f32 v[198:199], v[190:191], v[216:217] op_sel_hi:[1,0]
	v_exp_f32_e32 v196, v196
	v_exp_f32_e32 v197, v197
	v_exp_f32_e32 v198, v198
	v_exp_f32_e32 v199, v199
	v_pk_add_f32 v[196:197], v[196:197], v[214:215] op_sel_hi:[1,0]
	v_pk_add_f32 v[198:199], v[198:199], v[214:215] op_sel_hi:[1,0]
	v_rcp_f32_e32 v196, v196
	v_rcp_f32_e32 v197, v197
	v_rcp_f32_e32 v198, v198
	v_rcp_f32_e32 v199, v199
	v_pk_mul_f32 v[188:189], v[188:189], v[196:197]
	v_pk_mul_f32 v[190:191], v[190:191], v[198:199]
	v_pk_mul_f32 v[188:189], v[188:189], v[192:193]
	v_pk_mul_f32 v[190:191], v[190:191], v[194:195]
	v_cvt_pk_bf16_f32 v200, v188, v189
	v_cvt_pk_bf16_f32 v201, v190, v191
	v_pk_fma_f32 v[188:189], v[150:151], v[84:85], v[88:89]
	v_pk_fma_f32 v[190:191], v[152:153], v[86:87], v[90:91]
	v_pk_fma_f32 v[192:193], v[142:143], v[100:101], v[104:105]
	v_pk_fma_f32 v[194:195], v[144:145], v[102:103], v[106:107]
	v_fmac_f32_dpp v188, v150, v80 row_shr:1 row_mask:0xf bank_mask:0xf
	v_fmac_f32_dpp v189, v151, v81 row_shr:1 row_mask:0xf bank_mask:0xf
	v_fmac_f32_dpp v190, v152, v82 row_shr:1 row_mask:0xf bank_mask:0xf
	v_fmac_f32_dpp v191, v153, v83 row_shr:1 row_mask:0xf bank_mask:0xf
	v_fmac_f32_dpp v192, v142, v96 row_shr:1 row_mask:0xf bank_mask:0xf
	v_fmac_f32_dpp v193, v143, v97 row_shr:1 row_mask:0xf bank_mask:0xf
	v_fmac_f32_dpp v194, v144, v98 row_shr:1 row_mask:0xf bank_mask:0xf
	v_fmac_f32_dpp v195, v145, v99 row_shr:1 row_mask:0xf bank_mask:0xf
	v_fmac_f32_dpp v188, v150, v76 row_shr:2 row_mask:0xf bank_mask:0xf
	v_fmac_f32_dpp v189, v151, v77 row_shr:2 row_mask:0xf bank_mask:0xf
	v_fmac_f32_dpp v190, v152, v78 row_shr:2 row_mask:0xf bank_mask:0xf
	v_fmac_f32_dpp v191, v153, v79 row_shr:2 row_mask:0xf bank_mask:0xf
	v_fmac_f32_dpp v192, v142, v92 row_shr:2 row_mask:0xf bank_mask:0xf
	v_fmac_f32_dpp v193, v143, v93 row_shr:2 row_mask:0xf bank_mask:0xf
	v_fmac_f32_dpp v194, v144, v94 row_shr:2 row_mask:0xf bank_mask:0xf
	v_fmac_f32_dpp v195, v145, v95 row_shr:2 row_mask:0xf bank_mask:0xf
	v_fmac_f32_dpp v188, v158, v80 row_shl:15 row_mask:0xf bank_mask:0xf
	v_fmac_f32_dpp v189, v159, v81 row_shl:15 row_mask:0xf bank_mask:0xf
	v_fmac_f32_dpp v190, v160, v82 row_shl:15 row_mask:0xf bank_mask:0xf
	v_fmac_f32_dpp v191, v161, v83 row_shl:15 row_mask:0xf bank_mask:0xf
	v_fmac_f32_dpp v192, v154, v96 row_shl:15 row_mask:0xf bank_mask:0xf
	v_fmac_f32_dpp v193, v155, v97 row_shl:15 row_mask:0xf bank_mask:0xf
	v_fmac_f32_dpp v194, v156, v98 row_shl:15 row_mask:0xf bank_mask:0xf
	v_fmac_f32_dpp v195, v157, v99 row_shl:15 row_mask:0xf bank_mask:0xf
	v_fmac_f32_dpp v188, v158, v76 row_shl:14 row_mask:0xf bank_mask:0xf
	v_fmac_f32_dpp v189, v159, v77 row_shl:14 row_mask:0xf bank_mask:0xf
	v_fmac_f32_dpp v190, v160, v78 row_shl:14 row_mask:0xf bank_mask:0xf
	v_fmac_f32_dpp v191, v161, v79 row_shl:14 row_mask:0xf bank_mask:0xf
	v_fmac_f32_dpp v192, v154, v92 row_shl:14 row_mask:0xf bank_mask:0xf
	v_fmac_f32_dpp v193, v155, v93 row_shl:14 row_mask:0xf bank_mask:0xf
	v_fmac_f32_dpp v194, v156, v94 row_shl:14 row_mask:0xf bank_mask:0xf
	v_fmac_f32_dpp v195, v157, v95 row_shl:14 row_mask:0xf bank_mask:0xf
	v_pk_mul_f32 v[196:197], v[188:189], v[216:217] op_sel_hi:[1,0]
	v_pk_mul_f32 v[198:199], v[190:191], v[216:217] op_sel_hi:[1,0]
	v_exp_f32_e32 v196, v196
	v_exp_f32_e32 v197, v197
	v_exp_f32_e32 v198, v198
	v_exp_f32_e32 v199, v199
	v_pk_add_f32 v[196:197], v[196:197], v[214:215] op_sel_hi:[1,0]
	v_pk_add_f32 v[198:199], v[198:199], v[214:215] op_sel_hi:[1,0]
	v_rcp_f32_e32 v196, v196
	v_rcp_f32_e32 v197, v197
	v_rcp_f32_e32 v198, v198
	v_rcp_f32_e32 v199, v199
	v_pk_mul_f32 v[188:189], v[188:189], v[196:197]
	v_pk_mul_f32 v[190:191], v[190:191], v[198:199]
	v_pk_mul_f32 v[188:189], v[188:189], v[192:193]
	v_pk_mul_f32 v[190:191], v[190:191], v[194:195]
	v_cvt_pk_bf16_f32 v158, v188, v189
	v_cvt_pk_bf16_f32 v159, v190, v191
	global_load_dwordx4 v[154:157], v212, s[82:83] offset:16
	v_pk_fma_f32 v[188:189], v[146:147], v[84:85], v[88:89]
	v_pk_fma_f32 v[190:191], v[148:149], v[86:87], v[90:91]
	v_pk_fma_f32 v[192:193], v[134:135], v[100:101], v[104:105]
	v_pk_fma_f32 v[194:195], v[136:137], v[102:103], v[106:107]
	v_fmac_f32_dpp v188, v146, v80 row_shr:1 row_mask:0xf bank_mask:0xf
	v_fmac_f32_dpp v189, v147, v81 row_shr:1 row_mask:0xf bank_mask:0xf
	v_fmac_f32_dpp v190, v148, v82 row_shr:1 row_mask:0xf bank_mask:0xf
	v_fmac_f32_dpp v191, v149, v83 row_shr:1 row_mask:0xf bank_mask:0xf
	v_fmac_f32_dpp v192, v134, v96 row_shr:1 row_mask:0xf bank_mask:0xf
	v_fmac_f32_dpp v193, v135, v97 row_shr:1 row_mask:0xf bank_mask:0xf
	v_fmac_f32_dpp v194, v136, v98 row_shr:1 row_mask:0xf bank_mask:0xf
	v_fmac_f32_dpp v195, v137, v99 row_shr:1 row_mask:0xf bank_mask:0xf
	v_fmac_f32_dpp v188, v146, v76 row_shr:2 row_mask:0xf bank_mask:0xf
	v_fmac_f32_dpp v189, v147, v77 row_shr:2 row_mask:0xf bank_mask:0xf
	v_fmac_f32_dpp v190, v148, v78 row_shr:2 row_mask:0xf bank_mask:0xf
	v_fmac_f32_dpp v191, v149, v79 row_shr:2 row_mask:0xf bank_mask:0xf
	v_fmac_f32_dpp v192, v134, v92 row_shr:2 row_mask:0xf bank_mask:0xf
	v_fmac_f32_dpp v193, v135, v93 row_shr:2 row_mask:0xf bank_mask:0xf
	v_fmac_f32_dpp v194, v136, v94 row_shr:2 row_mask:0xf bank_mask:0xf
	v_fmac_f32_dpp v195, v137, v95 row_shr:2 row_mask:0xf bank_mask:0xf
	v_fmac_f32_dpp v188, v150, v80 row_shl:15 row_mask:0xf bank_mask:0xf
	v_fmac_f32_dpp v189, v151, v81 row_shl:15 row_mask:0xf bank_mask:0xf
	v_fmac_f32_dpp v190, v152, v82 row_shl:15 row_mask:0xf bank_mask:0xf
	v_fmac_f32_dpp v191, v153, v83 row_shl:15 row_mask:0xf bank_mask:0xf
	v_fmac_f32_dpp v192, v142, v96 row_shl:15 row_mask:0xf bank_mask:0xf
	v_fmac_f32_dpp v193, v143, v97 row_shl:15 row_mask:0xf bank_mask:0xf
	v_fmac_f32_dpp v194, v144, v98 row_shl:15 row_mask:0xf bank_mask:0xf
	v_fmac_f32_dpp v195, v145, v99 row_shl:15 row_mask:0xf bank_mask:0xf
	v_fmac_f32_dpp v188, v150, v76 row_shl:14 row_mask:0xf bank_mask:0xf
	v_fmac_f32_dpp v189, v151, v77 row_shl:14 row_mask:0xf bank_mask:0xf
	v_fmac_f32_dpp v190, v152, v78 row_shl:14 row_mask:0xf bank_mask:0xf
	v_fmac_f32_dpp v191, v153, v79 row_shl:14 row_mask:0xf bank_mask:0xf
	v_fmac_f32_dpp v192, v142, v92 row_shl:14 row_mask:0xf bank_mask:0xf
	v_fmac_f32_dpp v193, v143, v93 row_shl:14 row_mask:0xf bank_mask:0xf
	v_fmac_f32_dpp v194, v144, v94 row_shl:14 row_mask:0xf bank_mask:0xf
	v_fmac_f32_dpp v195, v145, v95 row_shl:14 row_mask:0xf bank_mask:0xf
	v_pk_mul_f32 v[196:197], v[188:189], v[216:217] op_sel_hi:[1,0]
	v_pk_mul_f32 v[198:199], v[190:191], v[216:217] op_sel_hi:[1,0]
	v_exp_f32_e32 v196, v196
	v_exp_f32_e32 v197, v197
	v_exp_f32_e32 v198, v198
	v_exp_f32_e32 v199, v199
	v_pk_add_f32 v[196:197], v[196:197], v[214:215] op_sel_hi:[1,0]
	v_pk_add_f32 v[198:199], v[198:199], v[214:215] op_sel_hi:[1,0]
	v_rcp_f32_e32 v196, v196
	v_rcp_f32_e32 v197, v197
	v_rcp_f32_e32 v198, v198
	v_rcp_f32_e32 v199, v199
	v_pk_mul_f32 v[188:189], v[188:189], v[196:197]
	v_pk_mul_f32 v[190:191], v[190:191], v[198:199]
	v_pk_mul_f32 v[188:189], v[188:189], v[192:193]
	v_pk_mul_f32 v[190:191], v[190:191], v[194:195]
	v_cvt_pk_bf16_f32 v150, v188, v189
	v_cvt_pk_bf16_f32 v151, v190, v191
	v_add_u32_e32 v213, 0xb000, v212
	global_load_dwordx4 v[142:145], v213, s[82:83] offset:16
	v_pk_fma_f32 v[188:189], v[138:139], v[84:85], v[88:89]
	v_pk_fma_f32 v[190:191], v[140:141], v[86:87], v[90:91]
	v_pk_fma_f32 v[192:193], v[130:131], v[100:101], v[104:105]
	v_pk_fma_f32 v[194:195], v[132:133], v[102:103], v[106:107]
	v_fmac_f32_dpp v188, v138, v80 row_shr:1 row_mask:0xf bank_mask:0xf
	v_fmac_f32_dpp v189, v139, v81 row_shr:1 row_mask:0xf bank_mask:0xf
	v_fmac_f32_dpp v190, v140, v82 row_shr:1 row_mask:0xf bank_mask:0xf
	v_fmac_f32_dpp v191, v141, v83 row_shr:1 row_mask:0xf bank_mask:0xf
	v_fmac_f32_dpp v192, v130, v96 row_shr:1 row_mask:0xf bank_mask:0xf
	v_fmac_f32_dpp v193, v131, v97 row_shr:1 row_mask:0xf bank_mask:0xf
	v_fmac_f32_dpp v194, v132, v98 row_shr:1 row_mask:0xf bank_mask:0xf
	v_fmac_f32_dpp v195, v133, v99 row_shr:1 row_mask:0xf bank_mask:0xf
	v_fmac_f32_dpp v188, v138, v76 row_shr:2 row_mask:0xf bank_mask:0xf
	v_fmac_f32_dpp v189, v139, v77 row_shr:2 row_mask:0xf bank_mask:0xf
	v_fmac_f32_dpp v190, v140, v78 row_shr:2 row_mask:0xf bank_mask:0xf
	v_fmac_f32_dpp v191, v141, v79 row_shr:2 row_mask:0xf bank_mask:0xf
	v_fmac_f32_dpp v192, v130, v92 row_shr:2 row_mask:0xf bank_mask:0xf
	v_fmac_f32_dpp v193, v131, v93 row_shr:2 row_mask:0xf bank_mask:0xf
	v_fmac_f32_dpp v194, v132, v94 row_shr:2 row_mask:0xf bank_mask:0xf
	v_fmac_f32_dpp v195, v133, v95 row_shr:2 row_mask:0xf bank_mask:0xf
	v_fmac_f32_dpp v188, v146, v80 row_shl:15 row_mask:0xf bank_mask:0xf
	v_fmac_f32_dpp v189, v147, v81 row_shl:15 row_mask:0xf bank_mask:0xf
	v_fmac_f32_dpp v190, v148, v82 row_shl:15 row_mask:0xf bank_mask:0xf
	v_fmac_f32_dpp v191, v149, v83 row_shl:15 row_mask:0xf bank_mask:0xf
	v_fmac_f32_dpp v192, v134, v96 row_shl:15 row_mask:0xf bank_mask:0xf
	v_fmac_f32_dpp v193, v135, v97 row_shl:15 row_mask:0xf bank_mask:0xf
	v_fmac_f32_dpp v194, v136, v98 row_shl:15 row_mask:0xf bank_mask:0xf
	v_fmac_f32_dpp v195, v137, v99 row_shl:15 row_mask:0xf bank_mask:0xf
	v_fmac_f32_dpp v188, v146, v76 row_shl:14 row_mask:0xf bank_mask:0xf
	v_fmac_f32_dpp v189, v147, v77 row_shl:14 row_mask:0xf bank_mask:0xf
	v_fmac_f32_dpp v190, v148, v78 row_shl:14 row_mask:0xf bank_mask:0xf
	v_fmac_f32_dpp v191, v149, v79 row_shl:14 row_mask:0xf bank_mask:0xf
	v_fmac_f32_dpp v192, v134, v92 row_shl:14 row_mask:0xf bank_mask:0xf
	v_fmac_f32_dpp v193, v135, v93 row_shl:14 row_mask:0xf bank_mask:0xf
	v_fmac_f32_dpp v194, v136, v94 row_shl:14 row_mask:0xf bank_mask:0xf
	v_fmac_f32_dpp v195, v137, v95 row_shl:14 row_mask:0xf bank_mask:0xf
	v_pk_mul_f32 v[196:197], v[188:189], v[216:217] op_sel_hi:[1,0]
	v_pk_mul_f32 v[198:199], v[190:191], v[216:217] op_sel_hi:[1,0]
	v_exp_f32_e32 v196, v196
	v_exp_f32_e32 v197, v197
	v_exp_f32_e32 v198, v198
	v_exp_f32_e32 v199, v199
	v_pk_add_f32 v[196:197], v[196:197], v[214:215] op_sel_hi:[1,0]
	v_pk_add_f32 v[198:199], v[198:199], v[214:215] op_sel_hi:[1,0]
	v_rcp_f32_e32 v196, v196
	v_rcp_f32_e32 v197, v197
	v_rcp_f32_e32 v198, v198
	v_rcp_f32_e32 v199, v199
	v_pk_mul_f32 v[188:189], v[188:189], v[196:197]
	v_pk_mul_f32 v[190:191], v[190:191], v[198:199]
	v_pk_mul_f32 v[188:189], v[188:189], v[192:193]
	v_pk_mul_f32 v[190:191], v[190:191], v[194:195]
	v_cvt_pk_bf16_f32 v146, v188, v189
	v_cvt_pk_bf16_f32 v147, v190, v191
	v_add_u32_e32 v213, 0x16000, v212
	global_load_dwordx4 v[134:137], v213, s[82:83] offset:16
	v_pk_fma_f32 v[188:189], v[126:127], v[84:85], v[88:89]
	v_pk_fma_f32 v[190:191], v[128:129], v[86:87], v[90:91]
	v_pk_fma_f32 v[192:193], v[118:119], v[100:101], v[104:105]
	v_pk_fma_f32 v[194:195], v[120:121], v[102:103], v[106:107]
	v_fmac_f32_dpp v188, v126, v80 row_shr:1 row_mask:0xf bank_mask:0xf
	v_fmac_f32_dpp v189, v127, v81 row_shr:1 row_mask:0xf bank_mask:0xf
	v_fmac_f32_dpp v190, v128, v82 row_shr:1 row_mask:0xf bank_mask:0xf
	v_fmac_f32_dpp v191, v129, v83 row_shr:1 row_mask:0xf bank_mask:0xf
	v_fmac_f32_dpp v192, v118, v96 row_shr:1 row_mask:0xf bank_mask:0xf
	v_fmac_f32_dpp v193, v119, v97 row_shr:1 row_mask:0xf bank_mask:0xf
	v_fmac_f32_dpp v194, v120, v98 row_shr:1 row_mask:0xf bank_mask:0xf
	v_fmac_f32_dpp v195, v121, v99 row_shr:1 row_mask:0xf bank_mask:0xf
	v_fmac_f32_dpp v188, v126, v76 row_shr:2 row_mask:0xf bank_mask:0xf
	v_fmac_f32_dpp v189, v127, v77 row_shr:2 row_mask:0xf bank_mask:0xf
	v_fmac_f32_dpp v190, v128, v78 row_shr:2 row_mask:0xf bank_mask:0xf
	v_fmac_f32_dpp v191, v129, v79 row_shr:2 row_mask:0xf bank_mask:0xf
	v_fmac_f32_dpp v192, v118, v92 row_shr:2 row_mask:0xf bank_mask:0xf
	v_fmac_f32_dpp v193, v119, v93 row_shr:2 row_mask:0xf bank_mask:0xf
	v_fmac_f32_dpp v194, v120, v94 row_shr:2 row_mask:0xf bank_mask:0xf
	v_fmac_f32_dpp v195, v121, v95 row_shr:2 row_mask:0xf bank_mask:0xf
	v_fmac_f32_dpp v188, v138, v80 row_shl:15 row_mask:0xf bank_mask:0xf
	v_fmac_f32_dpp v189, v139, v81 row_shl:15 row_mask:0xf bank_mask:0xf
	v_fmac_f32_dpp v190, v140, v82 row_shl:15 row_mask:0xf bank_mask:0xf
	v_fmac_f32_dpp v191, v141, v83 row_shl:15 row_mask:0xf bank_mask:0xf
	v_fmac_f32_dpp v192, v130, v96 row_shl:15 row_mask:0xf bank_mask:0xf
	v_fmac_f32_dpp v193, v131, v97 row_shl:15 row_mask:0xf bank_mask:0xf
	v_fmac_f32_dpp v194, v132, v98 row_shl:15 row_mask:0xf bank_mask:0xf
	v_fmac_f32_dpp v195, v133, v99 row_shl:15 row_mask:0xf bank_mask:0xf
	v_fmac_f32_dpp v188, v138, v76 row_shl:14 row_mask:0xf bank_mask:0xf
	v_fmac_f32_dpp v189, v139, v77 row_shl:14 row_mask:0xf bank_mask:0xf
	v_fmac_f32_dpp v190, v140, v78 row_shl:14 row_mask:0xf bank_mask:0xf
	v_fmac_f32_dpp v191, v141, v79 row_shl:14 row_mask:0xf bank_mask:0xf
	v_fmac_f32_dpp v192, v130, v92 row_shl:14 row_mask:0xf bank_mask:0xf
	v_fmac_f32_dpp v193, v131, v93 row_shl:14 row_mask:0xf bank_mask:0xf
	v_fmac_f32_dpp v194, v132, v94 row_shl:14 row_mask:0xf bank_mask:0xf
	v_fmac_f32_dpp v195, v133, v95 row_shl:14 row_mask:0xf bank_mask:0xf
	v_pk_mul_f32 v[196:197], v[188:189], v[216:217] op_sel_hi:[1,0]
	v_pk_mul_f32 v[198:199], v[190:191], v[216:217] op_sel_hi:[1,0]
	v_exp_f32_e32 v196, v196
	v_exp_f32_e32 v197, v197
	v_exp_f32_e32 v198, v198
	v_exp_f32_e32 v199, v199
	v_pk_add_f32 v[196:197], v[196:197], v[214:215] op_sel_hi:[1,0]
	v_pk_add_f32 v[198:199], v[198:199], v[214:215] op_sel_hi:[1,0]
	v_rcp_f32_e32 v196, v196
	v_rcp_f32_e32 v197, v197
	v_rcp_f32_e32 v198, v198
	v_rcp_f32_e32 v199, v199
	v_pk_mul_f32 v[188:189], v[188:189], v[196:197]
	v_pk_mul_f32 v[190:191], v[190:191], v[198:199]
	v_pk_mul_f32 v[188:189], v[188:189], v[192:193]
	v_pk_mul_f32 v[190:191], v[190:191], v[194:195]
	v_cvt_pk_bf16_f32 v138, v188, v189
	v_cvt_pk_bf16_f32 v139, v190, v191
	global_load_dwordx4 v[130:133], v212, s[84:85] offset:16
	v_pk_fma_f32 v[188:189], v[122:123], v[84:85], v[88:89]
	v_pk_fma_f32 v[190:191], v[124:125], v[86:87], v[90:91]
	v_pk_fma_f32 v[192:193], v[110:111], v[100:101], v[104:105]
	v_pk_fma_f32 v[194:195], v[112:113], v[102:103], v[106:107]
	v_fmac_f32_dpp v188, v122, v80 row_shr:1 row_mask:0xf bank_mask:0xf
	v_fmac_f32_dpp v189, v123, v81 row_shr:1 row_mask:0xf bank_mask:0xf
	v_fmac_f32_dpp v190, v124, v82 row_shr:1 row_mask:0xf bank_mask:0xf
	v_fmac_f32_dpp v191, v125, v83 row_shr:1 row_mask:0xf bank_mask:0xf
	v_fmac_f32_dpp v192, v110, v96 row_shr:1 row_mask:0xf bank_mask:0xf
	v_fmac_f32_dpp v193, v111, v97 row_shr:1 row_mask:0xf bank_mask:0xf
	v_fmac_f32_dpp v194, v112, v98 row_shr:1 row_mask:0xf bank_mask:0xf
	v_fmac_f32_dpp v195, v113, v99 row_shr:1 row_mask:0xf bank_mask:0xf
	v_fmac_f32_dpp v188, v122, v76 row_shr:2 row_mask:0xf bank_mask:0xf
	v_fmac_f32_dpp v189, v123, v77 row_shr:2 row_mask:0xf bank_mask:0xf
	v_fmac_f32_dpp v190, v124, v78 row_shr:2 row_mask:0xf bank_mask:0xf
	v_fmac_f32_dpp v191, v125, v79 row_shr:2 row_mask:0xf bank_mask:0xf
	v_fmac_f32_dpp v192, v110, v92 row_shr:2 row_mask:0xf bank_mask:0xf
	v_fmac_f32_dpp v193, v111, v93 row_shr:2 row_mask:0xf bank_mask:0xf
	v_fmac_f32_dpp v194, v112, v94 row_shr:2 row_mask:0xf bank_mask:0xf
	v_fmac_f32_dpp v195, v113, v95 row_shr:2 row_mask:0xf bank_mask:0xf
	v_fmac_f32_dpp v188, v126, v80 row_shl:15 row_mask:0xf bank_mask:0xf
	v_fmac_f32_dpp v189, v127, v81 row_shl:15 row_mask:0xf bank_mask:0xf
	v_fmac_f32_dpp v190, v128, v82 row_shl:15 row_mask:0xf bank_mask:0xf
	v_fmac_f32_dpp v191, v129, v83 row_shl:15 row_mask:0xf bank_mask:0xf
	v_fmac_f32_dpp v192, v118, v96 row_shl:15 row_mask:0xf bank_mask:0xf
	v_fmac_f32_dpp v193, v119, v97 row_shl:15 row_mask:0xf bank_mask:0xf
	v_fmac_f32_dpp v194, v120, v98 row_shl:15 row_mask:0xf bank_mask:0xf
	v_fmac_f32_dpp v195, v121, v99 row_shl:15 row_mask:0xf bank_mask:0xf
	v_fmac_f32_dpp v188, v126, v76 row_shl:14 row_mask:0xf bank_mask:0xf
	v_fmac_f32_dpp v189, v127, v77 row_shl:14 row_mask:0xf bank_mask:0xf
	v_fmac_f32_dpp v190, v128, v78 row_shl:14 row_mask:0xf bank_mask:0xf
	v_fmac_f32_dpp v191, v129, v79 row_shl:14 row_mask:0xf bank_mask:0xf
	v_fmac_f32_dpp v192, v118, v92 row_shl:14 row_mask:0xf bank_mask:0xf
	v_fmac_f32_dpp v193, v119, v93 row_shl:14 row_mask:0xf bank_mask:0xf
	v_fmac_f32_dpp v194, v120, v94 row_shl:14 row_mask:0xf bank_mask:0xf
	v_fmac_f32_dpp v195, v121, v95 row_shl:14 row_mask:0xf bank_mask:0xf
	v_pk_mul_f32 v[196:197], v[188:189], v[216:217] op_sel_hi:[1,0]
	v_pk_mul_f32 v[198:199], v[190:191], v[216:217] op_sel_hi:[1,0]
	v_exp_f32_e32 v196, v196
	v_exp_f32_e32 v197, v197
	v_exp_f32_e32 v198, v198
	v_exp_f32_e32 v199, v199
	v_pk_add_f32 v[196:197], v[196:197], v[214:215] op_sel_hi:[1,0]
	v_pk_add_f32 v[198:199], v[198:199], v[214:215] op_sel_hi:[1,0]
	v_rcp_f32_e32 v196, v196
	v_rcp_f32_e32 v197, v197
	v_rcp_f32_e32 v198, v198
	v_rcp_f32_e32 v199, v199
	v_pk_mul_f32 v[188:189], v[188:189], v[196:197]
	v_pk_mul_f32 v[190:191], v[190:191], v[198:199]
	v_pk_mul_f32 v[188:189], v[188:189], v[192:193]
	v_pk_mul_f32 v[190:191], v[190:191], v[194:195]
	v_cvt_pk_bf16_f32 v126, v188, v189
	v_cvt_pk_bf16_f32 v127, v190, v191
	v_add_u32_e32 v213, 0x5800, v212
	global_load_dwordx4 v[118:121], v213, s[82:83] offset:16
	v_pk_fma_f32 v[188:189], v[114:115], v[84:85], v[88:89]
	v_pk_fma_f32 v[190:191], v[116:117], v[86:87], v[90:91]
	v_pk_fma_f32 v[192:193], v[68:69], v[100:101], v[104:105]
	v_pk_fma_f32 v[194:195], v[70:71], v[102:103], v[106:107]
	v_fmac_f32_dpp v188, v114, v80 row_shr:1 row_mask:0xf bank_mask:0xf
	v_fmac_f32_dpp v189, v115, v81 row_shr:1 row_mask:0xf bank_mask:0xf
	v_fmac_f32_dpp v190, v116, v82 row_shr:1 row_mask:0xf bank_mask:0xf
	v_fmac_f32_dpp v191, v117, v83 row_shr:1 row_mask:0xf bank_mask:0xf
	v_fmac_f32_dpp v192, v68, v96 row_shr:1 row_mask:0xf bank_mask:0xf
	v_fmac_f32_dpp v193, v69, v97 row_shr:1 row_mask:0xf bank_mask:0xf
	v_fmac_f32_dpp v194, v70, v98 row_shr:1 row_mask:0xf bank_mask:0xf
	v_fmac_f32_dpp v195, v71, v99 row_shr:1 row_mask:0xf bank_mask:0xf
	v_fmac_f32_dpp v188, v114, v76 row_shr:2 row_mask:0xf bank_mask:0xf
	v_fmac_f32_dpp v189, v115, v77 row_shr:2 row_mask:0xf bank_mask:0xf
	v_fmac_f32_dpp v190, v116, v78 row_shr:2 row_mask:0xf bank_mask:0xf
	v_fmac_f32_dpp v191, v117, v79 row_shr:2 row_mask:0xf bank_mask:0xf
	v_fmac_f32_dpp v192, v68, v92 row_shr:2 row_mask:0xf bank_mask:0xf
	v_fmac_f32_dpp v193, v69, v93 row_shr:2 row_mask:0xf bank_mask:0xf
	v_fmac_f32_dpp v194, v70, v94 row_shr:2 row_mask:0xf bank_mask:0xf
	v_fmac_f32_dpp v195, v71, v95 row_shr:2 row_mask:0xf bank_mask:0xf
	v_fmac_f32_dpp v188, v122, v80 row_shl:15 row_mask:0xf bank_mask:0xf
	v_fmac_f32_dpp v189, v123, v81 row_shl:15 row_mask:0xf bank_mask:0xf
	v_fmac_f32_dpp v190, v124, v82 row_shl:15 row_mask:0xf bank_mask:0xf
	v_fmac_f32_dpp v191, v125, v83 row_shl:15 row_mask:0xf bank_mask:0xf
	v_fmac_f32_dpp v192, v110, v96 row_shl:15 row_mask:0xf bank_mask:0xf
	v_fmac_f32_dpp v193, v111, v97 row_shl:15 row_mask:0xf bank_mask:0xf
	v_fmac_f32_dpp v194, v112, v98 row_shl:15 row_mask:0xf bank_mask:0xf
	v_fmac_f32_dpp v195, v113, v99 row_shl:15 row_mask:0xf bank_mask:0xf
	v_fmac_f32_dpp v188, v122, v76 row_shl:14 row_mask:0xf bank_mask:0xf
	v_fmac_f32_dpp v189, v123, v77 row_shl:14 row_mask:0xf bank_mask:0xf
	v_fmac_f32_dpp v190, v124, v78 row_shl:14 row_mask:0xf bank_mask:0xf
	v_fmac_f32_dpp v191, v125, v79 row_shl:14 row_mask:0xf bank_mask:0xf
	v_fmac_f32_dpp v192, v110, v92 row_shl:14 row_mask:0xf bank_mask:0xf
	v_fmac_f32_dpp v193, v111, v93 row_shl:14 row_mask:0xf bank_mask:0xf
	v_fmac_f32_dpp v194, v112, v94 row_shl:14 row_mask:0xf bank_mask:0xf
	v_fmac_f32_dpp v195, v113, v95 row_shl:14 row_mask:0xf bank_mask:0xf
	v_pk_mul_f32 v[196:197], v[188:189], v[216:217] op_sel_hi:[1,0]
	v_pk_mul_f32 v[198:199], v[190:191], v[216:217] op_sel_hi:[1,0]
	v_exp_f32_e32 v196, v196
	v_exp_f32_e32 v197, v197
	v_exp_f32_e32 v198, v198
	v_exp_f32_e32 v199, v199
	v_pk_add_f32 v[196:197], v[196:197], v[214:215] op_sel_hi:[1,0]
	v_pk_add_f32 v[198:199], v[198:199], v[214:215] op_sel_hi:[1,0]
	v_rcp_f32_e32 v196, v196
	v_rcp_f32_e32 v197, v197
	v_rcp_f32_e32 v198, v198
	v_rcp_f32_e32 v199, v199
	v_pk_mul_f32 v[188:189], v[188:189], v[196:197]
	v_pk_mul_f32 v[190:191], v[190:191], v[198:199]
	v_pk_mul_f32 v[188:189], v[188:189], v[192:193]
	v_pk_mul_f32 v[190:191], v[190:191], v[194:195]
	v_cvt_pk_bf16_f32 v122, v188, v189
	v_cvt_pk_bf16_f32 v123, v190, v191
	v_add_u32_e32 v213, 0x10800, v212
	global_load_dwordx4 v[110:113], v213, s[82:83] offset:16
	v_pk_fma_f32 v[188:189], v[72:73], v[84:85], v[88:89]
	v_pk_fma_f32 v[190:191], v[74:75], v[86:87], v[90:91]
	v_pk_fma_f32 v[192:193], v[64:65], v[100:101], v[104:105]
	v_pk_fma_f32 v[194:195], v[66:67], v[102:103], v[106:107]
	v_fmac_f32_dpp v188, v72, v80 row_shr:1 row_mask:0xf bank_mask:0xf
	v_fmac_f32_dpp v189, v73, v81 row_shr:1 row_mask:0xf bank_mask:0xf
	v_fmac_f32_dpp v190, v74, v82 row_shr:1 row_mask:0xf bank_mask:0xf
	v_fmac_f32_dpp v191, v75, v83 row_shr:1 row_mask:0xf bank_mask:0xf
	v_fmac_f32_dpp v192, v64, v96 row_shr:1 row_mask:0xf bank_mask:0xf
	v_fmac_f32_dpp v193, v65, v97 row_shr:1 row_mask:0xf bank_mask:0xf
	v_fmac_f32_dpp v194, v66, v98 row_shr:1 row_mask:0xf bank_mask:0xf
	v_fmac_f32_dpp v195, v67, v99 row_shr:1 row_mask:0xf bank_mask:0xf
	v_fmac_f32_dpp v188, v72, v76 row_shr:2 row_mask:0xf bank_mask:0xf
	v_fmac_f32_dpp v189, v73, v77 row_shr:2 row_mask:0xf bank_mask:0xf
	v_fmac_f32_dpp v190, v74, v78 row_shr:2 row_mask:0xf bank_mask:0xf
	v_fmac_f32_dpp v191, v75, v79 row_shr:2 row_mask:0xf bank_mask:0xf
	v_fmac_f32_dpp v192, v64, v92 row_shr:2 row_mask:0xf bank_mask:0xf
	v_fmac_f32_dpp v193, v65, v93 row_shr:2 row_mask:0xf bank_mask:0xf
	v_fmac_f32_dpp v194, v66, v94 row_shr:2 row_mask:0xf bank_mask:0xf
	v_fmac_f32_dpp v195, v67, v95 row_shr:2 row_mask:0xf bank_mask:0xf
	v_fmac_f32_dpp v188, v114, v80 row_shl:15 row_mask:0xf bank_mask:0xf
	v_fmac_f32_dpp v189, v115, v81 row_shl:15 row_mask:0xf bank_mask:0xf
	v_fmac_f32_dpp v190, v116, v82 row_shl:15 row_mask:0xf bank_mask:0xf
	v_fmac_f32_dpp v191, v117, v83 row_shl:15 row_mask:0xf bank_mask:0xf
	v_fmac_f32_dpp v192, v68, v96 row_shl:15 row_mask:0xf bank_mask:0xf
	v_fmac_f32_dpp v193, v69, v97 row_shl:15 row_mask:0xf bank_mask:0xf
	v_fmac_f32_dpp v194, v70, v98 row_shl:15 row_mask:0xf bank_mask:0xf
	v_fmac_f32_dpp v195, v71, v99 row_shl:15 row_mask:0xf bank_mask:0xf
	v_fmac_f32_dpp v188, v114, v76 row_shl:14 row_mask:0xf bank_mask:0xf
	v_fmac_f32_dpp v189, v115, v77 row_shl:14 row_mask:0xf bank_mask:0xf
	v_fmac_f32_dpp v190, v116, v78 row_shl:14 row_mask:0xf bank_mask:0xf
	v_fmac_f32_dpp v191, v117, v79 row_shl:14 row_mask:0xf bank_mask:0xf
	v_fmac_f32_dpp v192, v68, v92 row_shl:14 row_mask:0xf bank_mask:0xf
	v_fmac_f32_dpp v193, v69, v93 row_shl:14 row_mask:0xf bank_mask:0xf
	v_fmac_f32_dpp v194, v70, v94 row_shl:14 row_mask:0xf bank_mask:0xf
	v_fmac_f32_dpp v195, v71, v95 row_shl:14 row_mask:0xf bank_mask:0xf
	v_pk_mul_f32 v[196:197], v[188:189], v[216:217] op_sel_hi:[1,0]
	v_pk_mul_f32 v[198:199], v[190:191], v[216:217] op_sel_hi:[1,0]
	v_exp_f32_e32 v196, v196
	v_exp_f32_e32 v197, v197
	v_exp_f32_e32 v198, v198
	v_exp_f32_e32 v199, v199
	v_pk_add_f32 v[196:197], v[196:197], v[214:215] op_sel_hi:[1,0]
	v_pk_add_f32 v[198:199], v[198:199], v[214:215] op_sel_hi:[1,0]
	v_rcp_f32_e32 v196, v196
	v_rcp_f32_e32 v197, v197
	v_rcp_f32_e32 v198, v198
	v_rcp_f32_e32 v199, v199
	v_pk_mul_f32 v[188:189], v[188:189], v[196:197]
	v_pk_mul_f32 v[190:191], v[190:191], v[198:199]
	v_pk_mul_f32 v[188:189], v[188:189], v[192:193]
	v_pk_mul_f32 v[190:191], v[190:191], v[194:195]
	v_cvt_pk_bf16_f32 v114, v188, v189
	v_cvt_pk_bf16_f32 v115, v190, v191
	s_waitcnt vmcnt(0)
	v_pk_fma_f32 v[188:189], v[60:61], v[134:135], v[130:131]
	v_pk_fma_f32 v[190:191], v[62:63], v[136:137], v[132:133]
	v_pk_fma_f32 v[192:193], v[56:57], v[204:205], v[208:209]
	v_pk_fma_f32 v[194:195], v[58:59], v[206:207], v[210:211]
	v_fmac_f32_dpp v188, v60, v142 row_shr:1 row_mask:0xf bank_mask:0xf
	v_fmac_f32_dpp v189, v61, v143 row_shr:1 row_mask:0xf bank_mask:0xf
	v_fmac_f32_dpp v190, v62, v144 row_shr:1 row_mask:0xf bank_mask:0xf
	v_fmac_f32_dpp v191, v63, v145 row_shr:1 row_mask:0xf bank_mask:0xf
	v_fmac_f32_dpp v192, v56, v110 row_shr:1 row_mask:0xf bank_mask:0xf
	v_fmac_f32_dpp v193, v57, v111 row_shr:1 row_mask:0xf bank_mask:0xf
	v_fmac_f32_dpp v194, v58, v112 row_shr:1 row_mask:0xf bank_mask:0xf
	v_fmac_f32_dpp v195, v59, v113 row_shr:1 row_mask:0xf bank_mask:0xf
	v_fmac_f32_dpp v188, v60, v154 row_shr:2 row_mask:0xf bank_mask:0xf
	v_fmac_f32_dpp v189, v61, v155 row_shr:2 row_mask:0xf bank_mask:0xf
	v_fmac_f32_dpp v190, v62, v156 row_shr:2 row_mask:0xf bank_mask:0xf
	v_fmac_f32_dpp v191, v63, v157 row_shr:2 row_mask:0xf bank_mask:0xf
	v_fmac_f32_dpp v192, v56, v118 row_shr:2 row_mask:0xf bank_mask:0xf
	v_fmac_f32_dpp v193, v57, v119 row_shr:2 row_mask:0xf bank_mask:0xf
	v_fmac_f32_dpp v194, v58, v120 row_shr:2 row_mask:0xf bank_mask:0xf
	v_fmac_f32_dpp v195, v59, v121 row_shr:2 row_mask:0xf bank_mask:0xf
	v_pk_mul_f32 v[196:197], v[188:189], v[216:217] op_sel_hi:[1,0]
	v_pk_mul_f32 v[198:199], v[190:191], v[216:217] op_sel_hi:[1,0]
	v_exp_f32_e32 v196, v196
	v_exp_f32_e32 v197, v197
	v_exp_f32_e32 v198, v198
	v_exp_f32_e32 v199, v199
	v_pk_add_f32 v[196:197], v[196:197], v[214:215] op_sel_hi:[1,0]
	v_pk_add_f32 v[198:199], v[198:199], v[214:215] op_sel_hi:[1,0]
	v_rcp_f32_e32 v196, v196
	v_rcp_f32_e32 v197, v197
	v_rcp_f32_e32 v198, v198
	v_rcp_f32_e32 v199, v199
	v_pk_mul_f32 v[188:189], v[188:189], v[196:197]
	v_pk_mul_f32 v[190:191], v[190:191], v[198:199]
	v_pk_mul_f32 v[188:189], v[188:189], v[192:193]
	v_pk_mul_f32 v[190:191], v[190:191], v[194:195]
	v_cvt_pk_bf16_f32 v202, v188, v189
	v_cvt_pk_bf16_f32 v203, v190, v191
	s_mov_b64 exec, vcc
	global_store_dwordx4 v215, v[200:203], s[96:97]
	s_mov_b64 exec, -1
	v_pk_fma_f32 v[188:189], v[52:53], v[134:135], v[130:131]
	v_pk_fma_f32 v[190:191], v[54:55], v[136:137], v[132:133]
	v_pk_fma_f32 v[192:193], v[44:45], v[204:205], v[208:209]
	v_pk_fma_f32 v[194:195], v[46:47], v[206:207], v[210:211]
	v_fmac_f32_dpp v188, v52, v142 row_shr:1 row_mask:0xf bank_mask:0xf
	v_fmac_f32_dpp v189, v53, v143 row_shr:1 row_mask:0xf bank_mask:0xf
	v_fmac_f32_dpp v190, v54, v144 row_shr:1 row_mask:0xf bank_mask:0xf
	v_fmac_f32_dpp v191, v55, v145 row_shr:1 row_mask:0xf bank_mask:0xf
	v_fmac_f32_dpp v192, v44, v110 row_shr:1 row_mask:0xf bank_mask:0xf
	v_fmac_f32_dpp v193, v45, v111 row_shr:1 row_mask:0xf bank_mask:0xf
	v_fmac_f32_dpp v194, v46, v112 row_shr:1 row_mask:0xf bank_mask:0xf
	v_fmac_f32_dpp v195, v47, v113 row_shr:1 row_mask:0xf bank_mask:0xf
	v_fmac_f32_dpp v188, v52, v154 row_shr:2 row_mask:0xf bank_mask:0xf
	v_fmac_f32_dpp v189, v53, v155 row_shr:2 row_mask:0xf bank_mask:0xf
	v_fmac_f32_dpp v190, v54, v156 row_shr:2 row_mask:0xf bank_mask:0xf
	v_fmac_f32_dpp v191, v55, v157 row_shr:2 row_mask:0xf bank_mask:0xf
	v_fmac_f32_dpp v192, v44, v118 row_shr:2 row_mask:0xf bank_mask:0xf
	v_fmac_f32_dpp v193, v45, v119 row_shr:2 row_mask:0xf bank_mask:0xf
	v_fmac_f32_dpp v194, v46, v120 row_shr:2 row_mask:0xf bank_mask:0xf
	v_fmac_f32_dpp v195, v47, v121 row_shr:2 row_mask:0xf bank_mask:0xf
	v_fmac_f32_dpp v188, v60, v142 row_shl:15 row_mask:0xf bank_mask:0xf
	v_fmac_f32_dpp v189, v61, v143 row_shl:15 row_mask:0xf bank_mask:0xf
	v_fmac_f32_dpp v190, v62, v144 row_shl:15 row_mask:0xf bank_mask:0xf
	v_fmac_f32_dpp v191, v63, v145 row_shl:15 row_mask:0xf bank_mask:0xf
	v_fmac_f32_dpp v192, v56, v110 row_shl:15 row_mask:0xf bank_mask:0xf
	v_fmac_f32_dpp v193, v57, v111 row_shl:15 row_mask:0xf bank_mask:0xf
	v_fmac_f32_dpp v194, v58, v112 row_shl:15 row_mask:0xf bank_mask:0xf
	v_fmac_f32_dpp v195, v59, v113 row_shl:15 row_mask:0xf bank_mask:0xf
	v_fmac_f32_dpp v188, v60, v154 row_shl:14 row_mask:0xf bank_mask:0xf
	v_fmac_f32_dpp v189, v61, v155 row_shl:14 row_mask:0xf bank_mask:0xf
	v_fmac_f32_dpp v190, v62, v156 row_shl:14 row_mask:0xf bank_mask:0xf
	v_fmac_f32_dpp v191, v63, v157 row_shl:14 row_mask:0xf bank_mask:0xf
	v_fmac_f32_dpp v192, v56, v118 row_shl:14 row_mask:0xf bank_mask:0xf
	v_fmac_f32_dpp v193, v57, v119 row_shl:14 row_mask:0xf bank_mask:0xf
	v_fmac_f32_dpp v194, v58, v120 row_shl:14 row_mask:0xf bank_mask:0xf
	v_fmac_f32_dpp v195, v59, v121 row_shl:14 row_mask:0xf bank_mask:0xf
	v_pk_mul_f32 v[196:197], v[188:189], v[216:217] op_sel_hi:[1,0]
	v_pk_mul_f32 v[198:199], v[190:191], v[216:217] op_sel_hi:[1,0]
	v_exp_f32_e32 v196, v196
	v_exp_f32_e32 v197, v197
	v_exp_f32_e32 v198, v198
	v_exp_f32_e32 v199, v199
	v_pk_add_f32 v[196:197], v[196:197], v[214:215] op_sel_hi:[1,0]
	v_pk_add_f32 v[198:199], v[198:199], v[214:215] op_sel_hi:[1,0]
	v_rcp_f32_e32 v196, v196
	v_rcp_f32_e32 v197, v197
	v_rcp_f32_e32 v198, v198
	v_rcp_f32_e32 v199, v199
	v_pk_mul_f32 v[188:189], v[188:189], v[196:197]
	v_pk_mul_f32 v[190:191], v[190:191], v[198:199]
	v_pk_mul_f32 v[188:189], v[188:189], v[192:193]
	v_pk_mul_f32 v[190:191], v[190:191], v[194:195]
	v_cvt_pk_bf16_f32 v160, v188, v189
	v_cvt_pk_bf16_f32 v161, v190, v191
	v_add_u32_e32 v213, 0x2c000, v215
	global_store_dwordx4 v213, v[158:161], s[96:97]
	v_pk_fma_f32 v[188:189], v[48:49], v[134:135], v[130:131]
	v_pk_fma_f32 v[190:191], v[50:51], v[136:137], v[132:133]
	v_pk_fma_f32 v[192:193], v[36:37], v[204:205], v[208:209]
	v_pk_fma_f32 v[194:195], v[38:39], v[206:207], v[210:211]
	v_fmac_f32_dpp v188, v48, v142 row_shr:1 row_mask:0xf bank_mask:0xf
	v_fmac_f32_dpp v189, v49, v143 row_shr:1 row_mask:0xf bank_mask:0xf
	v_fmac_f32_dpp v190, v50, v144 row_shr:1 row_mask:0xf bank_mask:0xf
	v_fmac_f32_dpp v191, v51, v145 row_shr:1 row_mask:0xf bank_mask:0xf
	v_fmac_f32_dpp v192, v36, v110 row_shr:1 row_mask:0xf bank_mask:0xf
	v_fmac_f32_dpp v193, v37, v111 row_shr:1 row_mask:0xf bank_mask:0xf
	v_fmac_f32_dpp v194, v38, v112 row_shr:1 row_mask:0xf bank_mask:0xf
	v_fmac_f32_dpp v195, v39, v113 row_shr:1 row_mask:0xf bank_mask:0xf
	v_fmac_f32_dpp v188, v48, v154 row_shr:2 row_mask:0xf bank_mask:0xf
	v_fmac_f32_dpp v189, v49, v155 row_shr:2 row_mask:0xf bank_mask:0xf
	v_fmac_f32_dpp v190, v50, v156 row_shr:2 row_mask:0xf bank_mask:0xf
	v_fmac_f32_dpp v191, v51, v157 row_shr:2 row_mask:0xf bank_mask:0xf
	v_fmac_f32_dpp v192, v36, v118 row_shr:2 row_mask:0xf bank_mask:0xf
	v_fmac_f32_dpp v193, v37, v119 row_shr:2 row_mask:0xf bank_mask:0xf
	v_fmac_f32_dpp v194, v38, v120 row_shr:2 row_mask:0xf bank_mask:0xf
	v_fmac_f32_dpp v195, v39, v121 row_shr:2 row_mask:0xf bank_mask:0xf
	v_fmac_f32_dpp v188, v52, v142 row_shl:15 row_mask:0xf bank_mask:0xf
	v_fmac_f32_dpp v189, v53, v143 row_shl:15 row_mask:0xf bank_mask:0xf
	v_fmac_f32_dpp v190, v54, v144 row_shl:15 row_mask:0xf bank_mask:0xf
	v_fmac_f32_dpp v191, v55, v145 row_shl:15 row_mask:0xf bank_mask:0xf
	v_fmac_f32_dpp v192, v44, v110 row_shl:15 row_mask:0xf bank_mask:0xf
	v_fmac_f32_dpp v193, v45, v111 row_shl:15 row_mask:0xf bank_mask:0xf
	v_fmac_f32_dpp v194, v46, v112 row_shl:15 row_mask:0xf bank_mask:0xf
	v_fmac_f32_dpp v195, v47, v113 row_shl:15 row_mask:0xf bank_mask:0xf
	v_fmac_f32_dpp v188, v52, v154 row_shl:14 row_mask:0xf bank_mask:0xf
	v_fmac_f32_dpp v189, v53, v155 row_shl:14 row_mask:0xf bank_mask:0xf
	v_fmac_f32_dpp v190, v54, v156 row_shl:14 row_mask:0xf bank_mask:0xf
	v_fmac_f32_dpp v191, v55, v157 row_shl:14 row_mask:0xf bank_mask:0xf
	v_fmac_f32_dpp v192, v44, v118 row_shl:14 row_mask:0xf bank_mask:0xf
	v_fmac_f32_dpp v193, v45, v119 row_shl:14 row_mask:0xf bank_mask:0xf
	v_fmac_f32_dpp v194, v46, v120 row_shl:14 row_mask:0xf bank_mask:0xf
	v_fmac_f32_dpp v195, v47, v121 row_shl:14 row_mask:0xf bank_mask:0xf
	v_pk_mul_f32 v[196:197], v[188:189], v[216:217] op_sel_hi:[1,0]
	v_pk_mul_f32 v[198:199], v[190:191], v[216:217] op_sel_hi:[1,0]
	v_exp_f32_e32 v196, v196
	v_exp_f32_e32 v197, v197
	v_exp_f32_e32 v198, v198
	v_exp_f32_e32 v199, v199
	v_pk_add_f32 v[196:197], v[196:197], v[214:215] op_sel_hi:[1,0]
	v_pk_add_f32 v[198:199], v[198:199], v[214:215] op_sel_hi:[1,0]
	v_rcp_f32_e32 v196, v196
	v_rcp_f32_e32 v197, v197
	v_rcp_f32_e32 v198, v198
	v_rcp_f32_e32 v199, v199
	v_pk_mul_f32 v[188:189], v[188:189], v[196:197]
	v_pk_mul_f32 v[190:191], v[190:191], v[198:199]
	v_pk_mul_f32 v[188:189], v[188:189], v[192:193]
	v_pk_mul_f32 v[190:191], v[190:191], v[194:195]
	v_cvt_pk_bf16_f32 v152, v188, v189
	v_cvt_pk_bf16_f32 v153, v190, v191
	v_add_u32_e32 v213, 0x58000, v215
	global_store_dwordx4 v213, v[150:153], s[96:97]
	v_pk_fma_f32 v[188:189], v[40:41], v[134:135], v[130:131]
	v_pk_fma_f32 v[190:191], v[42:43], v[136:137], v[132:133]
	v_pk_fma_f32 v[192:193], v[32:33], v[204:205], v[208:209]
	v_pk_fma_f32 v[194:195], v[34:35], v[206:207], v[210:211]
	v_fmac_f32_dpp v188, v40, v142 row_shr:1 row_mask:0xf bank_mask:0xf
	v_fmac_f32_dpp v189, v41, v143 row_shr:1 row_mask:0xf bank_mask:0xf
	v_fmac_f32_dpp v190, v42, v144 row_shr:1 row_mask:0xf bank_mask:0xf
	v_fmac_f32_dpp v191, v43, v145 row_shr:1 row_mask:0xf bank_mask:0xf
	v_fmac_f32_dpp v192, v32, v110 row_shr:1 row_mask:0xf bank_mask:0xf
	v_fmac_f32_dpp v193, v33, v111 row_shr:1 row_mask:0xf bank_mask:0xf
	v_fmac_f32_dpp v194, v34, v112 row_shr:1 row_mask:0xf bank_mask:0xf
	v_fmac_f32_dpp v195, v35, v113 row_shr:1 row_mask:0xf bank_mask:0xf
	v_fmac_f32_dpp v188, v40, v154 row_shr:2 row_mask:0xf bank_mask:0xf
	v_fmac_f32_dpp v189, v41, v155 row_shr:2 row_mask:0xf bank_mask:0xf
	v_fmac_f32_dpp v190, v42, v156 row_shr:2 row_mask:0xf bank_mask:0xf
	v_fmac_f32_dpp v191, v43, v157 row_shr:2 row_mask:0xf bank_mask:0xf
	v_fmac_f32_dpp v192, v32, v118 row_shr:2 row_mask:0xf bank_mask:0xf
	v_fmac_f32_dpp v193, v33, v119 row_shr:2 row_mask:0xf bank_mask:0xf
	v_fmac_f32_dpp v194, v34, v120 row_shr:2 row_mask:0xf bank_mask:0xf
	v_fmac_f32_dpp v195, v35, v121 row_shr:2 row_mask:0xf bank_mask:0xf
	v_fmac_f32_dpp v188, v48, v142 row_shl:15 row_mask:0xf bank_mask:0xf
	v_fmac_f32_dpp v189, v49, v143 row_shl:15 row_mask:0xf bank_mask:0xf
	v_fmac_f32_dpp v190, v50, v144 row_shl:15 row_mask:0xf bank_mask:0xf
	v_fmac_f32_dpp v191, v51, v145 row_shl:15 row_mask:0xf bank_mask:0xf
	v_fmac_f32_dpp v192, v36, v110 row_shl:15 row_mask:0xf bank_mask:0xf
	v_fmac_f32_dpp v193, v37, v111 row_shl:15 row_mask:0xf bank_mask:0xf
	v_fmac_f32_dpp v194, v38, v112 row_shl:15 row_mask:0xf bank_mask:0xf
	v_fmac_f32_dpp v195, v39, v113 row_shl:15 row_mask:0xf bank_mask:0xf
	v_fmac_f32_dpp v188, v48, v154 row_shl:14 row_mask:0xf bank_mask:0xf
	v_fmac_f32_dpp v189, v49, v155 row_shl:14 row_mask:0xf bank_mask:0xf
	v_fmac_f32_dpp v190, v50, v156 row_shl:14 row_mask:0xf bank_mask:0xf
	v_fmac_f32_dpp v191, v51, v157 row_shl:14 row_mask:0xf bank_mask:0xf
	v_fmac_f32_dpp v192, v36, v118 row_shl:14 row_mask:0xf bank_mask:0xf
	v_fmac_f32_dpp v193, v37, v119 row_shl:14 row_mask:0xf bank_mask:0xf
	v_fmac_f32_dpp v194, v38, v120 row_shl:14 row_mask:0xf bank_mask:0xf
	v_fmac_f32_dpp v195, v39, v121 row_shl:14 row_mask:0xf bank_mask:0xf
	v_pk_mul_f32 v[196:197], v[188:189], v[216:217] op_sel_hi:[1,0]
	v_pk_mul_f32 v[198:199], v[190:191], v[216:217] op_sel_hi:[1,0]
	v_exp_f32_e32 v196, v196
	v_exp_f32_e32 v197, v197
	v_exp_f32_e32 v198, v198
	v_exp_f32_e32 v199, v199
	v_pk_add_f32 v[196:197], v[196:197], v[214:215] op_sel_hi:[1,0]
	v_pk_add_f32 v[198:199], v[198:199], v[214:215] op_sel_hi:[1,0]
	v_rcp_f32_e32 v196, v196
	v_rcp_f32_e32 v197, v197
	v_rcp_f32_e32 v198, v198
	v_rcp_f32_e32 v199, v199
	v_pk_mul_f32 v[188:189], v[188:189], v[196:197]
	v_pk_mul_f32 v[190:191], v[190:191], v[198:199]
	v_pk_mul_f32 v[188:189], v[188:189], v[192:193]
	v_pk_mul_f32 v[190:191], v[190:191], v[194:195]
	v_cvt_pk_bf16_f32 v148, v188, v189
	v_cvt_pk_bf16_f32 v149, v190, v191
	v_add_u32_e32 v213, 0x84000, v215
	global_store_dwordx4 v213, v[146:149], s[96:97]
	v_pk_fma_f32 v[188:189], v[28:29], v[134:135], v[130:131]
	v_pk_fma_f32 v[190:191], v[30:31], v[136:137], v[132:133]
	v_pk_fma_f32 v[192:193], v[16:17], v[204:205], v[208:209]
	v_pk_fma_f32 v[194:195], v[18:19], v[206:207], v[210:211]
	v_fmac_f32_dpp v188, v28, v142 row_shr:1 row_mask:0xf bank_mask:0xf
	v_fmac_f32_dpp v189, v29, v143 row_shr:1 row_mask:0xf bank_mask:0xf
	v_fmac_f32_dpp v190, v30, v144 row_shr:1 row_mask:0xf bank_mask:0xf
	v_fmac_f32_dpp v191, v31, v145 row_shr:1 row_mask:0xf bank_mask:0xf
	v_fmac_f32_dpp v192, v16, v110 row_shr:1 row_mask:0xf bank_mask:0xf
	v_fmac_f32_dpp v193, v17, v111 row_shr:1 row_mask:0xf bank_mask:0xf
	v_fmac_f32_dpp v194, v18, v112 row_shr:1 row_mask:0xf bank_mask:0xf
	v_fmac_f32_dpp v195, v19, v113 row_shr:1 row_mask:0xf bank_mask:0xf
	v_fmac_f32_dpp v188, v28, v154 row_shr:2 row_mask:0xf bank_mask:0xf
	v_fmac_f32_dpp v189, v29, v155 row_shr:2 row_mask:0xf bank_mask:0xf
	v_fmac_f32_dpp v190, v30, v156 row_shr:2 row_mask:0xf bank_mask:0xf
	v_fmac_f32_dpp v191, v31, v157 row_shr:2 row_mask:0xf bank_mask:0xf
	v_fmac_f32_dpp v192, v16, v118 row_shr:2 row_mask:0xf bank_mask:0xf
	v_fmac_f32_dpp v193, v17, v119 row_shr:2 row_mask:0xf bank_mask:0xf
	v_fmac_f32_dpp v194, v18, v120 row_shr:2 row_mask:0xf bank_mask:0xf
	v_fmac_f32_dpp v195, v19, v121 row_shr:2 row_mask:0xf bank_mask:0xf
	v_fmac_f32_dpp v188, v40, v142 row_shl:15 row_mask:0xf bank_mask:0xf
	v_fmac_f32_dpp v189, v41, v143 row_shl:15 row_mask:0xf bank_mask:0xf
	v_fmac_f32_dpp v190, v42, v144 row_shl:15 row_mask:0xf bank_mask:0xf
	v_fmac_f32_dpp v191, v43, v145 row_shl:15 row_mask:0xf bank_mask:0xf
	v_fmac_f32_dpp v192, v32, v110 row_shl:15 row_mask:0xf bank_mask:0xf
	v_fmac_f32_dpp v193, v33, v111 row_shl:15 row_mask:0xf bank_mask:0xf
	v_fmac_f32_dpp v194, v34, v112 row_shl:15 row_mask:0xf bank_mask:0xf
	v_fmac_f32_dpp v195, v35, v113 row_shl:15 row_mask:0xf bank_mask:0xf
	v_fmac_f32_dpp v188, v40, v154 row_shl:14 row_mask:0xf bank_mask:0xf
	v_fmac_f32_dpp v189, v41, v155 row_shl:14 row_mask:0xf bank_mask:0xf
	v_fmac_f32_dpp v190, v42, v156 row_shl:14 row_mask:0xf bank_mask:0xf
	v_fmac_f32_dpp v191, v43, v157 row_shl:14 row_mask:0xf bank_mask:0xf
	v_fmac_f32_dpp v192, v32, v118 row_shl:14 row_mask:0xf bank_mask:0xf
	v_fmac_f32_dpp v193, v33, v119 row_shl:14 row_mask:0xf bank_mask:0xf
	v_fmac_f32_dpp v194, v34, v120 row_shl:14 row_mask:0xf bank_mask:0xf
	v_fmac_f32_dpp v195, v35, v121 row_shl:14 row_mask:0xf bank_mask:0xf
	v_pk_mul_f32 v[196:197], v[188:189], v[216:217] op_sel_hi:[1,0]
	v_pk_mul_f32 v[198:199], v[190:191], v[216:217] op_sel_hi:[1,0]
	v_exp_f32_e32 v196, v196
	v_exp_f32_e32 v197, v197
	v_exp_f32_e32 v198, v198
	v_exp_f32_e32 v199, v199
	v_pk_add_f32 v[196:197], v[196:197], v[214:215] op_sel_hi:[1,0]
	v_pk_add_f32 v[198:199], v[198:199], v[214:215] op_sel_hi:[1,0]
	v_rcp_f32_e32 v196, v196
	v_rcp_f32_e32 v197, v197
	v_rcp_f32_e32 v198, v198
	v_rcp_f32_e32 v199, v199
	v_pk_mul_f32 v[188:189], v[188:189], v[196:197]
	v_pk_mul_f32 v[190:191], v[190:191], v[198:199]
	v_pk_mul_f32 v[188:189], v[188:189], v[192:193]
	v_pk_mul_f32 v[190:191], v[190:191], v[194:195]
	v_cvt_pk_bf16_f32 v140, v188, v189
	v_cvt_pk_bf16_f32 v141, v190, v191
	v_add_u32_e32 v213, 0xb0000, v215
	global_store_dwordx4 v213, v[138:141], s[96:97]
	v_pk_fma_f32 v[188:189], v[24:25], v[134:135], v[130:131]
	v_pk_fma_f32 v[190:191], v[26:27], v[136:137], v[132:133]
	v_pk_fma_f32 v[192:193], v[12:13], v[204:205], v[208:209]
	v_pk_fma_f32 v[194:195], v[14:15], v[206:207], v[210:211]
	v_fmac_f32_dpp v188, v24, v142 row_shr:1 row_mask:0xf bank_mask:0xf
	v_fmac_f32_dpp v189, v25, v143 row_shr:1 row_mask:0xf bank_mask:0xf
	v_fmac_f32_dpp v190, v26, v144 row_shr:1 row_mask:0xf bank_mask:0xf
	v_fmac_f32_dpp v191, v27, v145 row_shr:1 row_mask:0xf bank_mask:0xf
	v_fmac_f32_dpp v192, v12, v110 row_shr:1 row_mask:0xf bank_mask:0xf
	v_fmac_f32_dpp v193, v13, v111 row_shr:1 row_mask:0xf bank_mask:0xf
	v_fmac_f32_dpp v194, v14, v112 row_shr:1 row_mask:0xf bank_mask:0xf
	v_fmac_f32_dpp v195, v15, v113 row_shr:1 row_mask:0xf bank_mask:0xf
	v_fmac_f32_dpp v188, v24, v154 row_shr:2 row_mask:0xf bank_mask:0xf
	v_fmac_f32_dpp v189, v25, v155 row_shr:2 row_mask:0xf bank_mask:0xf
	v_fmac_f32_dpp v190, v26, v156 row_shr:2 row_mask:0xf bank_mask:0xf
	v_fmac_f32_dpp v191, v27, v157 row_shr:2 row_mask:0xf bank_mask:0xf
	v_fmac_f32_dpp v192, v12, v118 row_shr:2 row_mask:0xf bank_mask:0xf
	v_fmac_f32_dpp v193, v13, v119 row_shr:2 row_mask:0xf bank_mask:0xf
	v_fmac_f32_dpp v194, v14, v120 row_shr:2 row_mask:0xf bank_mask:0xf
	v_fmac_f32_dpp v195, v15, v121 row_shr:2 row_mask:0xf bank_mask:0xf
	v_fmac_f32_dpp v188, v28, v142 row_shl:15 row_mask:0xf bank_mask:0xf
	v_fmac_f32_dpp v189, v29, v143 row_shl:15 row_mask:0xf bank_mask:0xf
	v_fmac_f32_dpp v190, v30, v144 row_shl:15 row_mask:0xf bank_mask:0xf
	v_fmac_f32_dpp v191, v31, v145 row_shl:15 row_mask:0xf bank_mask:0xf
	v_fmac_f32_dpp v192, v16, v110 row_shl:15 row_mask:0xf bank_mask:0xf
	v_fmac_f32_dpp v193, v17, v111 row_shl:15 row_mask:0xf bank_mask:0xf
	v_fmac_f32_dpp v194, v18, v112 row_shl:15 row_mask:0xf bank_mask:0xf
	v_fmac_f32_dpp v195, v19, v113 row_shl:15 row_mask:0xf bank_mask:0xf
	v_fmac_f32_dpp v188, v28, v154 row_shl:14 row_mask:0xf bank_mask:0xf
	v_fmac_f32_dpp v189, v29, v155 row_shl:14 row_mask:0xf bank_mask:0xf
	v_fmac_f32_dpp v190, v30, v156 row_shl:14 row_mask:0xf bank_mask:0xf
	v_fmac_f32_dpp v191, v31, v157 row_shl:14 row_mask:0xf bank_mask:0xf
	v_fmac_f32_dpp v192, v16, v118 row_shl:14 row_mask:0xf bank_mask:0xf
	v_fmac_f32_dpp v193, v17, v119 row_shl:14 row_mask:0xf bank_mask:0xf
	v_fmac_f32_dpp v194, v18, v120 row_shl:14 row_mask:0xf bank_mask:0xf
	v_fmac_f32_dpp v195, v19, v121 row_shl:14 row_mask:0xf bank_mask:0xf
	v_pk_mul_f32 v[196:197], v[188:189], v[216:217] op_sel_hi:[1,0]
	v_pk_mul_f32 v[198:199], v[190:191], v[216:217] op_sel_hi:[1,0]
	v_exp_f32_e32 v196, v196
	v_exp_f32_e32 v197, v197
	v_exp_f32_e32 v198, v198
	v_exp_f32_e32 v199, v199
	v_pk_add_f32 v[196:197], v[196:197], v[214:215] op_sel_hi:[1,0]
	v_pk_add_f32 v[198:199], v[198:199], v[214:215] op_sel_hi:[1,0]
	v_rcp_f32_e32 v196, v196
	v_rcp_f32_e32 v197, v197
	v_rcp_f32_e32 v198, v198
	v_rcp_f32_e32 v199, v199
	v_pk_mul_f32 v[188:189], v[188:189], v[196:197]
	v_pk_mul_f32 v[190:191], v[190:191], v[198:199]
	v_pk_mul_f32 v[188:189], v[188:189], v[192:193]
	v_pk_mul_f32 v[190:191], v[190:191], v[194:195]
	v_cvt_pk_bf16_f32 v128, v188, v189
	v_cvt_pk_bf16_f32 v129, v190, v191
	v_add_u32_e32 v213, 0xdc000, v215
	global_store_dwordx4 v213, v[126:129], s[96:97]
	v_pk_fma_f32 v[188:189], v[20:21], v[134:135], v[130:131]
	v_pk_fma_f32 v[190:191], v[22:23], v[136:137], v[132:133]
	v_pk_fma_f32 v[192:193], v[8:9], v[204:205], v[208:209]
	v_pk_fma_f32 v[194:195], v[10:11], v[206:207], v[210:211]
	v_fmac_f32_dpp v188, v20, v142 row_shr:1 row_mask:0xf bank_mask:0xf
	v_fmac_f32_dpp v189, v21, v143 row_shr:1 row_mask:0xf bank_mask:0xf
	v_fmac_f32_dpp v190, v22, v144 row_shr:1 row_mask:0xf bank_mask:0xf
	v_fmac_f32_dpp v191, v23, v145 row_shr:1 row_mask:0xf bank_mask:0xf
	v_fmac_f32_dpp v192, v8, v110 row_shr:1 row_mask:0xf bank_mask:0xf
	v_fmac_f32_dpp v193, v9, v111 row_shr:1 row_mask:0xf bank_mask:0xf
	v_fmac_f32_dpp v194, v10, v112 row_shr:1 row_mask:0xf bank_mask:0xf
	v_fmac_f32_dpp v195, v11, v113 row_shr:1 row_mask:0xf bank_mask:0xf
	v_fmac_f32_dpp v188, v20, v154 row_shr:2 row_mask:0xf bank_mask:0xf
	v_fmac_f32_dpp v189, v21, v155 row_shr:2 row_mask:0xf bank_mask:0xf
	v_fmac_f32_dpp v190, v22, v156 row_shr:2 row_mask:0xf bank_mask:0xf
	v_fmac_f32_dpp v191, v23, v157 row_shr:2 row_mask:0xf bank_mask:0xf
	v_fmac_f32_dpp v192, v8, v118 row_shr:2 row_mask:0xf bank_mask:0xf
	v_fmac_f32_dpp v193, v9, v119 row_shr:2 row_mask:0xf bank_mask:0xf
	v_fmac_f32_dpp v194, v10, v120 row_shr:2 row_mask:0xf bank_mask:0xf
	v_fmac_f32_dpp v195, v11, v121 row_shr:2 row_mask:0xf bank_mask:0xf
	v_fmac_f32_dpp v188, v24, v142 row_shl:15 row_mask:0xf bank_mask:0xf
	v_fmac_f32_dpp v189, v25, v143 row_shl:15 row_mask:0xf bank_mask:0xf
	v_fmac_f32_dpp v190, v26, v144 row_shl:15 row_mask:0xf bank_mask:0xf
	v_fmac_f32_dpp v191, v27, v145 row_shl:15 row_mask:0xf bank_mask:0xf
	v_fmac_f32_dpp v192, v12, v110 row_shl:15 row_mask:0xf bank_mask:0xf
	v_fmac_f32_dpp v193, v13, v111 row_shl:15 row_mask:0xf bank_mask:0xf
	v_fmac_f32_dpp v194, v14, v112 row_shl:15 row_mask:0xf bank_mask:0xf
	v_fmac_f32_dpp v195, v15, v113 row_shl:15 row_mask:0xf bank_mask:0xf
	v_fmac_f32_dpp v188, v24, v154 row_shl:14 row_mask:0xf bank_mask:0xf
	v_fmac_f32_dpp v189, v25, v155 row_shl:14 row_mask:0xf bank_mask:0xf
	v_fmac_f32_dpp v190, v26, v156 row_shl:14 row_mask:0xf bank_mask:0xf
	v_fmac_f32_dpp v191, v27, v157 row_shl:14 row_mask:0xf bank_mask:0xf
	v_fmac_f32_dpp v192, v12, v118 row_shl:14 row_mask:0xf bank_mask:0xf
	v_fmac_f32_dpp v193, v13, v119 row_shl:14 row_mask:0xf bank_mask:0xf
	v_fmac_f32_dpp v194, v14, v120 row_shl:14 row_mask:0xf bank_mask:0xf
	v_fmac_f32_dpp v195, v15, v121 row_shl:14 row_mask:0xf bank_mask:0xf
	v_pk_mul_f32 v[196:197], v[188:189], v[216:217] op_sel_hi:[1,0]
	v_pk_mul_f32 v[198:199], v[190:191], v[216:217] op_sel_hi:[1,0]
	v_exp_f32_e32 v196, v196
	v_exp_f32_e32 v197, v197
	v_exp_f32_e32 v198, v198
	v_exp_f32_e32 v199, v199
	v_pk_add_f32 v[196:197], v[196:197], v[214:215] op_sel_hi:[1,0]
	v_pk_add_f32 v[198:199], v[198:199], v[214:215] op_sel_hi:[1,0]
	v_rcp_f32_e32 v196, v196
	v_rcp_f32_e32 v197, v197
	v_rcp_f32_e32 v198, v198
	v_rcp_f32_e32 v199, v199
	v_pk_mul_f32 v[188:189], v[188:189], v[196:197]
	v_pk_mul_f32 v[190:191], v[190:191], v[198:199]
	v_pk_mul_f32 v[188:189], v[188:189], v[192:193]
	v_pk_mul_f32 v[190:191], v[190:191], v[194:195]
	v_cvt_pk_bf16_f32 v124, v188, v189
	v_cvt_pk_bf16_f32 v125, v190, v191
	v_add_u32_e32 v213, 0x108000, v215
	global_store_dwordx4 v213, v[122:125], s[96:97]
	v_pk_fma_f32 v[188:189], v[4:5], v[134:135], v[130:131]
	v_pk_fma_f32 v[190:191], v[6:7], v[136:137], v[132:133]
	v_pk_fma_f32 v[192:193], v[0:1], v[204:205], v[208:209]
	v_pk_fma_f32 v[194:195], v[2:3], v[206:207], v[210:211]
	v_fmac_f32_dpp v188, v4, v142 row_shr:1 row_mask:0xf bank_mask:0xf
	v_fmac_f32_dpp v189, v5, v143 row_shr:1 row_mask:0xf bank_mask:0xf
	v_fmac_f32_dpp v190, v6, v144 row_shr:1 row_mask:0xf bank_mask:0xf
	v_fmac_f32_dpp v191, v7, v145 row_shr:1 row_mask:0xf bank_mask:0xf
	v_fmac_f32_dpp v192, v0, v110 row_shr:1 row_mask:0xf bank_mask:0xf
	v_fmac_f32_dpp v193, v1, v111 row_shr:1 row_mask:0xf bank_mask:0xf
	v_fmac_f32_dpp v194, v2, v112 row_shr:1 row_mask:0xf bank_mask:0xf
	v_fmac_f32_dpp v195, v3, v113 row_shr:1 row_mask:0xf bank_mask:0xf
	v_fmac_f32_dpp v188, v4, v154 row_shr:2 row_mask:0xf bank_mask:0xf
	v_fmac_f32_dpp v189, v5, v155 row_shr:2 row_mask:0xf bank_mask:0xf
	v_fmac_f32_dpp v190, v6, v156 row_shr:2 row_mask:0xf bank_mask:0xf
	v_fmac_f32_dpp v191, v7, v157 row_shr:2 row_mask:0xf bank_mask:0xf
	v_fmac_f32_dpp v192, v0, v118 row_shr:2 row_mask:0xf bank_mask:0xf
	v_fmac_f32_dpp v193, v1, v119 row_shr:2 row_mask:0xf bank_mask:0xf
	v_fmac_f32_dpp v194, v2, v120 row_shr:2 row_mask:0xf bank_mask:0xf
	v_fmac_f32_dpp v195, v3, v121 row_shr:2 row_mask:0xf bank_mask:0xf
	v_fmac_f32_dpp v188, v20, v142 row_shl:15 row_mask:0xf bank_mask:0xf
	v_fmac_f32_dpp v189, v21, v143 row_shl:15 row_mask:0xf bank_mask:0xf
	v_fmac_f32_dpp v190, v22, v144 row_shl:15 row_mask:0xf bank_mask:0xf
	v_fmac_f32_dpp v191, v23, v145 row_shl:15 row_mask:0xf bank_mask:0xf
	v_fmac_f32_dpp v192, v8, v110 row_shl:15 row_mask:0xf bank_mask:0xf
	v_fmac_f32_dpp v193, v9, v111 row_shl:15 row_mask:0xf bank_mask:0xf
	v_fmac_f32_dpp v194, v10, v112 row_shl:15 row_mask:0xf bank_mask:0xf
	v_fmac_f32_dpp v195, v11, v113 row_shl:15 row_mask:0xf bank_mask:0xf
	v_fmac_f32_dpp v188, v20, v154 row_shl:14 row_mask:0xf bank_mask:0xf
	v_fmac_f32_dpp v189, v21, v155 row_shl:14 row_mask:0xf bank_mask:0xf
	v_fmac_f32_dpp v190, v22, v156 row_shl:14 row_mask:0xf bank_mask:0xf
	v_fmac_f32_dpp v191, v23, v157 row_shl:14 row_mask:0xf bank_mask:0xf
	v_fmac_f32_dpp v192, v8, v118 row_shl:14 row_mask:0xf bank_mask:0xf
	v_fmac_f32_dpp v193, v9, v119 row_shl:14 row_mask:0xf bank_mask:0xf
	v_fmac_f32_dpp v194, v10, v120 row_shl:14 row_mask:0xf bank_mask:0xf
	v_fmac_f32_dpp v195, v11, v121 row_shl:14 row_mask:0xf bank_mask:0xf
	v_pk_mul_f32 v[196:197], v[188:189], v[216:217] op_sel_hi:[1,0]
	v_pk_mul_f32 v[198:199], v[190:191], v[216:217] op_sel_hi:[1,0]
	v_exp_f32_e32 v196, v196
	v_exp_f32_e32 v197, v197
	v_exp_f32_e32 v198, v198
	v_exp_f32_e32 v199, v199
	v_pk_add_f32 v[196:197], v[196:197], v[214:215] op_sel_hi:[1,0]
	v_pk_add_f32 v[198:199], v[198:199], v[214:215] op_sel_hi:[1,0]
	v_rcp_f32_e32 v196, v196
	v_rcp_f32_e32 v197, v197
	v_rcp_f32_e32 v198, v198
	v_rcp_f32_e32 v199, v199
	v_pk_mul_f32 v[188:189], v[188:189], v[196:197]
	v_pk_mul_f32 v[190:191], v[190:191], v[198:199]
	v_pk_mul_f32 v[188:189], v[188:189], v[192:193]
	v_pk_mul_f32 v[190:191], v[190:191], v[194:195]
	v_cvt_pk_bf16_f32 v116, v188, v189
	v_cvt_pk_bf16_f32 v117, v190, v191
	v_add_u32_e32 v213, 0x134000, v215
	global_store_dwordx4 v213, v[114:117], s[96:97]
	s_branch .LBB0_359

.LBB0_836:
	s_or_b64 exec, exec, s[0:1]
	s_and_b64 vcc, exec, s[6:7]
	s_mov_b64 s[8:9], s[38:39]
	s_mov_b64 s[10:11], s[40:41]
	s_mov_b32 s1, s34
	s_mov_b32 s0, s36
	s_cbranch_vccnz .LBB0_851

.LBB0_840:
	ds_read_b128 v[76:79], v171
	v_xor_b32_e32 v91, 64, v171
	ds_read_b128 v[80:83], v91
	ds_read_b128 v[84:87], v171 offset:2048
	ds_read_b128 v[88:91], v91 offset:2048
	s_add_u32 s10, s8, 0x100
	s_addc_u32 s11, s9, 0
	s_cmp_eq_u32 s67, 28
	s_cselect_b32 s43, s33, s11
	s_cselect_b32 s42, s37, s10
	s_cselect_b32 s13, s35, s66
	s_cselect_b32 s12, s64, s65
	v_lshl_add_u64 v[108:109], s[8:9], 0, v[180:181]
	s_add_i32 m0, s48, 0xc000
	ds_read_b128 v[92:95], v173
	v_xor_b32_e32 v203, 64, v173
	ds_read_b128 v[96:99], v203
	ds_read_b128 v[100:103], v173 offset:2048
	ds_read_b128 v[104:107], v203 offset:2048
	ds_read_b128 v[188:191], v173 offset:4096
	ds_read_b128 v[192:195], v203 offset:4096
	ds_read_b128 v[196:199], v173 offset:6144
	ds_read_b128 v[200:203], v203 offset:6144
	global_load_lds_dwordx4 v[108:109], off
	v_lshl_add_u64 v[108:109], s[8:9], 0, v[182:183]
	s_add_i32 m0, s48, 0xe000
	s_nop 0
	global_load_lds_dwordx4 v[108:109], off
	s_waitcnt lgkmcnt(8)
	s_barrier
	s_waitcnt lgkmcnt(0)
	s_setprio 1
	s_waitcnt lgkmcnt(0)
	v_mfma_f32_16x16x32_bf16 v[158:161], v[76:79], v[92:95], v[158:161]
	v_mfma_f32_16x16x32_bf16 v[158:161], v[80:83], v[96:99], v[158:161]
	v_mfma_f32_16x16x32_bf16 v[60:63], v[88:91], v[96:99], v[60:63]
	v_mfma_f32_16x16x32_bf16 v[60:63], v[84:87], v[92:95], v[60:63]
	v_mfma_f32_16x16x32_bf16 v[52:55], v[84:87], v[100:103], v[52:55]
	v_mfma_f32_16x16x32_bf16 v[52:55], v[88:91], v[104:107], v[52:55]
	v_mfma_f32_16x16x32_bf16 v[150:153], v[80:83], v[104:107], v[150:153]
	v_mfma_f32_16x16x32_bf16 v[150:153], v[76:79], v[100:103], v[150:153]
	v_mfma_f32_16x16x32_bf16 v[146:149], v[76:79], v[188:191], v[146:149]
	v_mfma_f32_16x16x32_bf16 v[146:149], v[80:83], v[192:195], v[146:149]
	v_mfma_f32_16x16x32_bf16 v[48:51], v[88:91], v[192:195], v[48:51]
	v_mfma_f32_16x16x32_bf16 v[48:51], v[84:87], v[188:191], v[48:51]
	v_mfma_f32_16x16x32_bf16 v[40:43], v[84:87], v[196:199], v[40:43]
	v_mfma_f32_16x16x32_bf16 v[40:43], v[88:91], v[200:203], v[40:43]
	v_mfma_f32_16x16x32_bf16 v[138:141], v[80:83], v[200:203], v[138:141]
	v_mfma_f32_16x16x32_bf16 v[138:141], v[76:79], v[196:199], v[138:141]
	s_setprio 0
	s_barrier
	s_add_i32 s8, s60, s46
	v_lshl_add_u64 v[220:221], s[12:13], 0, v[164:165]
	s_mov_b32 m0, s8
	ds_read_b128 v[204:207], v175
	v_xor_b32_e32 v219, 64, v175
	ds_read_b128 v[208:211], v219
	ds_read_b128 v[212:215], v175 offset:2048
	ds_read_b128 v[216:219], v219 offset:2048
	global_load_lds_dwordx4 v[220:221], off
	v_lshl_add_u64 v[238:239], s[12:13], 0, v[166:167]
	s_add_i32 m0, s8, 0x2000
	s_nop 0
	global_load_lds_dwordx4 v[238:239], off
	s_barrier
	s_waitcnt lgkmcnt(0)
	s_setprio 1
	s_waitcnt lgkmcnt(0)
	v_mfma_f32_16x16x32_bf16 v[154:157], v[204:207], v[92:95], v[154:157]
	v_mfma_f32_16x16x32_bf16 v[154:157], v[208:211], v[96:99], v[154:157]
	v_mfma_f32_16x16x32_bf16 v[56:59], v[216:219], v[96:99], v[56:59]
	v_mfma_f32_16x16x32_bf16 v[56:59], v[212:215], v[92:95], v[56:59]
	v_mfma_f32_16x16x32_bf16 v[44:47], v[212:215], v[100:103], v[44:47]
	v_mfma_f32_16x16x32_bf16 v[44:47], v[216:219], v[104:107], v[44:47]
	v_mfma_f32_16x16x32_bf16 v[36:39], v[216:219], v[192:195], v[36:39]
	v_mfma_f32_16x16x32_bf16 v[36:39], v[212:215], v[188:191], v[36:39]
	v_mfma_f32_16x16x32_bf16 v[32:35], v[212:215], v[196:199], v[32:35]
	v_mfma_f32_16x16x32_bf16 v[32:35], v[216:219], v[200:203], v[32:35]
	v_mfma_f32_16x16x32_bf16 v[92:95], v[204:207], v[100:103], v[142:145]
	v_mfma_f32_16x16x32_bf16 v[92:95], v[208:211], v[104:107], v[92:95]
	v_mfma_f32_16x16x32_bf16 v[96:99], v[208:211], v[192:195], v[134:137]
	v_mfma_f32_16x16x32_bf16 v[96:99], v[204:207], v[188:191], v[96:99]
	v_mfma_f32_16x16x32_bf16 v[100:103], v[204:207], v[196:199], v[130:133]
	v_mfma_f32_16x16x32_bf16 v[100:103], v[208:211], v[200:203], v[100:103]
	s_setprio 0
	s_mov_b32 m0, s48
	v_lshl_add_u64 v[240:241], s[42:43], 0, v[178:179]
	s_barrier
	ds_read_b128 v[104:107], v173 offset:16384
	v_xor_b32_e32 v203, 64, v173
	ds_read_b128 v[130:133], v203 offset:16384
	ds_read_b128 v[134:137], v173 offset:18432
	ds_read_b128 v[142:145], v203 offset:18432
	ds_read_b128 v[188:191], v173 offset:20480
	ds_read_b128 v[192:195], v203 offset:20480
	ds_read_b128 v[196:199], v173 offset:22528
	ds_read_b128 v[200:203], v203 offset:22528
	global_load_lds_dwordx4 v[240:241], off
	v_lshl_add_u64 v[242:243], s[42:43], 0, v[176:177]
	s_mov_b32 m0, s49
	s_nop 0
	global_load_lds_dwordx4 v[242:243], off
	s_barrier
	s_waitcnt lgkmcnt(0)
	s_setprio 1
	s_waitcnt lgkmcnt(0)
	v_mfma_f32_16x16x32_bf16 v[126:129], v[76:79], v[104:107], v[126:129]
	v_mfma_f32_16x16x32_bf16 v[126:129], v[80:83], v[130:133], v[126:129]
	v_mfma_f32_16x16x32_bf16 v[28:31], v[88:91], v[130:133], v[28:31]
	v_mfma_f32_16x16x32_bf16 v[28:31], v[84:87], v[104:107], v[28:31]
	v_mfma_f32_16x16x32_bf16 v[24:27], v[84:87], v[134:137], v[24:27]
	v_mfma_f32_16x16x32_bf16 v[24:27], v[88:91], v[142:145], v[24:27]
	v_mfma_f32_16x16x32_bf16 v[122:125], v[80:83], v[142:145], v[122:125]
	v_mfma_f32_16x16x32_bf16 v[122:125], v[76:79], v[134:137], v[122:125]
	v_mfma_f32_16x16x32_bf16 v[114:117], v[76:79], v[188:191], v[114:117]
	v_mfma_f32_16x16x32_bf16 v[114:117], v[80:83], v[192:195], v[114:117]
	v_mfma_f32_16x16x32_bf16 v[20:23], v[88:91], v[192:195], v[20:23]
	v_mfma_f32_16x16x32_bf16 v[20:23], v[84:87], v[188:191], v[20:23]
	v_mfma_f32_16x16x32_bf16 v[4:7], v[84:87], v[196:199], v[4:7]
	v_mfma_f32_16x16x32_bf16 v[4:7], v[88:91], v[200:203], v[4:7]
	v_mfma_f32_16x16x32_bf16 v[72:75], v[80:83], v[200:203], v[72:75]
	v_mfma_f32_16x16x32_bf16 v[72:75], v[76:79], v[196:199], v[72:75]
	s_setprio 0
	s_barrier
	s_add_u32 s8, s12, 0x1600000
	s_addc_u32 s9, s13, 0
	s_add_i32 s68, s61, s46
	v_lshl_add_u64 v[76:77], s[8:9], 0, v[164:165]
	s_mov_b32 m0, s68
	s_nop 0
	global_load_lds_dwordx4 v[76:77], off
	v_lshl_add_u64 v[76:77], s[8:9], 0, v[166:167]
	s_add_i32 m0, s68, 0x2000
	s_nop 0
	global_load_lds_dwordx4 v[76:77], off
	s_waitcnt vmcnt(6)
	s_barrier
	s_setprio 1
	v_mfma_f32_16x16x32_bf16 v[16:19], v[212:215], v[104:107], v[16:19]
	v_mfma_f32_16x16x32_bf16 v[16:19], v[216:219], v[130:133], v[16:19]
	v_mfma_f32_16x16x32_bf16 v[12:15], v[216:219], v[142:145], v[12:15]
	v_mfma_f32_16x16x32_bf16 v[12:15], v[212:215], v[134:137], v[12:15]
	v_mfma_f32_16x16x32_bf16 v[8:11], v[212:215], v[188:191], v[8:11]
	v_mfma_f32_16x16x32_bf16 v[8:11], v[216:219], v[192:195], v[8:11]
	v_mfma_f32_16x16x32_bf16 v[68:71], v[208:211], v[192:195], v[68:71]
	v_mfma_f32_16x16x32_bf16 v[68:71], v[204:207], v[188:191], v[68:71]
	v_mfma_f32_16x16x32_bf16 v[64:67], v[204:207], v[196:199], v[64:67]
	v_mfma_f32_16x16x32_bf16 v[64:67], v[208:211], v[200:203], v[64:67]
	v_mfma_f32_16x16x32_bf16 v[0:3], v[216:219], v[200:203], v[0:3]
	v_mfma_f32_16x16x32_bf16 v[0:3], v[212:215], v[196:199], v[0:3]
	v_mfma_f32_16x16x32_bf16 v[76:79], v[204:207], v[104:107], v[118:121]
	v_mfma_f32_16x16x32_bf16 v[76:79], v[208:211], v[130:133], v[76:79]
	v_mfma_f32_16x16x32_bf16 v[80:83], v[208:211], v[142:145], v[110:113]
	v_mfma_f32_16x16x32_bf16 v[80:83], v[204:207], v[134:137], v[80:83]
	s_setprio 0
	s_add_i32 s68, 0, 0x18000
	v_add_u32_e32 v108, s68, v169
	s_barrier
	ds_read_b128 v[84:87], v108
	v_xor_b32_e32 v111, 64, v108
	ds_read_b128 v[88:91], v111
	ds_read_b128 v[104:107], v108 offset:2048
	ds_read_b128 v[108:111], v111 offset:2048
	s_add_u32 s8, s42, 0x40000
	s_addc_u32 s9, s43, 0
	s_mov_b32 m0, s50
	v_lshl_add_u64 v[112:113], s[8:9], 0, v[178:179]
	ds_read_b128 v[118:121], v173 offset:32768
	v_xor_b32_e32 v207, 64, v173
	ds_read_b128 v[130:133], v207 offset:32768
	ds_read_b128 v[134:137], v173 offset:34816
	ds_read_b128 v[188:191], v207 offset:34816
	ds_read_b128 v[192:195], v173 offset:36864
	ds_read_b128 v[196:199], v207 offset:36864
	ds_read_b128 v[200:203], v173 offset:38912
	ds_read_b128 v[204:207], v207 offset:38912
	global_load_lds_dwordx4 v[112:113], off
	v_lshl_add_u64 v[112:113], s[8:9], 0, v[176:177]
	s_mov_b32 m0, s51
	s_nop 0
	global_load_lds_dwordx4 v[112:113], off
	s_waitcnt lgkmcnt(8)
	s_barrier
	s_waitcnt lgkmcnt(0)
	s_setprio 1
	s_waitcnt lgkmcnt(0)
	v_mfma_f32_16x16x32_bf16 v[142:145], v[84:87], v[118:121], v[158:161]
	v_mfma_f32_16x16x32_bf16 v[158:161], v[88:91], v[130:133], v[142:145]
	v_mfma_f32_16x16x32_bf16 v[60:63], v[108:111], v[130:133], v[60:63]
	v_mfma_f32_16x16x32_bf16 v[60:63], v[104:107], v[118:121], v[60:63]
	v_mfma_f32_16x16x32_bf16 v[52:55], v[104:107], v[134:137], v[52:55]
	v_mfma_f32_16x16x32_bf16 v[52:55], v[108:111], v[188:191], v[52:55]
	v_mfma_f32_16x16x32_bf16 v[48:51], v[108:111], v[196:199], v[48:51]
	v_mfma_f32_16x16x32_bf16 v[48:51], v[104:107], v[192:195], v[48:51]
	v_mfma_f32_16x16x32_bf16 v[40:43], v[104:107], v[200:203], v[40:43]
	v_mfma_f32_16x16x32_bf16 v[40:43], v[108:111], v[204:207], v[40:43]
	v_mfma_f32_16x16x32_bf16 v[138:141], v[88:91], v[204:207], v[138:141]
	v_mfma_f32_16x16x32_bf16 v[138:141], v[84:87], v[200:203], v[138:141]
	v_mfma_f32_16x16x32_bf16 v[142:145], v[84:87], v[134:137], v[150:153]
	v_mfma_f32_16x16x32_bf16 v[150:153], v[88:91], v[188:191], v[142:145]
	v_mfma_f32_16x16x32_bf16 v[142:145], v[84:87], v[192:195], v[146:149]
	v_mfma_f32_16x16x32_bf16 v[146:149], v[88:91], v[196:199], v[142:145]
	s_setprio 0
	s_barrier
	s_add_i32 s42, 0, 0x1c000
	v_add_u32_e32 v112, s42, v169
	s_add_i32 s8, s68, s46
	ds_read_b128 v[208:211], v112
	v_xor_b32_e32 v237, 64, v112
	ds_read_b128 v[212:215], v237
	ds_read_b128 v[216:219], v112 offset:2048
	ds_read_b128 v[234:237], v237 offset:2048
	v_lshl_add_u64 v[112:113], v[220:221], 0, s[18:19]
	s_mov_b32 m0, s8
	s_nop 0
	global_load_lds_dwordx4 v[112:113], off
	v_lshl_add_u64 v[112:113], v[238:239], 0, s[18:19]
	s_add_i32 m0, s8, 0x2000
	s_nop 0
	global_load_lds_dwordx4 v[112:113], off
	s_barrier
	s_waitcnt lgkmcnt(0)
	s_setprio 1
	s_waitcnt lgkmcnt(0)
	v_mfma_f32_16x16x32_bf16 v[142:145], v[208:211], v[118:121], v[154:157]
	v_mfma_f32_16x16x32_bf16 v[154:157], v[212:215], v[130:133], v[142:145]
	v_mfma_f32_16x16x32_bf16 v[56:59], v[234:237], v[130:133], v[56:59]
	v_mfma_f32_16x16x32_bf16 v[56:59], v[216:219], v[118:121], v[56:59]
	v_mfma_f32_16x16x32_bf16 v[44:47], v[216:219], v[134:137], v[44:47]
	v_mfma_f32_16x16x32_bf16 v[44:47], v[234:237], v[188:191], v[44:47]
	v_mfma_f32_16x16x32_bf16 v[36:39], v[234:237], v[196:199], v[36:39]
	v_mfma_f32_16x16x32_bf16 v[36:39], v[216:219], v[192:195], v[36:39]
	v_mfma_f32_16x16x32_bf16 v[32:35], v[216:219], v[200:203], v[32:35]
	v_mfma_f32_16x16x32_bf16 v[32:35], v[234:237], v[204:207], v[32:35]
	v_mfma_f32_16x16x32_bf16 v[92:95], v[208:211], v[134:137], v[92:95]
	v_mfma_f32_16x16x32_bf16 v[142:145], v[212:215], v[188:191], v[92:95]
	v_mfma_f32_16x16x32_bf16 v[92:95], v[208:211], v[192:195], v[96:99]
	v_mfma_f32_16x16x32_bf16 v[134:137], v[212:215], v[196:199], v[92:95]
	v_mfma_f32_16x16x32_bf16 v[92:95], v[208:211], v[200:203], v[100:103]
	v_mfma_f32_16x16x32_bf16 v[130:133], v[212:215], v[204:207], v[92:95]
	s_setprio 0
	s_mov_b32 m0, s54
	v_lshl_add_u64 v[112:113], v[240:241], 0, s[18:19]
	s_barrier
	ds_read_b128 v[92:95], v173 offset:49152
	v_xor_b32_e32 v207, 64, v173
	ds_read_b128 v[96:99], v207 offset:49152
	ds_read_b128 v[100:103], v173 offset:51200
	ds_read_b128 v[188:191], v207 offset:51200
	ds_read_b128 v[192:195], v173 offset:53248
	ds_read_b128 v[196:199], v207 offset:53248
	ds_read_b128 v[200:203], v173 offset:55296
	ds_read_b128 v[204:207], v207 offset:55296
	global_load_lds_dwordx4 v[112:113], off
	v_lshl_add_u64 v[112:113], v[242:243], 0, s[18:19]
	s_mov_b32 m0, s55
	s_nop 0
	global_load_lds_dwordx4 v[112:113], off
	s_barrier
	s_waitcnt lgkmcnt(0)
	s_setprio 1
	s_waitcnt lgkmcnt(0)
	v_mfma_f32_16x16x32_bf16 v[118:121], v[84:87], v[92:95], v[126:129]
	v_mfma_f32_16x16x32_bf16 v[126:129], v[88:91], v[96:99], v[118:121]
	v_mfma_f32_16x16x32_bf16 v[28:31], v[108:111], v[96:99], v[28:31]
	v_mfma_f32_16x16x32_bf16 v[28:31], v[104:107], v[92:95], v[28:31]
	v_mfma_f32_16x16x32_bf16 v[24:27], v[104:107], v[100:103], v[24:27]
	v_mfma_f32_16x16x32_bf16 v[24:27], v[108:111], v[188:191], v[24:27]
	v_mfma_f32_16x16x32_bf16 v[20:23], v[108:111], v[196:199], v[20:23]
	v_mfma_f32_16x16x32_bf16 v[20:23], v[104:107], v[192:195], v[20:23]
	v_mfma_f32_16x16x32_bf16 v[112:115], v[84:87], v[192:195], v[114:117]
	v_mfma_f32_16x16x32_bf16 v[114:117], v[88:91], v[196:199], v[112:115]
	v_mfma_f32_16x16x32_bf16 v[72:75], v[88:91], v[204:207], v[72:75]
	v_mfma_f32_16x16x32_bf16 v[72:75], v[84:87], v[200:203], v[72:75]
	v_mfma_f32_16x16x32_bf16 v[118:121], v[84:87], v[100:103], v[122:125]
	v_mfma_f32_16x16x32_bf16 v[122:125], v[88:91], v[188:191], v[118:121]
	v_mfma_f32_16x16x32_bf16 v[4:7], v[104:107], v[200:203], v[4:7]
	v_mfma_f32_16x16x32_bf16 v[4:7], v[108:111], v[204:207], v[4:7]
	s_setprio 0
	s_barrier
	s_add_u32 s8, s12, 0x1600080
	s_addc_u32 s9, s13, 0
	s_add_i32 s12, s42, s46
	v_lshl_add_u64 v[84:85], s[8:9], 0, v[164:165]
	s_mov_b32 m0, s12
	s_nop 0
	global_load_lds_dwordx4 v[84:85], off
	v_lshl_add_u64 v[84:85], s[8:9], 0, v[166:167]
	s_add_i32 m0, s12, 0x2000
	s_nop 0
	global_load_lds_dwordx4 v[84:85], off
	s_waitcnt vmcnt(6)
	s_barrier
	s_setprio 1
	v_mfma_f32_16x16x32_bf16 v[76:79], v[208:211], v[92:95], v[76:79]
	v_mfma_f32_16x16x32_bf16 v[118:121], v[212:215], v[96:99], v[76:79]
	v_mfma_f32_16x16x32_bf16 v[16:19], v[234:237], v[96:99], v[16:19]
	v_mfma_f32_16x16x32_bf16 v[16:19], v[216:219], v[92:95], v[16:19]
	v_mfma_f32_16x16x32_bf16 v[12:15], v[216:219], v[100:103], v[12:15]
	v_mfma_f32_16x16x32_bf16 v[12:15], v[234:237], v[188:191], v[12:15]
	v_mfma_f32_16x16x32_bf16 v[8:11], v[234:237], v[196:199], v[8:11]
	v_mfma_f32_16x16x32_bf16 v[8:11], v[216:219], v[192:195], v[8:11]
	v_mfma_f32_16x16x32_bf16 v[68:71], v[208:211], v[192:195], v[68:71]
	v_mfma_f32_16x16x32_bf16 v[68:71], v[212:215], v[196:199], v[68:71]
	v_mfma_f32_16x16x32_bf16 v[64:67], v[212:215], v[204:207], v[64:67]
	v_mfma_f32_16x16x32_bf16 v[64:67], v[208:211], v[200:203], v[64:67]
	v_mfma_f32_16x16x32_bf16 v[76:79], v[208:211], v[100:103], v[80:83]
	v_mfma_f32_16x16x32_bf16 v[110:113], v[212:215], v[188:191], v[76:79]
	v_mfma_f32_16x16x32_bf16 v[0:3], v[216:219], v[200:203], v[0:3]
	v_mfma_f32_16x16x32_bf16 v[0:3], v[234:237], v[204:207], v[0:3]
	s_setprio 0
	s_add_i32 s67, s67, 2
	s_add_u32 s65, s65, 0x100
	s_addc_u32 s66, s66, 0
	s_cmp_gt_u32 s67, 29
	s_mov_b64 s[8:9], s[10:11]
	s_barrier
	s_cbranch_scc0 .LBB0_840
	s_lshl_b32 s8, s0, 8
	s_add_i32 s8, s8, s58
	s_lshl_b32 s9, s1, 7
	s_add_i32 s9, s9, s53
	s_lshl_b32 s10, s0, 3
	s_lshr_b32 s11, s58, 5
	s_add_i32 s10, s10, s11
	v_add_u32_e32 v200, s8, v163
	v_lshlrev_b32_e32 v213, 2, v200
	global_load_dword v188, v213, s[4:5]
	global_load_dword v189, v213, s[4:5] offset:64
	global_load_dword v190, v213, s[4:5] offset:128
	global_load_dword v191, v213, s[4:5] offset:192
	global_load_dword v192, v213, s[4:5] offset:256
	global_load_dword v193, v213, s[4:5] offset:320
	global_load_dword v194, v213, s[4:5] offset:384
	global_load_dword v195, v213, s[4:5] offset:448
	v_lshl_add_u32 v201, v225, 3, s9
	v_lshlrev_b32_e32 v212, 2, v201
	v_add_u32_e32 v213, 0x21000, v212
	global_load_dwordx4 v[76:79], v213, s[82:83]
	v_add_u32_e32 v213, 0x2c000, v212
	global_load_dwordx4 v[80:83], v213, s[82:83]
	v_add_u32_e32 v213, 0x37000, v212
	global_load_dwordx4 v[84:87], v213, s[82:83]
	v_add_u32_e32 v213, 0xb000, v212
	global_load_dwordx4 v[88:91], v213, s[84:85]
	v_add_u32_e32 v213, 0x26800, v212
	global_load_dwordx4 v[92:95], v213, s[82:83]
	v_add_u32_e32 v213, 0x31800, v212
	global_load_dwordx4 v[96:99], v213, s[82:83]
	v_add_u32_e32 v213, 0x3c800, v212
	global_load_dwordx4 v[100:103], v213, s[82:83]
	v_add_u32_e32 v213, 0x10800, v212
	global_load_dwordx4 v[104:107], v213, s[84:85]
	v_mul_u32_u24_e32 v215, 0x2c00, v200
	v_lshl_add_u32 v215, v201, 1, v215
	v_add_u32_e32 v213, s10, v163
	v_mul_u32_u24_e32 v217, 0xb000, v213
	v_add_u32_e32 v217, v217, v212
	v_cmp_gt_u32_e64 s[8:9], 2, v163
	v_cmp_lt_u32_e64 s[10:11], 13, v163
	v_cmp_lt_u32_e32 vcc, 1, v163
	v_mov_b32_e32 v214, 1.0
	v_mov_b32_e32 v216, 0xbfb8aa3b
	v_mov_b32_e32 v108, 0x3727c5ac
	s_waitcnt vmcnt(8)
	v_fmamk_f32 v188, v188, 0x3a000000, v108
	v_fmamk_f32 v189, v189, 0x3a000000, v108
	v_fmamk_f32 v190, v190, 0x3a000000, v108
	v_fmamk_f32 v191, v191, 0x3a000000, v108
	v_fmamk_f32 v192, v192, 0x3a000000, v108
	v_fmamk_f32 v193, v193, 0x3a000000, v108
	v_fmamk_f32 v194, v194, 0x3a000000, v108
	v_fmamk_f32 v195, v195, 0x3a000000, v108
	v_rsq_f32_e32 v188, v188
	v_rsq_f32_e32 v189, v189
	v_rsq_f32_e32 v190, v190
	v_rsq_f32_e32 v191, v191
	v_rsq_f32_e32 v192, v192
	v_rsq_f32_e32 v193, v193
	v_rsq_f32_e32 v194, v194
	v_rsq_f32_e32 v195, v195
	v_pk_mul_f32 v[158:159], v[158:159], v[188:189] op_sel_hi:[1,0]
	v_pk_mul_f32 v[160:161], v[160:161], v[188:189] op_sel_hi:[1,0]
	v_pk_mul_f32 v[60:61], v[60:61], v[188:189] op_sel_hi:[1,0]
	v_pk_mul_f32 v[62:63], v[62:63], v[188:189] op_sel_hi:[1,0]
	v_pk_mul_f32 v[154:155], v[154:155], v[188:189] op_sel_hi:[1,0]
	v_pk_mul_f32 v[156:157], v[156:157], v[188:189] op_sel_hi:[1,0]
	v_pk_mul_f32 v[56:57], v[56:57], v[188:189] op_sel_hi:[1,0]
	v_pk_mul_f32 v[58:59], v[58:59], v[188:189] op_sel_hi:[1,0]
	v_pk_mul_f32 v[150:151], v[150:151], v[188:189] op_sel:[0,1] op_sel_hi:[1,1]
	v_pk_mul_f32 v[152:153], v[152:153], v[188:189] op_sel:[0,1] op_sel_hi:[1,1]
	v_pk_mul_f32 v[52:53], v[52:53], v[188:189] op_sel:[0,1] op_sel_hi:[1,1]
	v_pk_mul_f32 v[54:55], v[54:55], v[188:189] op_sel:[0,1] op_sel_hi:[1,1]
	v_pk_mul_f32 v[142:143], v[142:143], v[188:189] op_sel:[0,1] op_sel_hi:[1,1]
	v_pk_mul_f32 v[144:145], v[144:145], v[188:189] op_sel:[0,1] op_sel_hi:[1,1]
	v_pk_mul_f32 v[44:45], v[44:45], v[188:189] op_sel:[0,1] op_sel_hi:[1,1]
	v_pk_mul_f32 v[46:47], v[46:47], v[188:189] op_sel:[0,1] op_sel_hi:[1,1]
	v_pk_mul_f32 v[146:147], v[146:147], v[190:191] op_sel_hi:[1,0]
	v_pk_mul_f32 v[148:149], v[148:149], v[190:191] op_sel_hi:[1,0]
	v_pk_mul_f32 v[48:49], v[48:49], v[190:191] op_sel_hi:[1,0]
	v_pk_mul_f32 v[50:51], v[50:51], v[190:191] op_sel_hi:[1,0]
	v_pk_mul_f32 v[134:135], v[134:135], v[190:191] op_sel_hi:[1,0]
	v_pk_mul_f32 v[136:137], v[136:137], v[190:191] op_sel_hi:[1,0]
	v_pk_mul_f32 v[36:37], v[36:37], v[190:191] op_sel_hi:[1,0]
	v_pk_mul_f32 v[38:39], v[38:39], v[190:191] op_sel_hi:[1,0]
	v_pk_mul_f32 v[138:139], v[138:139], v[190:191] op_sel:[0,1] op_sel_hi:[1,1]
	v_pk_mul_f32 v[140:141], v[140:141], v[190:191] op_sel:[0,1] op_sel_hi:[1,1]
	v_pk_mul_f32 v[40:41], v[40:41], v[190:191] op_sel:[0,1] op_sel_hi:[1,1]
	v_pk_mul_f32 v[42:43], v[42:43], v[190:191] op_sel:[0,1] op_sel_hi:[1,1]
	v_pk_mul_f32 v[130:131], v[130:131], v[190:191] op_sel:[0,1] op_sel_hi:[1,1]
	v_pk_mul_f32 v[132:133], v[132:133], v[190:191] op_sel:[0,1] op_sel_hi:[1,1]
	v_pk_mul_f32 v[32:33], v[32:33], v[190:191] op_sel:[0,1] op_sel_hi:[1,1]
	v_pk_mul_f32 v[34:35], v[34:35], v[190:191] op_sel:[0,1] op_sel_hi:[1,1]
	v_pk_mul_f32 v[126:127], v[126:127], v[192:193] op_sel_hi:[1,0]
	v_pk_mul_f32 v[128:129], v[128:129], v[192:193] op_sel_hi:[1,0]
	v_pk_mul_f32 v[28:29], v[28:29], v[192:193] op_sel_hi:[1,0]
	v_pk_mul_f32 v[30:31], v[30:31], v[192:193] op_sel_hi:[1,0]
	v_pk_mul_f32 v[118:119], v[118:119], v[192:193] op_sel_hi:[1,0]
	v_pk_mul_f32 v[120:121], v[120:121], v[192:193] op_sel_hi:[1,0]
	v_pk_mul_f32 v[16:17], v[16:17], v[192:193] op_sel_hi:[1,0]
	v_pk_mul_f32 v[18:19], v[18:19], v[192:193] op_sel_hi:[1,0]
	v_pk_mul_f32 v[122:123], v[122:123], v[192:193] op_sel:[0,1] op_sel_hi:[1,1]
	v_pk_mul_f32 v[124:125], v[124:125], v[192:193] op_sel:[0,1] op_sel_hi:[1,1]
	v_pk_mul_f32 v[24:25], v[24:25], v[192:193] op_sel:[0,1] op_sel_hi:[1,1]
	v_pk_mul_f32 v[26:27], v[26:27], v[192:193] op_sel:[0,1] op_sel_hi:[1,1]
	v_pk_mul_f32 v[110:111], v[110:111], v[192:193] op_sel:[0,1] op_sel_hi:[1,1]
	v_pk_mul_f32 v[112:113], v[112:113], v[192:193] op_sel:[0,1] op_sel_hi:[1,1]
	v_pk_mul_f32 v[12:13], v[12:13], v[192:193] op_sel:[0,1] op_sel_hi:[1,1]
	v_pk_mul_f32 v[14:15], v[14:15], v[192:193] op_sel:[0,1] op_sel_hi:[1,1]
	v_pk_mul_f32 v[114:115], v[114:115], v[194:195] op_sel_hi:[1,0]
	v_pk_mul_f32 v[116:117], v[116:117], v[194:195] op_sel_hi:[1,0]
	v_pk_mul_f32 v[20:21], v[20:21], v[194:195] op_sel_hi:[1,0]
	v_pk_mul_f32 v[22:23], v[22:23], v[194:195] op_sel_hi:[1,0]
	v_pk_mul_f32 v[68:69], v[68:69], v[194:195] op_sel_hi:[1,0]
	v_pk_mul_f32 v[70:71], v[70:71], v[194:195] op_sel_hi:[1,0]
	v_pk_mul_f32 v[8:9], v[8:9], v[194:195] op_sel_hi:[1,0]
	v_pk_mul_f32 v[10:11], v[10:11], v[194:195] op_sel_hi:[1,0]
	v_pk_mul_f32 v[72:73], v[72:73], v[194:195] op_sel:[0,1] op_sel_hi:[1,1]
	v_pk_mul_f32 v[74:75], v[74:75], v[194:195] op_sel:[0,1] op_sel_hi:[1,1]
	v_pk_mul_f32 v[4:5], v[4:5], v[194:195] op_sel:[0,1] op_sel_hi:[1,1]
	v_pk_mul_f32 v[6:7], v[6:7], v[194:195] op_sel:[0,1] op_sel_hi:[1,1]
	v_pk_mul_f32 v[64:65], v[64:65], v[194:195] op_sel:[0,1] op_sel_hi:[1,1]
	v_pk_mul_f32 v[66:67], v[66:67], v[194:195] op_sel:[0,1] op_sel_hi:[1,1]
	v_pk_mul_f32 v[0:1], v[0:1], v[194:195] op_sel:[0,1] op_sel_hi:[1,1]
	v_pk_mul_f32 v[2:3], v[2:3], v[194:195] op_sel:[0,1] op_sel_hi:[1,1]
	s_nop 1
	s_mov_b64 exec, s[8:9]
	v_add_u32_e32 v213, 0x5800, v217
	global_store_dwordx4 v217, v[158:161], s[70:71]
	global_store_dwordx4 v213, v[154:157], s[70:71]
	global_store_dwordx4 v217, v[60:63], s[70:71] offset:16
	global_store_dwordx4 v213, v[56:59], s[70:71] offset:16
	s_mov_b64 exec, s[10:11]
	v_add_u32_e32 v213, 0xfff7c000, v217
	global_store_dwordx4 v213, v[72:75], s[70:71]
	global_store_dwordx4 v213, v[4:7], s[70:71] offset:16
	v_add_u32_e32 v213, 0xfff81800, v217
	global_store_dwordx4 v213, v[64:67], s[70:71]
	global_store_dwordx4 v213, v[0:3], s[70:71] offset:16
	s_mov_b64 exec, -1
	v_add_u32_e32 v213, 0x3c800, v212
	global_load_dwordx4 v[204:207], v213, s[82:83] offset:16
	v_add_u32_e32 v213, 0x10800, v212
	global_load_dwordx4 v[208:211], v213, s[84:85] offset:16
	s_waitcnt vmcnt(10)
	v_pk_fma_f32 v[188:189], v[158:159], v[84:85], v[88:89]
	v_pk_fma_f32 v[190:191], v[160:161], v[86:87], v[90:91]
	v_pk_fma_f32 v[192:193], v[154:155], v[100:101], v[104:105]
	v_pk_fma_f32 v[194:195], v[156:157], v[102:103], v[106:107]
	v_fmac_f32_dpp v188, v158, v80 row_shr:1 row_mask:0xf bank_mask:0xf
	v_fmac_f32_dpp v189, v159, v81 row_shr:1 row_mask:0xf bank_mask:0xf
	v_fmac_f32_dpp v190, v160, v82 row_shr:1 row_mask:0xf bank_mask:0xf
	v_fmac_f32_dpp v191, v161, v83 row_shr:1 row_mask:0xf bank_mask:0xf
	v_fmac_f32_dpp v192, v154, v96 row_shr:1 row_mask:0xf bank_mask:0xf
	v_fmac_f32_dpp v193, v155, v97 row_shr:1 row_mask:0xf bank_mask:0xf
	v_fmac_f32_dpp v194, v156, v98 row_shr:1 row_mask:0xf bank_mask:0xf
	v_fmac_f32_dpp v195, v157, v99 row_shr:1 row_mask:0xf bank_mask:0xf
	v_fmac_f32_dpp v188, v158, v76 row_shr:2 row_mask:0xf bank_mask:0xf
	v_fmac_f32_dpp v189, v159, v77 row_shr:2 row_mask:0xf bank_mask:0xf
	v_fmac_f32_dpp v190, v160, v78 row_shr:2 row_mask:0xf bank_mask:0xf
	v_fmac_f32_dpp v191, v161, v79 row_shr:2 row_mask:0xf bank_mask:0xf
	v_fmac_f32_dpp v192, v154, v92 row_shr:2 row_mask:0xf bank_mask:0xf
	v_fmac_f32_dpp v193, v155, v93 row_shr:2 row_mask:0xf bank_mask:0xf
	v_fmac_f32_dpp v194, v156, v94 row_shr:2 row_mask:0xf bank_mask:0xf
	v_fmac_f32_dpp v195, v157, v95 row_shr:2 row_mask:0xf bank_mask:0xf
	v_pk_mul_f32 v[196:197], v[188:189], v[216:217] op_sel_hi:[1,0]
	v_pk_mul_f32 v[198:199], v[190:191], v[216:217] op_sel_hi:[1,0]
	v_exp_f32_e32 v196, v196
	v_exp_f32_e32 v197, v197
	v_exp_f32_e32 v198, v198
	v_exp_f32_e32 v199, v199
	v_pk_add_f32 v[196:197], v[196:197], v[214:215] op_sel_hi:[1,0]
	v_pk_add_f32 v[198:199], v[198:199], v[214:215] op_sel_hi:[1,0]
	v_rcp_f32_e32 v196, v196
	v_rcp_f32_e32 v197, v197
	v_rcp_f32_e32 v198, v198
	v_rcp_f32_e32 v199, v199
	v_pk_mul_f32 v[188:189], v[188:189], v[196:197]
	v_pk_mul_f32 v[190:191], v[190:191], v[198:199]
	v_pk_mul_f32 v[188:189], v[188:189], v[192:193]
	v_pk_mul_f32 v[190:191], v[190:191], v[194:195]
	v_cvt_pk_bf16_f32 v200, v188, v189
	v_cvt_pk_bf16_f32 v201, v190, v191
	v_pk_fma_f32 v[188:189], v[150:151], v[84:85], v[88:89]
	v_pk_fma_f32 v[190:191], v[152:153], v[86:87], v[90:91]
	v_pk_fma_f32 v[192:193], v[142:143], v[100:101], v[104:105]
	v_pk_fma_f32 v[194:195], v[144:145], v[102:103], v[106:107]
	v_fmac_f32_dpp v188, v150, v80 row_shr:1 row_mask:0xf bank_mask:0xf
	v_fmac_f32_dpp v189, v151, v81 row_shr:1 row_mask:0xf bank_mask:0xf
	v_fmac_f32_dpp v190, v152, v82 row_shr:1 row_mask:0xf bank_mask:0xf
	v_fmac_f32_dpp v191, v153, v83 row_shr:1 row_mask:0xf bank_mask:0xf
	v_fmac_f32_dpp v192, v142, v96 row_shr:1 row_mask:0xf bank_mask:0xf
	v_fmac_f32_dpp v193, v143, v97 row_shr:1 row_mask:0xf bank_mask:0xf
	v_fmac_f32_dpp v194, v144, v98 row_shr:1 row_mask:0xf bank_mask:0xf
	v_fmac_f32_dpp v195, v145, v99 row_shr:1 row_mask:0xf bank_mask:0xf
	v_fmac_f32_dpp v188, v150, v76 row_shr:2 row_mask:0xf bank_mask:0xf
	v_fmac_f32_dpp v189, v151, v77 row_shr:2 row_mask:0xf bank_mask:0xf
	v_fmac_f32_dpp v190, v152, v78 row_shr:2 row_mask:0xf bank_mask:0xf
	v_fmac_f32_dpp v191, v153, v79 row_shr:2 row_mask:0xf bank_mask:0xf
	v_fmac_f32_dpp v192, v142, v92 row_shr:2 row_mask:0xf bank_mask:0xf
	v_fmac_f32_dpp v193, v143, v93 row_shr:2 row_mask:0xf bank_mask:0xf
	v_fmac_f32_dpp v194, v144, v94 row_shr:2 row_mask:0xf bank_mask:0xf
	v_fmac_f32_dpp v195, v145, v95 row_shr:2 row_mask:0xf bank_mask:0xf
	v_fmac_f32_dpp v188, v158, v80 row_shl:15 row_mask:0xf bank_mask:0xf
	v_fmac_f32_dpp v189, v159, v81 row_shl:15 row_mask:0xf bank_mask:0xf
	v_fmac_f32_dpp v190, v160, v82 row_shl:15 row_mask:0xf bank_mask:0xf
	v_fmac_f32_dpp v191, v161, v83 row_shl:15 row_mask:0xf bank_mask:0xf
	v_fmac_f32_dpp v192, v154, v96 row_shl:15 row_mask:0xf bank_mask:0xf
	v_fmac_f32_dpp v193, v155, v97 row_shl:15 row_mask:0xf bank_mask:0xf
	v_fmac_f32_dpp v194, v156, v98 row_shl:15 row_mask:0xf bank_mask:0xf
	v_fmac_f32_dpp v195, v157, v99 row_shl:15 row_mask:0xf bank_mask:0xf
	v_fmac_f32_dpp v188, v158, v76 row_shl:14 row_mask:0xf bank_mask:0xf
	v_fmac_f32_dpp v189, v159, v77 row_shl:14 row_mask:0xf bank_mask:0xf
	v_fmac_f32_dpp v190, v160, v78 row_shl:14 row_mask:0xf bank_mask:0xf
	v_fmac_f32_dpp v191, v161, v79 row_shl:14 row_mask:0xf bank_mask:0xf
	v_fmac_f32_dpp v192, v154, v92 row_shl:14 row_mask:0xf bank_mask:0xf
	v_fmac_f32_dpp v193, v155, v93 row_shl:14 row_mask:0xf bank_mask:0xf
	v_fmac_f32_dpp v194, v156, v94 row_shl:14 row_mask:0xf bank_mask:0xf
	v_fmac_f32_dpp v195, v157, v95 row_shl:14 row_mask:0xf bank_mask:0xf
	v_pk_mul_f32 v[196:197], v[188:189], v[216:217] op_sel_hi:[1,0]
	v_pk_mul_f32 v[198:199], v[190:191], v[216:217] op_sel_hi:[1,0]
	v_exp_f32_e32 v196, v196
	v_exp_f32_e32 v197, v197
	v_exp_f32_e32 v198, v198
	v_exp_f32_e32 v199, v199
	v_pk_add_f32 v[196:197], v[196:197], v[214:215] op_sel_hi:[1,0]
	v_pk_add_f32 v[198:199], v[198:199], v[214:215] op_sel_hi:[1,0]
	v_rcp_f32_e32 v196, v196
	v_rcp_f32_e32 v197, v197
	v_rcp_f32_e32 v198, v198
	v_rcp_f32_e32 v199, v199
	v_pk_mul_f32 v[188:189], v[188:189], v[196:197]
	v_pk_mul_f32 v[190:191], v[190:191], v[198:199]
	v_pk_mul_f32 v[188:189], v[188:189], v[192:193]
	v_pk_mul_f32 v[190:191], v[190:191], v[194:195]
	v_cvt_pk_bf16_f32 v158, v188, v189
	v_cvt_pk_bf16_f32 v159, v190, v191
	v_add_u32_e32 v213, 0x21000, v212
	global_load_dwordx4 v[154:157], v213, s[82:83] offset:16
	v_pk_fma_f32 v[188:189], v[146:147], v[84:85], v[88:89]
	v_pk_fma_f32 v[190:191], v[148:149], v[86:87], v[90:91]
	v_pk_fma_f32 v[192:193], v[134:135], v[100:101], v[104:105]
	v_pk_fma_f32 v[194:195], v[136:137], v[102:103], v[106:107]
	v_fmac_f32_dpp v188, v146, v80 row_shr:1 row_mask:0xf bank_mask:0xf
	v_fmac_f32_dpp v189, v147, v81 row_shr:1 row_mask:0xf bank_mask:0xf
	v_fmac_f32_dpp v190, v148, v82 row_shr:1 row_mask:0xf bank_mask:0xf
	v_fmac_f32_dpp v191, v149, v83 row_shr:1 row_mask:0xf bank_mask:0xf
	v_fmac_f32_dpp v192, v134, v96 row_shr:1 row_mask:0xf bank_mask:0xf
	v_fmac_f32_dpp v193, v135, v97 row_shr:1 row_mask:0xf bank_mask:0xf
	v_fmac_f32_dpp v194, v136, v98 row_shr:1 row_mask:0xf bank_mask:0xf
	v_fmac_f32_dpp v195, v137, v99 row_shr:1 row_mask:0xf bank_mask:0xf
	v_fmac_f32_dpp v188, v146, v76 row_shr:2 row_mask:0xf bank_mask:0xf
	v_fmac_f32_dpp v189, v147, v77 row_shr:2 row_mask:0xf bank_mask:0xf
	v_fmac_f32_dpp v190, v148, v78 row_shr:2 row_mask:0xf bank_mask:0xf
	v_fmac_f32_dpp v191, v149, v79 row_shr:2 row_mask:0xf bank_mask:0xf
	v_fmac_f32_dpp v192, v134, v92 row_shr:2 row_mask:0xf bank_mask:0xf
	v_fmac_f32_dpp v193, v135, v93 row_shr:2 row_mask:0xf bank_mask:0xf
	v_fmac_f32_dpp v194, v136, v94 row_shr:2 row_mask:0xf bank_mask:0xf
	v_fmac_f32_dpp v195, v137, v95 row_shr:2 row_mask:0xf bank_mask:0xf
	v_fmac_f32_dpp v188, v150, v80 row_shl:15 row_mask:0xf bank_mask:0xf
	v_fmac_f32_dpp v189, v151, v81 row_shl:15 row_mask:0xf bank_mask:0xf
	v_fmac_f32_dpp v190, v152, v82 row_shl:15 row_mask:0xf bank_mask:0xf
	v_fmac_f32_dpp v191, v153, v83 row_shl:15 row_mask:0xf bank_mask:0xf
	v_fmac_f32_dpp v192, v142, v96 row_shl:15 row_mask:0xf bank_mask:0xf
	v_fmac_f32_dpp v193, v143, v97 row_shl:15 row_mask:0xf bank_mask:0xf
	v_fmac_f32_dpp v194, v144, v98 row_shl:15 row_mask:0xf bank_mask:0xf
	v_fmac_f32_dpp v195, v145, v99 row_shl:15 row_mask:0xf bank_mask:0xf
	v_fmac_f32_dpp v188, v150, v76 row_shl:14 row_mask:0xf bank_mask:0xf
	v_fmac_f32_dpp v189, v151, v77 row_shl:14 row_mask:0xf bank_mask:0xf
	v_fmac_f32_dpp v190, v152, v78 row_shl:14 row_mask:0xf bank_mask:0xf
	v_fmac_f32_dpp v191, v153, v79 row_shl:14 row_mask:0xf bank_mask:0xf
	v_fmac_f32_dpp v192, v142, v92 row_shl:14 row_mask:0xf bank_mask:0xf
	v_fmac_f32_dpp v193, v143, v93 row_shl:14 row_mask:0xf bank_mask:0xf
	v_fmac_f32_dpp v194, v144, v94 row_shl:14 row_mask:0xf bank_mask:0xf
	v_fmac_f32_dpp v195, v145, v95 row_shl:14 row_mask:0xf bank_mask:0xf
	v_pk_mul_f32 v[196:197], v[188:189], v[216:217] op_sel_hi:[1,0]
	v_pk_mul_f32 v[198:199], v[190:191], v[216:217] op_sel_hi:[1,0]
	v_exp_f32_e32 v196, v196
	v_exp_f32_e32 v197, v197
	v_exp_f32_e32 v198, v198
	v_exp_f32_e32 v199, v199
	v_pk_add_f32 v[196:197], v[196:197], v[214:215] op_sel_hi:[1,0]
	v_pk_add_f32 v[198:199], v[198:199], v[214:215] op_sel_hi:[1,0]
	v_rcp_f32_e32 v196, v196
	v_rcp_f32_e32 v197, v197
	v_rcp_f32_e32 v198, v198
	v_rcp_f32_e32 v199, v199
	v_pk_mul_f32 v[188:189], v[188:189], v[196:197]
	v_pk_mul_f32 v[190:191], v[190:191], v[198:199]
	v_pk_mul_f32 v[188:189], v[188:189], v[192:193]
	v_pk_mul_f32 v[190:191], v[190:191], v[194:195]
	v_cvt_pk_bf16_f32 v150, v188, v189
	v_cvt_pk_bf16_f32 v151, v190, v191
	v_add_u32_e32 v213, 0x2c000, v212
	global_load_dwordx4 v[142:145], v213, s[82:83] offset:16
	v_pk_fma_f32 v[188:189], v[138:139], v[84:85], v[88:89]
	v_pk_fma_f32 v[190:191], v[140:141], v[86:87], v[90:91]
	v_pk_fma_f32 v[192:193], v[130:131], v[100:101], v[104:105]
	v_pk_fma_f32 v[194:195], v[132:133], v[102:103], v[106:107]
	v_fmac_f32_dpp v188, v138, v80 row_shr:1 row_mask:0xf bank_mask:0xf
	v_fmac_f32_dpp v189, v139, v81 row_shr:1 row_mask:0xf bank_mask:0xf
	v_fmac_f32_dpp v190, v140, v82 row_shr:1 row_mask:0xf bank_mask:0xf
	v_fmac_f32_dpp v191, v141, v83 row_shr:1 row_mask:0xf bank_mask:0xf
	v_fmac_f32_dpp v192, v130, v96 row_shr:1 row_mask:0xf bank_mask:0xf
	v_fmac_f32_dpp v193, v131, v97 row_shr:1 row_mask:0xf bank_mask:0xf
	v_fmac_f32_dpp v194, v132, v98 row_shr:1 row_mask:0xf bank_mask:0xf
	v_fmac_f32_dpp v195, v133, v99 row_shr:1 row_mask:0xf bank_mask:0xf
	v_fmac_f32_dpp v188, v138, v76 row_shr:2 row_mask:0xf bank_mask:0xf
	v_fmac_f32_dpp v189, v139, v77 row_shr:2 row_mask:0xf bank_mask:0xf
	v_fmac_f32_dpp v190, v140, v78 row_shr:2 row_mask:0xf bank_mask:0xf
	v_fmac_f32_dpp v191, v141, v79 row_shr:2 row_mask:0xf bank_mask:0xf
	v_fmac_f32_dpp v192, v130, v92 row_shr:2 row_mask:0xf bank_mask:0xf
	v_fmac_f32_dpp v193, v131, v93 row_shr:2 row_mask:0xf bank_mask:0xf
	v_fmac_f32_dpp v194, v132, v94 row_shr:2 row_mask:0xf bank_mask:0xf
	v_fmac_f32_dpp v195, v133, v95 row_shr:2 row_mask:0xf bank_mask:0xf
	v_fmac_f32_dpp v188, v146, v80 row_shl:15 row_mask:0xf bank_mask:0xf
	v_fmac_f32_dpp v189, v147, v81 row_shl:15 row_mask:0xf bank_mask:0xf
	v_fmac_f32_dpp v190, v148, v82 row_shl:15 row_mask:0xf bank_mask:0xf
	v_fmac_f32_dpp v191, v149, v83 row_shl:15 row_mask:0xf bank_mask:0xf
	v_fmac_f32_dpp v192, v134, v96 row_shl:15 row_mask:0xf bank_mask:0xf
	v_fmac_f32_dpp v193, v135, v97 row_shl:15 row_mask:0xf bank_mask:0xf
	v_fmac_f32_dpp v194, v136, v98 row_shl:15 row_mask:0xf bank_mask:0xf
	v_fmac_f32_dpp v195, v137, v99 row_shl:15 row_mask:0xf bank_mask:0xf
	v_fmac_f32_dpp v188, v146, v76 row_shl:14 row_mask:0xf bank_mask:0xf
	v_fmac_f32_dpp v189, v147, v77 row_shl:14 row_mask:0xf bank_mask:0xf
	v_fmac_f32_dpp v190, v148, v78 row_shl:14 row_mask:0xf bank_mask:0xf
	v_fmac_f32_dpp v191, v149, v79 row_shl:14 row_mask:0xf bank_mask:0xf
	v_fmac_f32_dpp v192, v134, v92 row_shl:14 row_mask:0xf bank_mask:0xf
	v_fmac_f32_dpp v193, v135, v93 row_shl:14 row_mask:0xf bank_mask:0xf
	v_fmac_f32_dpp v194, v136, v94 row_shl:14 row_mask:0xf bank_mask:0xf
	v_fmac_f32_dpp v195, v137, v95 row_shl:14 row_mask:0xf bank_mask:0xf
	v_pk_mul_f32 v[196:197], v[188:189], v[216:217] op_sel_hi:[1,0]
	v_pk_mul_f32 v[198:199], v[190:191], v[216:217] op_sel_hi:[1,0]
	v_exp_f32_e32 v196, v196
	v_exp_f32_e32 v197, v197
	v_exp_f32_e32 v198, v198
	v_exp_f32_e32 v199, v199
	v_pk_add_f32 v[196:197], v[196:197], v[214:215] op_sel_hi:[1,0]
	v_pk_add_f32 v[198:199], v[198:199], v[214:215] op_sel_hi:[1,0]
	v_rcp_f32_e32 v196, v196
	v_rcp_f32_e32 v197, v197
	v_rcp_f32_e32 v198, v198
	v_rcp_f32_e32 v199, v199
	v_pk_mul_f32 v[188:189], v[188:189], v[196:197]
	v_pk_mul_f32 v[190:191], v[190:191], v[198:199]
	v_pk_mul_f32 v[188:189], v[188:189], v[192:193]
	v_pk_mul_f32 v[190:191], v[190:191], v[194:195]
	v_cvt_pk_bf16_f32 v146, v188, v189
	v_cvt_pk_bf16_f32 v147, v190, v191
	v_add_u32_e32 v213, 0x37000, v212
	global_load_dwordx4 v[134:137], v213, s[82:83] offset:16
	v_pk_fma_f32 v[188:189], v[126:127], v[84:85], v[88:89]
	v_pk_fma_f32 v[190:191], v[128:129], v[86:87], v[90:91]
	v_pk_fma_f32 v[192:193], v[118:119], v[100:101], v[104:105]
	v_pk_fma_f32 v[194:195], v[120:121], v[102:103], v[106:107]
	v_fmac_f32_dpp v188, v126, v80 row_shr:1 row_mask:0xf bank_mask:0xf
	v_fmac_f32_dpp v189, v127, v81 row_shr:1 row_mask:0xf bank_mask:0xf
	v_fmac_f32_dpp v190, v128, v82 row_shr:1 row_mask:0xf bank_mask:0xf
	v_fmac_f32_dpp v191, v129, v83 row_shr:1 row_mask:0xf bank_mask:0xf
	v_fmac_f32_dpp v192, v118, v96 row_shr:1 row_mask:0xf bank_mask:0xf
	v_fmac_f32_dpp v193, v119, v97 row_shr:1 row_mask:0xf bank_mask:0xf
	v_fmac_f32_dpp v194, v120, v98 row_shr:1 row_mask:0xf bank_mask:0xf
	v_fmac_f32_dpp v195, v121, v99 row_shr:1 row_mask:0xf bank_mask:0xf
	v_fmac_f32_dpp v188, v126, v76 row_shr:2 row_mask:0xf bank_mask:0xf
	v_fmac_f32_dpp v189, v127, v77 row_shr:2 row_mask:0xf bank_mask:0xf
	v_fmac_f32_dpp v190, v128, v78 row_shr:2 row_mask:0xf bank_mask:0xf
	v_fmac_f32_dpp v191, v129, v79 row_shr:2 row_mask:0xf bank_mask:0xf
	v_fmac_f32_dpp v192, v118, v92 row_shr:2 row_mask:0xf bank_mask:0xf
	v_fmac_f32_dpp v193, v119, v93 row_shr:2 row_mask:0xf bank_mask:0xf
	v_fmac_f32_dpp v194, v120, v94 row_shr:2 row_mask:0xf bank_mask:0xf
	v_fmac_f32_dpp v195, v121, v95 row_shr:2 row_mask:0xf bank_mask:0xf
	v_fmac_f32_dpp v188, v138, v80 row_shl:15 row_mask:0xf bank_mask:0xf
	v_fmac_f32_dpp v189, v139, v81 row_shl:15 row_mask:0xf bank_mask:0xf
	v_fmac_f32_dpp v190, v140, v82 row_shl:15 row_mask:0xf bank_mask:0xf
	v_fmac_f32_dpp v191, v141, v83 row_shl:15 row_mask:0xf bank_mask:0xf
	v_fmac_f32_dpp v192, v130, v96 row_shl:15 row_mask:0xf bank_mask:0xf
	v_fmac_f32_dpp v193, v131, v97 row_shl:15 row_mask:0xf bank_mask:0xf
	v_fmac_f32_dpp v194, v132, v98 row_shl:15 row_mask:0xf bank_mask:0xf
	v_fmac_f32_dpp v195, v133, v99 row_shl:15 row_mask:0xf bank_mask:0xf
	v_fmac_f32_dpp v188, v138, v76 row_shl:14 row_mask:0xf bank_mask:0xf
	v_fmac_f32_dpp v189, v139, v77 row_shl:14 row_mask:0xf bank_mask:0xf
	v_fmac_f32_dpp v190, v140, v78 row_shl:14 row_mask:0xf bank_mask:0xf
	v_fmac_f32_dpp v191, v141, v79 row_shl:14 row_mask:0xf bank_mask:0xf
	v_fmac_f32_dpp v192, v130, v92 row_shl:14 row_mask:0xf bank_mask:0xf
	v_fmac_f32_dpp v193, v131, v93 row_shl:14 row_mask:0xf bank_mask:0xf
	v_fmac_f32_dpp v194, v132, v94 row_shl:14 row_mask:0xf bank_mask:0xf
	v_fmac_f32_dpp v195, v133, v95 row_shl:14 row_mask:0xf bank_mask:0xf
	v_pk_mul_f32 v[196:197], v[188:189], v[216:217] op_sel_hi:[1,0]
	v_pk_mul_f32 v[198:199], v[190:191], v[216:217] op_sel_hi:[1,0]
	v_exp_f32_e32 v196, v196
	v_exp_f32_e32 v197, v197
	v_exp_f32_e32 v198, v198
	v_exp_f32_e32 v199, v199
	v_pk_add_f32 v[196:197], v[196:197], v[214:215] op_sel_hi:[1,0]
	v_pk_add_f32 v[198:199], v[198:199], v[214:215] op_sel_hi:[1,0]
	v_rcp_f32_e32 v196, v196
	v_rcp_f32_e32 v197, v197
	v_rcp_f32_e32 v198, v198
	v_rcp_f32_e32 v199, v199
	v_pk_mul_f32 v[188:189], v[188:189], v[196:197]
	v_pk_mul_f32 v[190:191], v[190:191], v[198:199]
	v_pk_mul_f32 v[188:189], v[188:189], v[192:193]
	v_pk_mul_f32 v[190:191], v[190:191], v[194:195]
	v_cvt_pk_bf16_f32 v138, v188, v189
	v_cvt_pk_bf16_f32 v139, v190, v191
	v_add_u32_e32 v213, 0xb000, v212
	global_load_dwordx4 v[130:133], v213, s[84:85] offset:16
	v_pk_fma_f32 v[188:189], v[122:123], v[84:85], v[88:89]
	v_pk_fma_f32 v[190:191], v[124:125], v[86:87], v[90:91]
	v_pk_fma_f32 v[192:193], v[110:111], v[100:101], v[104:105]
	v_pk_fma_f32 v[194:195], v[112:113], v[102:103], v[106:107]
	v_fmac_f32_dpp v188, v122, v80 row_shr:1 row_mask:0xf bank_mask:0xf
	v_fmac_f32_dpp v189, v123, v81 row_shr:1 row_mask:0xf bank_mask:0xf
	v_fmac_f32_dpp v190, v124, v82 row_shr:1 row_mask:0xf bank_mask:0xf
	v_fmac_f32_dpp v191, v125, v83 row_shr:1 row_mask:0xf bank_mask:0xf
	v_fmac_f32_dpp v192, v110, v96 row_shr:1 row_mask:0xf bank_mask:0xf
	v_fmac_f32_dpp v193, v111, v97 row_shr:1 row_mask:0xf bank_mask:0xf
	v_fmac_f32_dpp v194, v112, v98 row_shr:1 row_mask:0xf bank_mask:0xf
	v_fmac_f32_dpp v195, v113, v99 row_shr:1 row_mask:0xf bank_mask:0xf
	v_fmac_f32_dpp v188, v122, v76 row_shr:2 row_mask:0xf bank_mask:0xf
	v_fmac_f32_dpp v189, v123, v77 row_shr:2 row_mask:0xf bank_mask:0xf
	v_fmac_f32_dpp v190, v124, v78 row_shr:2 row_mask:0xf bank_mask:0xf
	v_fmac_f32_dpp v191, v125, v79 row_shr:2 row_mask:0xf bank_mask:0xf
	v_fmac_f32_dpp v192, v110, v92 row_shr:2 row_mask:0xf bank_mask:0xf
	v_fmac_f32_dpp v193, v111, v93 row_shr:2 row_mask:0xf bank_mask:0xf
	v_fmac_f32_dpp v194, v112, v94 row_shr:2 row_mask:0xf bank_mask:0xf
	v_fmac_f32_dpp v195, v113, v95 row_shr:2 row_mask:0xf bank_mask:0xf
	v_fmac_f32_dpp v188, v126, v80 row_shl:15 row_mask:0xf bank_mask:0xf
	v_fmac_f32_dpp v189, v127, v81 row_shl:15 row_mask:0xf bank_mask:0xf
	v_fmac_f32_dpp v190, v128, v82 row_shl:15 row_mask:0xf bank_mask:0xf
	v_fmac_f32_dpp v191, v129, v83 row_shl:15 row_mask:0xf bank_mask:0xf
	v_fmac_f32_dpp v192, v118, v96 row_shl:15 row_mask:0xf bank_mask:0xf
	v_fmac_f32_dpp v193, v119, v97 row_shl:15 row_mask:0xf bank_mask:0xf
	v_fmac_f32_dpp v194, v120, v98 row_shl:15 row_mask:0xf bank_mask:0xf
	v_fmac_f32_dpp v195, v121, v99 row_shl:15 row_mask:0xf bank_mask:0xf
	v_fmac_f32_dpp v188, v126, v76 row_shl:14 row_mask:0xf bank_mask:0xf
	v_fmac_f32_dpp v189, v127, v77 row_shl:14 row_mask:0xf bank_mask:0xf
	v_fmac_f32_dpp v190, v128, v78 row_shl:14 row_mask:0xf bank_mask:0xf
	v_fmac_f32_dpp v191, v129, v79 row_shl:14 row_mask:0xf bank_mask:0xf
	v_fmac_f32_dpp v192, v118, v92 row_shl:14 row_mask:0xf bank_mask:0xf
	v_fmac_f32_dpp v193, v119, v93 row_shl:14 row_mask:0xf bank_mask:0xf
	v_fmac_f32_dpp v194, v120, v94 row_shl:14 row_mask:0xf bank_mask:0xf
	v_fmac_f32_dpp v195, v121, v95 row_shl:14 row_mask:0xf bank_mask:0xf
	v_pk_mul_f32 v[196:197], v[188:189], v[216:217] op_sel_hi:[1,0]
	v_pk_mul_f32 v[198:199], v[190:191], v[216:217] op_sel_hi:[1,0]
	v_exp_f32_e32 v196, v196
	v_exp_f32_e32 v197, v197
	v_exp_f32_e32 v198, v198
	v_exp_f32_e32 v199, v199
	v_pk_add_f32 v[196:197], v[196:197], v[214:215] op_sel_hi:[1,0]
	v_pk_add_f32 v[198:199], v[198:199], v[214:215] op_sel_hi:[1,0]
	v_rcp_f32_e32 v196, v196
	v_rcp_f32_e32 v197, v197
	v_rcp_f32_e32 v198, v198
	v_rcp_f32_e32 v199, v199
	v_pk_mul_f32 v[188:189], v[188:189], v[196:197]
	v_pk_mul_f32 v[190:191], v[190:191], v[198:199]
	v_pk_mul_f32 v[188:189], v[188:189], v[192:193]
	v_pk_mul_f32 v[190:191], v[190:191], v[194:195]
	v_cvt_pk_bf16_f32 v126, v188, v189
	v_cvt_pk_bf16_f32 v127, v190, v191
	v_add_u32_e32 v213, 0x26800, v212
	global_load_dwordx4 v[118:121], v213, s[82:83] offset:16
	v_pk_fma_f32 v[188:189], v[114:115], v[84:85], v[88:89]
	v_pk_fma_f32 v[190:191], v[116:117], v[86:87], v[90:91]
	v_pk_fma_f32 v[192:193], v[68:69], v[100:101], v[104:105]
	v_pk_fma_f32 v[194:195], v[70:71], v[102:103], v[106:107]
	v_fmac_f32_dpp v188, v114, v80 row_shr:1 row_mask:0xf bank_mask:0xf
	v_fmac_f32_dpp v189, v115, v81 row_shr:1 row_mask:0xf bank_mask:0xf
	v_fmac_f32_dpp v190, v116, v82 row_shr:1 row_mask:0xf bank_mask:0xf
	v_fmac_f32_dpp v191, v117, v83 row_shr:1 row_mask:0xf bank_mask:0xf
	v_fmac_f32_dpp v192, v68, v96 row_shr:1 row_mask:0xf bank_mask:0xf
	v_fmac_f32_dpp v193, v69, v97 row_shr:1 row_mask:0xf bank_mask:0xf
	v_fmac_f32_dpp v194, v70, v98 row_shr:1 row_mask:0xf bank_mask:0xf
	v_fmac_f32_dpp v195, v71, v99 row_shr:1 row_mask:0xf bank_mask:0xf
	v_fmac_f32_dpp v188, v114, v76 row_shr:2 row_mask:0xf bank_mask:0xf
	v_fmac_f32_dpp v189, v115, v77 row_shr:2 row_mask:0xf bank_mask:0xf
	v_fmac_f32_dpp v190, v116, v78 row_shr:2 row_mask:0xf bank_mask:0xf
	v_fmac_f32_dpp v191, v117, v79 row_shr:2 row_mask:0xf bank_mask:0xf
	v_fmac_f32_dpp v192, v68, v92 row_shr:2 row_mask:0xf bank_mask:0xf
	v_fmac_f32_dpp v193, v69, v93 row_shr:2 row_mask:0xf bank_mask:0xf
	v_fmac_f32_dpp v194, v70, v94 row_shr:2 row_mask:0xf bank_mask:0xf
	v_fmac_f32_dpp v195, v71, v95 row_shr:2 row_mask:0xf bank_mask:0xf
	v_fmac_f32_dpp v188, v122, v80 row_shl:15 row_mask:0xf bank_mask:0xf
	v_fmac_f32_dpp v189, v123, v81 row_shl:15 row_mask:0xf bank_mask:0xf
	v_fmac_f32_dpp v190, v124, v82 row_shl:15 row_mask:0xf bank_mask:0xf
	v_fmac_f32_dpp v191, v125, v83 row_shl:15 row_mask:0xf bank_mask:0xf
	v_fmac_f32_dpp v192, v110, v96 row_shl:15 row_mask:0xf bank_mask:0xf
	v_fmac_f32_dpp v193, v111, v97 row_shl:15 row_mask:0xf bank_mask:0xf
	v_fmac_f32_dpp v194, v112, v98 row_shl:15 row_mask:0xf bank_mask:0xf
	v_fmac_f32_dpp v195, v113, v99 row_shl:15 row_mask:0xf bank_mask:0xf
	v_fmac_f32_dpp v188, v122, v76 row_shl:14 row_mask:0xf bank_mask:0xf
	v_fmac_f32_dpp v189, v123, v77 row_shl:14 row_mask:0xf bank_mask:0xf
	v_fmac_f32_dpp v190, v124, v78 row_shl:14 row_mask:0xf bank_mask:0xf
	v_fmac_f32_dpp v191, v125, v79 row_shl:14 row_mask:0xf bank_mask:0xf
	v_fmac_f32_dpp v192, v110, v92 row_shl:14 row_mask:0xf bank_mask:0xf
	v_fmac_f32_dpp v193, v111, v93 row_shl:14 row_mask:0xf bank_mask:0xf
	v_fmac_f32_dpp v194, v112, v94 row_shl:14 row_mask:0xf bank_mask:0xf
	v_fmac_f32_dpp v195, v113, v95 row_shl:14 row_mask:0xf bank_mask:0xf
	v_pk_mul_f32 v[196:197], v[188:189], v[216:217] op_sel_hi:[1,0]
	v_pk_mul_f32 v[198:199], v[190:191], v[216:217] op_sel_hi:[1,0]
	v_exp_f32_e32 v196, v196
	v_exp_f32_e32 v197, v197
	v_exp_f32_e32 v198, v198
	v_exp_f32_e32 v199, v199
	v_pk_add_f32 v[196:197], v[196:197], v[214:215] op_sel_hi:[1,0]
	v_pk_add_f32 v[198:199], v[198:199], v[214:215] op_sel_hi:[1,0]
	v_rcp_f32_e32 v196, v196
	v_rcp_f32_e32 v197, v197
	v_rcp_f32_e32 v198, v198
	v_rcp_f32_e32 v199, v199
	v_pk_mul_f32 v[188:189], v[188:189], v[196:197]
	v_pk_mul_f32 v[190:191], v[190:191], v[198:199]
	v_pk_mul_f32 v[188:189], v[188:189], v[192:193]
	v_pk_mul_f32 v[190:191], v[190:191], v[194:195]
	v_cvt_pk_bf16_f32 v122, v188, v189
	v_cvt_pk_bf16_f32 v123, v190, v191
	v_add_u32_e32 v213, 0x31800, v212
	global_load_dwordx4 v[110:113], v213, s[82:83] offset:16
	v_pk_fma_f32 v[188:189], v[72:73], v[84:85], v[88:89]
	v_pk_fma_f32 v[190:191], v[74:75], v[86:87], v[90:91]
	v_pk_fma_f32 v[192:193], v[64:65], v[100:101], v[104:105]
	v_pk_fma_f32 v[194:195], v[66:67], v[102:103], v[106:107]
	v_fmac_f32_dpp v188, v72, v80 row_shr:1 row_mask:0xf bank_mask:0xf
	v_fmac_f32_dpp v189, v73, v81 row_shr:1 row_mask:0xf bank_mask:0xf
	v_fmac_f32_dpp v190, v74, v82 row_shr:1 row_mask:0xf bank_mask:0xf
	v_fmac_f32_dpp v191, v75, v83 row_shr:1 row_mask:0xf bank_mask:0xf
	v_fmac_f32_dpp v192, v64, v96 row_shr:1 row_mask:0xf bank_mask:0xf
	v_fmac_f32_dpp v193, v65, v97 row_shr:1 row_mask:0xf bank_mask:0xf
	v_fmac_f32_dpp v194, v66, v98 row_shr:1 row_mask:0xf bank_mask:0xf
	v_fmac_f32_dpp v195, v67, v99 row_shr:1 row_mask:0xf bank_mask:0xf
	v_fmac_f32_dpp v188, v72, v76 row_shr:2 row_mask:0xf bank_mask:0xf
	v_fmac_f32_dpp v189, v73, v77 row_shr:2 row_mask:0xf bank_mask:0xf
	v_fmac_f32_dpp v190, v74, v78 row_shr:2 row_mask:0xf bank_mask:0xf
	v_fmac_f32_dpp v191, v75, v79 row_shr:2 row_mask:0xf bank_mask:0xf
	v_fmac_f32_dpp v192, v64, v92 row_shr:2 row_mask:0xf bank_mask:0xf
	v_fmac_f32_dpp v193, v65, v93 row_shr:2 row_mask:0xf bank_mask:0xf
	v_fmac_f32_dpp v194, v66, v94 row_shr:2 row_mask:0xf bank_mask:0xf
	v_fmac_f32_dpp v195, v67, v95 row_shr:2 row_mask:0xf bank_mask:0xf
	v_fmac_f32_dpp v188, v114, v80 row_shl:15 row_mask:0xf bank_mask:0xf
	v_fmac_f32_dpp v189, v115, v81 row_shl:15 row_mask:0xf bank_mask:0xf
	v_fmac_f32_dpp v190, v116, v82 row_shl:15 row_mask:0xf bank_mask:0xf
	v_fmac_f32_dpp v191, v117, v83 row_shl:15 row_mask:0xf bank_mask:0xf
	v_fmac_f32_dpp v192, v68, v96 row_shl:15 row_mask:0xf bank_mask:0xf
	v_fmac_f32_dpp v193, v69, v97 row_shl:15 row_mask:0xf bank_mask:0xf
	v_fmac_f32_dpp v194, v70, v98 row_shl:15 row_mask:0xf bank_mask:0xf
	v_fmac_f32_dpp v195, v71, v99 row_shl:15 row_mask:0xf bank_mask:0xf
	v_fmac_f32_dpp v188, v114, v76 row_shl:14 row_mask:0xf bank_mask:0xf
	v_fmac_f32_dpp v189, v115, v77 row_shl:14 row_mask:0xf bank_mask:0xf
	v_fmac_f32_dpp v190, v116, v78 row_shl:14 row_mask:0xf bank_mask:0xf
	v_fmac_f32_dpp v191, v117, v79 row_shl:14 row_mask:0xf bank_mask:0xf
	v_fmac_f32_dpp v192, v68, v92 row_shl:14 row_mask:0xf bank_mask:0xf
	v_fmac_f32_dpp v193, v69, v93 row_shl:14 row_mask:0xf bank_mask:0xf
	v_fmac_f32_dpp v194, v70, v94 row_shl:14 row_mask:0xf bank_mask:0xf
	v_fmac_f32_dpp v195, v71, v95 row_shl:14 row_mask:0xf bank_mask:0xf
	v_pk_mul_f32 v[196:197], v[188:189], v[216:217] op_sel_hi:[1,0]
	v_pk_mul_f32 v[198:199], v[190:191], v[216:217] op_sel_hi:[1,0]
	v_exp_f32_e32 v196, v196
	v_exp_f32_e32 v197, v197
	v_exp_f32_e32 v198, v198
	v_exp_f32_e32 v199, v199
	v_pk_add_f32 v[196:197], v[196:197], v[214:215] op_sel_hi:[1,0]
	v_pk_add_f32 v[198:199], v[198:199], v[214:215] op_sel_hi:[1,0]
	v_rcp_f32_e32 v196, v196
	v_rcp_f32_e32 v197, v197
	v_rcp_f32_e32 v198, v198
	v_rcp_f32_e32 v199, v199
	v_pk_mul_f32 v[188:189], v[188:189], v[196:197]
	v_pk_mul_f32 v[190:191], v[190:191], v[198:199]
	v_pk_mul_f32 v[188:189], v[188:189], v[192:193]
	v_pk_mul_f32 v[190:191], v[190:191], v[194:195]
	v_cvt_pk_bf16_f32 v114, v188, v189
	v_cvt_pk_bf16_f32 v115, v190, v191
	s_waitcnt vmcnt(0)
	v_pk_fma_f32 v[188:189], v[60:61], v[134:135], v[130:131]
	v_pk_fma_f32 v[190:191], v[62:63], v[136:137], v[132:133]
	v_pk_fma_f32 v[192:193], v[56:57], v[204:205], v[208:209]
	v_pk_fma_f32 v[194:195], v[58:59], v[206:207], v[210:211]
	v_fmac_f32_dpp v188, v60, v142 row_shr:1 row_mask:0xf bank_mask:0xf
	v_fmac_f32_dpp v189, v61, v143 row_shr:1 row_mask:0xf bank_mask:0xf
	v_fmac_f32_dpp v190, v62, v144 row_shr:1 row_mask:0xf bank_mask:0xf
	v_fmac_f32_dpp v191, v63, v145 row_shr:1 row_mask:0xf bank_mask:0xf
	v_fmac_f32_dpp v192, v56, v110 row_shr:1 row_mask:0xf bank_mask:0xf
	v_fmac_f32_dpp v193, v57, v111 row_shr:1 row_mask:0xf bank_mask:0xf
	v_fmac_f32_dpp v194, v58, v112 row_shr:1 row_mask:0xf bank_mask:0xf
	v_fmac_f32_dpp v195, v59, v113 row_shr:1 row_mask:0xf bank_mask:0xf
	v_fmac_f32_dpp v188, v60, v154 row_shr:2 row_mask:0xf bank_mask:0xf
	v_fmac_f32_dpp v189, v61, v155 row_shr:2 row_mask:0xf bank_mask:0xf
	v_fmac_f32_dpp v190, v62, v156 row_shr:2 row_mask:0xf bank_mask:0xf
	v_fmac_f32_dpp v191, v63, v157 row_shr:2 row_mask:0xf bank_mask:0xf
	v_fmac_f32_dpp v192, v56, v118 row_shr:2 row_mask:0xf bank_mask:0xf
	v_fmac_f32_dpp v193, v57, v119 row_shr:2 row_mask:0xf bank_mask:0xf
	v_fmac_f32_dpp v194, v58, v120 row_shr:2 row_mask:0xf bank_mask:0xf
	v_fmac_f32_dpp v195, v59, v121 row_shr:2 row_mask:0xf bank_mask:0xf
	v_pk_mul_f32 v[196:197], v[188:189], v[216:217] op_sel_hi:[1,0]
	v_pk_mul_f32 v[198:199], v[190:191], v[216:217] op_sel_hi:[1,0]
	v_exp_f32_e32 v196, v196
	v_exp_f32_e32 v197, v197
	v_exp_f32_e32 v198, v198
	v_exp_f32_e32 v199, v199
	v_pk_add_f32 v[196:197], v[196:197], v[214:215] op_sel_hi:[1,0]
	v_pk_add_f32 v[198:199], v[198:199], v[214:215] op_sel_hi:[1,0]
	v_rcp_f32_e32 v196, v196
	v_rcp_f32_e32 v197, v197
	v_rcp_f32_e32 v198, v198
	v_rcp_f32_e32 v199, v199
	v_pk_mul_f32 v[188:189], v[188:189], v[196:197]
	v_pk_mul_f32 v[190:191], v[190:191], v[198:199]
	v_pk_mul_f32 v[188:189], v[188:189], v[192:193]
	v_pk_mul_f32 v[190:191], v[190:191], v[194:195]
	v_cvt_pk_bf16_f32 v202, v188, v189
	v_cvt_pk_bf16_f32 v203, v190, v191
	s_mov_b64 exec, vcc
	global_store_dwordx4 v215, v[200:203], s[96:97]
	s_mov_b64 exec, -1
	v_pk_fma_f32 v[188:189], v[52:53], v[134:135], v[130:131]
	v_pk_fma_f32 v[190:191], v[54:55], v[136:137], v[132:133]
	v_pk_fma_f32 v[192:193], v[44:45], v[204:205], v[208:209]
	v_pk_fma_f32 v[194:195], v[46:47], v[206:207], v[210:211]
	v_fmac_f32_dpp v188, v52, v142 row_shr:1 row_mask:0xf bank_mask:0xf
	v_fmac_f32_dpp v189, v53, v143 row_shr:1 row_mask:0xf bank_mask:0xf
	v_fmac_f32_dpp v190, v54, v144 row_shr:1 row_mask:0xf bank_mask:0xf
	v_fmac_f32_dpp v191, v55, v145 row_shr:1 row_mask:0xf bank_mask:0xf
	v_fmac_f32_dpp v192, v44, v110 row_shr:1 row_mask:0xf bank_mask:0xf
	v_fmac_f32_dpp v193, v45, v111 row_shr:1 row_mask:0xf bank_mask:0xf
	v_fmac_f32_dpp v194, v46, v112 row_shr:1 row_mask:0xf bank_mask:0xf
	v_fmac_f32_dpp v195, v47, v113 row_shr:1 row_mask:0xf bank_mask:0xf
	v_fmac_f32_dpp v188, v52, v154 row_shr:2 row_mask:0xf bank_mask:0xf
	v_fmac_f32_dpp v189, v53, v155 row_shr:2 row_mask:0xf bank_mask:0xf
	v_fmac_f32_dpp v190, v54, v156 row_shr:2 row_mask:0xf bank_mask:0xf
	v_fmac_f32_dpp v191, v55, v157 row_shr:2 row_mask:0xf bank_mask:0xf
	v_fmac_f32_dpp v192, v44, v118 row_shr:2 row_mask:0xf bank_mask:0xf
	v_fmac_f32_dpp v193, v45, v119 row_shr:2 row_mask:0xf bank_mask:0xf
	v_fmac_f32_dpp v194, v46, v120 row_shr:2 row_mask:0xf bank_mask:0xf
	v_fmac_f32_dpp v195, v47, v121 row_shr:2 row_mask:0xf bank_mask:0xf
	v_fmac_f32_dpp v188, v60, v142 row_shl:15 row_mask:0xf bank_mask:0xf
	v_fmac_f32_dpp v189, v61, v143 row_shl:15 row_mask:0xf bank_mask:0xf
	v_fmac_f32_dpp v190, v62, v144 row_shl:15 row_mask:0xf bank_mask:0xf
	v_fmac_f32_dpp v191, v63, v145 row_shl:15 row_mask:0xf bank_mask:0xf
	v_fmac_f32_dpp v192, v56, v110 row_shl:15 row_mask:0xf bank_mask:0xf
	v_fmac_f32_dpp v193, v57, v111 row_shl:15 row_mask:0xf bank_mask:0xf
	v_fmac_f32_dpp v194, v58, v112 row_shl:15 row_mask:0xf bank_mask:0xf
	v_fmac_f32_dpp v195, v59, v113 row_shl:15 row_mask:0xf bank_mask:0xf
	v_fmac_f32_dpp v188, v60, v154 row_shl:14 row_mask:0xf bank_mask:0xf
	v_fmac_f32_dpp v189, v61, v155 row_shl:14 row_mask:0xf bank_mask:0xf
	v_fmac_f32_dpp v190, v62, v156 row_shl:14 row_mask:0xf bank_mask:0xf
	v_fmac_f32_dpp v191, v63, v157 row_shl:14 row_mask:0xf bank_mask:0xf
	v_fmac_f32_dpp v192, v56, v118 row_shl:14 row_mask:0xf bank_mask:0xf
	v_fmac_f32_dpp v193, v57, v119 row_shl:14 row_mask:0xf bank_mask:0xf
	v_fmac_f32_dpp v194, v58, v120 row_shl:14 row_mask:0xf bank_mask:0xf
	v_fmac_f32_dpp v195, v59, v121 row_shl:14 row_mask:0xf bank_mask:0xf
	v_pk_mul_f32 v[196:197], v[188:189], v[216:217] op_sel_hi:[1,0]
	v_pk_mul_f32 v[198:199], v[190:191], v[216:217] op_sel_hi:[1,0]
	v_exp_f32_e32 v196, v196
	v_exp_f32_e32 v197, v197
	v_exp_f32_e32 v198, v198
	v_exp_f32_e32 v199, v199
	v_pk_add_f32 v[196:197], v[196:197], v[214:215] op_sel_hi:[1,0]
	v_pk_add_f32 v[198:199], v[198:199], v[214:215] op_sel_hi:[1,0]
	v_rcp_f32_e32 v196, v196
	v_rcp_f32_e32 v197, v197
	v_rcp_f32_e32 v198, v198
	v_rcp_f32_e32 v199, v199
	v_pk_mul_f32 v[188:189], v[188:189], v[196:197]
	v_pk_mul_f32 v[190:191], v[190:191], v[198:199]
	v_pk_mul_f32 v[188:189], v[188:189], v[192:193]
	v_pk_mul_f32 v[190:191], v[190:191], v[194:195]
	v_cvt_pk_bf16_f32 v160, v188, v189
	v_cvt_pk_bf16_f32 v161, v190, v191
	v_add_u32_e32 v213, 0x2c000, v215
	global_store_dwordx4 v213, v[158:161], s[96:97]
	v_pk_fma_f32 v[188:189], v[48:49], v[134:135], v[130:131]
	v_pk_fma_f32 v[190:191], v[50:51], v[136:137], v[132:133]
	v_pk_fma_f32 v[192:193], v[36:37], v[204:205], v[208:209]
	v_pk_fma_f32 v[194:195], v[38:39], v[206:207], v[210:211]
	v_fmac_f32_dpp v188, v48, v142 row_shr:1 row_mask:0xf bank_mask:0xf
	v_fmac_f32_dpp v189, v49, v143 row_shr:1 row_mask:0xf bank_mask:0xf
	v_fmac_f32_dpp v190, v50, v144 row_shr:1 row_mask:0xf bank_mask:0xf
	v_fmac_f32_dpp v191, v51, v145 row_shr:1 row_mask:0xf bank_mask:0xf
	v_fmac_f32_dpp v192, v36, v110 row_shr:1 row_mask:0xf bank_mask:0xf
	v_fmac_f32_dpp v193, v37, v111 row_shr:1 row_mask:0xf bank_mask:0xf
	v_fmac_f32_dpp v194, v38, v112 row_shr:1 row_mask:0xf bank_mask:0xf
	v_fmac_f32_dpp v195, v39, v113 row_shr:1 row_mask:0xf bank_mask:0xf
	v_fmac_f32_dpp v188, v48, v154 row_shr:2 row_mask:0xf bank_mask:0xf
	v_fmac_f32_dpp v189, v49, v155 row_shr:2 row_mask:0xf bank_mask:0xf
	v_fmac_f32_dpp v190, v50, v156 row_shr:2 row_mask:0xf bank_mask:0xf
	v_fmac_f32_dpp v191, v51, v157 row_shr:2 row_mask:0xf bank_mask:0xf
	v_fmac_f32_dpp v192, v36, v118 row_shr:2 row_mask:0xf bank_mask:0xf
	v_fmac_f32_dpp v193, v37, v119 row_shr:2 row_mask:0xf bank_mask:0xf
	v_fmac_f32_dpp v194, v38, v120 row_shr:2 row_mask:0xf bank_mask:0xf
	v_fmac_f32_dpp v195, v39, v121 row_shr:2 row_mask:0xf bank_mask:0xf
	v_fmac_f32_dpp v188, v52, v142 row_shl:15 row_mask:0xf bank_mask:0xf
	v_fmac_f32_dpp v189, v53, v143 row_shl:15 row_mask:0xf bank_mask:0xf
	v_fmac_f32_dpp v190, v54, v144 row_shl:15 row_mask:0xf bank_mask:0xf
	v_fmac_f32_dpp v191, v55, v145 row_shl:15 row_mask:0xf bank_mask:0xf
	v_fmac_f32_dpp v192, v44, v110 row_shl:15 row_mask:0xf bank_mask:0xf
	v_fmac_f32_dpp v193, v45, v111 row_shl:15 row_mask:0xf bank_mask:0xf
	v_fmac_f32_dpp v194, v46, v112 row_shl:15 row_mask:0xf bank_mask:0xf
	v_fmac_f32_dpp v195, v47, v113 row_shl:15 row_mask:0xf bank_mask:0xf
	v_fmac_f32_dpp v188, v52, v154 row_shl:14 row_mask:0xf bank_mask:0xf
	v_fmac_f32_dpp v189, v53, v155 row_shl:14 row_mask:0xf bank_mask:0xf
	v_fmac_f32_dpp v190, v54, v156 row_shl:14 row_mask:0xf bank_mask:0xf
	v_fmac_f32_dpp v191, v55, v157 row_shl:14 row_mask:0xf bank_mask:0xf
	v_fmac_f32_dpp v192, v44, v118 row_shl:14 row_mask:0xf bank_mask:0xf
	v_fmac_f32_dpp v193, v45, v119 row_shl:14 row_mask:0xf bank_mask:0xf
	v_fmac_f32_dpp v194, v46, v120 row_shl:14 row_mask:0xf bank_mask:0xf
	v_fmac_f32_dpp v195, v47, v121 row_shl:14 row_mask:0xf bank_mask:0xf
	v_pk_mul_f32 v[196:197], v[188:189], v[216:217] op_sel_hi:[1,0]
	v_pk_mul_f32 v[198:199], v[190:191], v[216:217] op_sel_hi:[1,0]
	v_exp_f32_e32 v196, v196
	v_exp_f32_e32 v197, v197
	v_exp_f32_e32 v198, v198
	v_exp_f32_e32 v199, v199
	v_pk_add_f32 v[196:197], v[196:197], v[214:215] op_sel_hi:[1,0]
	v_pk_add_f32 v[198:199], v[198:199], v[214:215] op_sel_hi:[1,0]
	v_rcp_f32_e32 v196, v196
	v_rcp_f32_e32 v197, v197
	v_rcp_f32_e32 v198, v198
	v_rcp_f32_e32 v199, v199
	v_pk_mul_f32 v[188:189], v[188:189], v[196:197]
	v_pk_mul_f32 v[190:191], v[190:191], v[198:199]
	v_pk_mul_f32 v[188:189], v[188:189], v[192:193]
	v_pk_mul_f32 v[190:191], v[190:191], v[194:195]
	v_cvt_pk_bf16_f32 v152, v188, v189
	v_cvt_pk_bf16_f32 v153, v190, v191
	v_add_u32_e32 v213, 0x58000, v215
	global_store_dwordx4 v213, v[150:153], s[96:97]
	v_pk_fma_f32 v[188:189], v[40:41], v[134:135], v[130:131]
	v_pk_fma_f32 v[190:191], v[42:43], v[136:137], v[132:133]
	v_pk_fma_f32 v[192:193], v[32:33], v[204:205], v[208:209]
	v_pk_fma_f32 v[194:195], v[34:35], v[206:207], v[210:211]
	v_fmac_f32_dpp v188, v40, v142 row_shr:1 row_mask:0xf bank_mask:0xf
	v_fmac_f32_dpp v189, v41, v143 row_shr:1 row_mask:0xf bank_mask:0xf
	v_fmac_f32_dpp v190, v42, v144 row_shr:1 row_mask:0xf bank_mask:0xf
	v_fmac_f32_dpp v191, v43, v145 row_shr:1 row_mask:0xf bank_mask:0xf
	v_fmac_f32_dpp v192, v32, v110 row_shr:1 row_mask:0xf bank_mask:0xf
	v_fmac_f32_dpp v193, v33, v111 row_shr:1 row_mask:0xf bank_mask:0xf
	v_fmac_f32_dpp v194, v34, v112 row_shr:1 row_mask:0xf bank_mask:0xf
	v_fmac_f32_dpp v195, v35, v113 row_shr:1 row_mask:0xf bank_mask:0xf
	v_fmac_f32_dpp v188, v40, v154 row_shr:2 row_mask:0xf bank_mask:0xf
	v_fmac_f32_dpp v189, v41, v155 row_shr:2 row_mask:0xf bank_mask:0xf
	v_fmac_f32_dpp v190, v42, v156 row_shr:2 row_mask:0xf bank_mask:0xf
	v_fmac_f32_dpp v191, v43, v157 row_shr:2 row_mask:0xf bank_mask:0xf
	v_fmac_f32_dpp v192, v32, v118 row_shr:2 row_mask:0xf bank_mask:0xf
	v_fmac_f32_dpp v193, v33, v119 row_shr:2 row_mask:0xf bank_mask:0xf
	v_fmac_f32_dpp v194, v34, v120 row_shr:2 row_mask:0xf bank_mask:0xf
	v_fmac_f32_dpp v195, v35, v121 row_shr:2 row_mask:0xf bank_mask:0xf
	v_fmac_f32_dpp v188, v48, v142 row_shl:15 row_mask:0xf bank_mask:0xf
	v_fmac_f32_dpp v189, v49, v143 row_shl:15 row_mask:0xf bank_mask:0xf
	v_fmac_f32_dpp v190, v50, v144 row_shl:15 row_mask:0xf bank_mask:0xf
	v_fmac_f32_dpp v191, v51, v145 row_shl:15 row_mask:0xf bank_mask:0xf
	v_fmac_f32_dpp v192, v36, v110 row_shl:15 row_mask:0xf bank_mask:0xf
	v_fmac_f32_dpp v193, v37, v111 row_shl:15 row_mask:0xf bank_mask:0xf
	v_fmac_f32_dpp v194, v38, v112 row_shl:15 row_mask:0xf bank_mask:0xf
	v_fmac_f32_dpp v195, v39, v113 row_shl:15 row_mask:0xf bank_mask:0xf
	v_fmac_f32_dpp v188, v48, v154 row_shl:14 row_mask:0xf bank_mask:0xf
	v_fmac_f32_dpp v189, v49, v155 row_shl:14 row_mask:0xf bank_mask:0xf
	v_fmac_f32_dpp v190, v50, v156 row_shl:14 row_mask:0xf bank_mask:0xf
	v_fmac_f32_dpp v191, v51, v157 row_shl:14 row_mask:0xf bank_mask:0xf
	v_fmac_f32_dpp v192, v36, v118 row_shl:14 row_mask:0xf bank_mask:0xf
	v_fmac_f32_dpp v193, v37, v119 row_shl:14 row_mask:0xf bank_mask:0xf
	v_fmac_f32_dpp v194, v38, v120 row_shl:14 row_mask:0xf bank_mask:0xf
	v_fmac_f32_dpp v195, v39, v121 row_shl:14 row_mask:0xf bank_mask:0xf
	v_pk_mul_f32 v[196:197], v[188:189], v[216:217] op_sel_hi:[1,0]
	v_pk_mul_f32 v[198:199], v[190:191], v[216:217] op_sel_hi:[1,0]
	v_exp_f32_e32 v196, v196
	v_exp_f32_e32 v197, v197
	v_exp_f32_e32 v198, v198
	v_exp_f32_e32 v199, v199
	v_pk_add_f32 v[196:197], v[196:197], v[214:215] op_sel_hi:[1,0]
	v_pk_add_f32 v[198:199], v[198:199], v[214:215] op_sel_hi:[1,0]
	v_rcp_f32_e32 v196, v196
	v_rcp_f32_e32 v197, v197
	v_rcp_f32_e32 v198, v198
	v_rcp_f32_e32 v199, v199
	v_pk_mul_f32 v[188:189], v[188:189], v[196:197]
	v_pk_mul_f32 v[190:191], v[190:191], v[198:199]
	v_pk_mul_f32 v[188:189], v[188:189], v[192:193]
	v_pk_mul_f32 v[190:191], v[190:191], v[194:195]
	v_cvt_pk_bf16_f32 v148, v188, v189
	v_cvt_pk_bf16_f32 v149, v190, v191
	v_add_u32_e32 v213, 0x84000, v215
	global_store_dwordx4 v213, v[146:149], s[96:97]
	v_pk_fma_f32 v[188:189], v[28:29], v[134:135], v[130:131]
	v_pk_fma_f32 v[190:191], v[30:31], v[136:137], v[132:133]
	v_pk_fma_f32 v[192:193], v[16:17], v[204:205], v[208:209]
	v_pk_fma_f32 v[194:195], v[18:19], v[206:207], v[210:211]
	v_fmac_f32_dpp v188, v28, v142 row_shr:1 row_mask:0xf bank_mask:0xf
	v_fmac_f32_dpp v189, v29, v143 row_shr:1 row_mask:0xf bank_mask:0xf
	v_fmac_f32_dpp v190, v30, v144 row_shr:1 row_mask:0xf bank_mask:0xf
	v_fmac_f32_dpp v191, v31, v145 row_shr:1 row_mask:0xf bank_mask:0xf
	v_fmac_f32_dpp v192, v16, v110 row_shr:1 row_mask:0xf bank_mask:0xf
	v_fmac_f32_dpp v193, v17, v111 row_shr:1 row_mask:0xf bank_mask:0xf
	v_fmac_f32_dpp v194, v18, v112 row_shr:1 row_mask:0xf bank_mask:0xf
	v_fmac_f32_dpp v195, v19, v113 row_shr:1 row_mask:0xf bank_mask:0xf
	v_fmac_f32_dpp v188, v28, v154 row_shr:2 row_mask:0xf bank_mask:0xf
	v_fmac_f32_dpp v189, v29, v155 row_shr:2 row_mask:0xf bank_mask:0xf
	v_fmac_f32_dpp v190, v30, v156 row_shr:2 row_mask:0xf bank_mask:0xf
	v_fmac_f32_dpp v191, v31, v157 row_shr:2 row_mask:0xf bank_mask:0xf
	v_fmac_f32_dpp v192, v16, v118 row_shr:2 row_mask:0xf bank_mask:0xf
	v_fmac_f32_dpp v193, v17, v119 row_shr:2 row_mask:0xf bank_mask:0xf
	v_fmac_f32_dpp v194, v18, v120 row_shr:2 row_mask:0xf bank_mask:0xf
	v_fmac_f32_dpp v195, v19, v121 row_shr:2 row_mask:0xf bank_mask:0xf
	v_fmac_f32_dpp v188, v40, v142 row_shl:15 row_mask:0xf bank_mask:0xf
	v_fmac_f32_dpp v189, v41, v143 row_shl:15 row_mask:0xf bank_mask:0xf
	v_fmac_f32_dpp v190, v42, v144 row_shl:15 row_mask:0xf bank_mask:0xf
	v_fmac_f32_dpp v191, v43, v145 row_shl:15 row_mask:0xf bank_mask:0xf
	v_fmac_f32_dpp v192, v32, v110 row_shl:15 row_mask:0xf bank_mask:0xf
	v_fmac_f32_dpp v193, v33, v111 row_shl:15 row_mask:0xf bank_mask:0xf
	v_fmac_f32_dpp v194, v34, v112 row_shl:15 row_mask:0xf bank_mask:0xf
	v_fmac_f32_dpp v195, v35, v113 row_shl:15 row_mask:0xf bank_mask:0xf
	v_fmac_f32_dpp v188, v40, v154 row_shl:14 row_mask:0xf bank_mask:0xf
	v_fmac_f32_dpp v189, v41, v155 row_shl:14 row_mask:0xf bank_mask:0xf
	v_fmac_f32_dpp v190, v42, v156 row_shl:14 row_mask:0xf bank_mask:0xf
	v_fmac_f32_dpp v191, v43, v157 row_shl:14 row_mask:0xf bank_mask:0xf
	v_fmac_f32_dpp v192, v32, v118 row_shl:14 row_mask:0xf bank_mask:0xf
	v_fmac_f32_dpp v193, v33, v119 row_shl:14 row_mask:0xf bank_mask:0xf
	v_fmac_f32_dpp v194, v34, v120 row_shl:14 row_mask:0xf bank_mask:0xf
	v_fmac_f32_dpp v195, v35, v121 row_shl:14 row_mask:0xf bank_mask:0xf
	v_pk_mul_f32 v[196:197], v[188:189], v[216:217] op_sel_hi:[1,0]
	v_pk_mul_f32 v[198:199], v[190:191], v[216:217] op_sel_hi:[1,0]
	v_exp_f32_e32 v196, v196
	v_exp_f32_e32 v197, v197
	v_exp_f32_e32 v198, v198
	v_exp_f32_e32 v199, v199
	v_pk_add_f32 v[196:197], v[196:197], v[214:215] op_sel_hi:[1,0]
	v_pk_add_f32 v[198:199], v[198:199], v[214:215] op_sel_hi:[1,0]
	v_rcp_f32_e32 v196, v196
	v_rcp_f32_e32 v197, v197
	v_rcp_f32_e32 v198, v198
	v_rcp_f32_e32 v199, v199
	v_pk_mul_f32 v[188:189], v[188:189], v[196:197]
	v_pk_mul_f32 v[190:191], v[190:191], v[198:199]
	v_pk_mul_f32 v[188:189], v[188:189], v[192:193]
	v_pk_mul_f32 v[190:191], v[190:191], v[194:195]
	v_cvt_pk_bf16_f32 v140, v188, v189
	v_cvt_pk_bf16_f32 v141, v190, v191
	v_add_u32_e32 v213, 0xb0000, v215
	global_store_dwordx4 v213, v[138:141], s[96:97]
	v_pk_fma_f32 v[188:189], v[24:25], v[134:135], v[130:131]
	v_pk_fma_f32 v[190:191], v[26:27], v[136:137], v[132:133]
	v_pk_fma_f32 v[192:193], v[12:13], v[204:205], v[208:209]
	v_pk_fma_f32 v[194:195], v[14:15], v[206:207], v[210:211]
	v_fmac_f32_dpp v188, v24, v142 row_shr:1 row_mask:0xf bank_mask:0xf
	v_fmac_f32_dpp v189, v25, v143 row_shr:1 row_mask:0xf bank_mask:0xf
	v_fmac_f32_dpp v190, v26, v144 row_shr:1 row_mask:0xf bank_mask:0xf
	v_fmac_f32_dpp v191, v27, v145 row_shr:1 row_mask:0xf bank_mask:0xf
	v_fmac_f32_dpp v192, v12, v110 row_shr:1 row_mask:0xf bank_mask:0xf
	v_fmac_f32_dpp v193, v13, v111 row_shr:1 row_mask:0xf bank_mask:0xf
	v_fmac_f32_dpp v194, v14, v112 row_shr:1 row_mask:0xf bank_mask:0xf
	v_fmac_f32_dpp v195, v15, v113 row_shr:1 row_mask:0xf bank_mask:0xf
	v_fmac_f32_dpp v188, v24, v154 row_shr:2 row_mask:0xf bank_mask:0xf
	v_fmac_f32_dpp v189, v25, v155 row_shr:2 row_mask:0xf bank_mask:0xf
	v_fmac_f32_dpp v190, v26, v156 row_shr:2 row_mask:0xf bank_mask:0xf
	v_fmac_f32_dpp v191, v27, v157 row_shr:2 row_mask:0xf bank_mask:0xf
	v_fmac_f32_dpp v192, v12, v118 row_shr:2 row_mask:0xf bank_mask:0xf
	v_fmac_f32_dpp v193, v13, v119 row_shr:2 row_mask:0xf bank_mask:0xf
	v_fmac_f32_dpp v194, v14, v120 row_shr:2 row_mask:0xf bank_mask:0xf
	v_fmac_f32_dpp v195, v15, v121 row_shr:2 row_mask:0xf bank_mask:0xf
	v_fmac_f32_dpp v188, v28, v142 row_shl:15 row_mask:0xf bank_mask:0xf
	v_fmac_f32_dpp v189, v29, v143 row_shl:15 row_mask:0xf bank_mask:0xf
	v_fmac_f32_dpp v190, v30, v144 row_shl:15 row_mask:0xf bank_mask:0xf
	v_fmac_f32_dpp v191, v31, v145 row_shl:15 row_mask:0xf bank_mask:0xf
	v_fmac_f32_dpp v192, v16, v110 row_shl:15 row_mask:0xf bank_mask:0xf
	v_fmac_f32_dpp v193, v17, v111 row_shl:15 row_mask:0xf bank_mask:0xf
	v_fmac_f32_dpp v194, v18, v112 row_shl:15 row_mask:0xf bank_mask:0xf
	v_fmac_f32_dpp v195, v19, v113 row_shl:15 row_mask:0xf bank_mask:0xf
	v_fmac_f32_dpp v188, v28, v154 row_shl:14 row_mask:0xf bank_mask:0xf
	v_fmac_f32_dpp v189, v29, v155 row_shl:14 row_mask:0xf bank_mask:0xf
	v_fmac_f32_dpp v190, v30, v156 row_shl:14 row_mask:0xf bank_mask:0xf
	v_fmac_f32_dpp v191, v31, v157 row_shl:14 row_mask:0xf bank_mask:0xf
	v_fmac_f32_dpp v192, v16, v118 row_shl:14 row_mask:0xf bank_mask:0xf
	v_fmac_f32_dpp v193, v17, v119 row_shl:14 row_mask:0xf bank_mask:0xf
	v_fmac_f32_dpp v194, v18, v120 row_shl:14 row_mask:0xf bank_mask:0xf
	v_fmac_f32_dpp v195, v19, v121 row_shl:14 row_mask:0xf bank_mask:0xf
	v_pk_mul_f32 v[196:197], v[188:189], v[216:217] op_sel_hi:[1,0]
	v_pk_mul_f32 v[198:199], v[190:191], v[216:217] op_sel_hi:[1,0]
	v_exp_f32_e32 v196, v196
	v_exp_f32_e32 v197, v197
	v_exp_f32_e32 v198, v198
	v_exp_f32_e32 v199, v199
	v_pk_add_f32 v[196:197], v[196:197], v[214:215] op_sel_hi:[1,0]
	v_pk_add_f32 v[198:199], v[198:199], v[214:215] op_sel_hi:[1,0]
	v_rcp_f32_e32 v196, v196
	v_rcp_f32_e32 v197, v197
	v_rcp_f32_e32 v198, v198
	v_rcp_f32_e32 v199, v199
	v_pk_mul_f32 v[188:189], v[188:189], v[196:197]
	v_pk_mul_f32 v[190:191], v[190:191], v[198:199]
	v_pk_mul_f32 v[188:189], v[188:189], v[192:193]
	v_pk_mul_f32 v[190:191], v[190:191], v[194:195]
	v_cvt_pk_bf16_f32 v128, v188, v189
	v_cvt_pk_bf16_f32 v129, v190, v191
	v_add_u32_e32 v213, 0xdc000, v215
	global_store_dwordx4 v213, v[126:129], s[96:97]
	v_pk_fma_f32 v[188:189], v[20:21], v[134:135], v[130:131]
	v_pk_fma_f32 v[190:191], v[22:23], v[136:137], v[132:133]
	v_pk_fma_f32 v[192:193], v[8:9], v[204:205], v[208:209]
	v_pk_fma_f32 v[194:195], v[10:11], v[206:207], v[210:211]
	v_fmac_f32_dpp v188, v20, v142 row_shr:1 row_mask:0xf bank_mask:0xf
	v_fmac_f32_dpp v189, v21, v143 row_shr:1 row_mask:0xf bank_mask:0xf
	v_fmac_f32_dpp v190, v22, v144 row_shr:1 row_mask:0xf bank_mask:0xf
	v_fmac_f32_dpp v191, v23, v145 row_shr:1 row_mask:0xf bank_mask:0xf
	v_fmac_f32_dpp v192, v8, v110 row_shr:1 row_mask:0xf bank_mask:0xf
	v_fmac_f32_dpp v193, v9, v111 row_shr:1 row_mask:0xf bank_mask:0xf
	v_fmac_f32_dpp v194, v10, v112 row_shr:1 row_mask:0xf bank_mask:0xf
	v_fmac_f32_dpp v195, v11, v113 row_shr:1 row_mask:0xf bank_mask:0xf
	v_fmac_f32_dpp v188, v20, v154 row_shr:2 row_mask:0xf bank_mask:0xf
	v_fmac_f32_dpp v189, v21, v155 row_shr:2 row_mask:0xf bank_mask:0xf
	v_fmac_f32_dpp v190, v22, v156 row_shr:2 row_mask:0xf bank_mask:0xf
	v_fmac_f32_dpp v191, v23, v157 row_shr:2 row_mask:0xf bank_mask:0xf
	v_fmac_f32_dpp v192, v8, v118 row_shr:2 row_mask:0xf bank_mask:0xf
	v_fmac_f32_dpp v193, v9, v119 row_shr:2 row_mask:0xf bank_mask:0xf
	v_fmac_f32_dpp v194, v10, v120 row_shr:2 row_mask:0xf bank_mask:0xf
	v_fmac_f32_dpp v195, v11, v121 row_shr:2 row_mask:0xf bank_mask:0xf
	v_fmac_f32_dpp v188, v24, v142 row_shl:15 row_mask:0xf bank_mask:0xf
	v_fmac_f32_dpp v189, v25, v143 row_shl:15 row_mask:0xf bank_mask:0xf
	v_fmac_f32_dpp v190, v26, v144 row_shl:15 row_mask:0xf bank_mask:0xf
	v_fmac_f32_dpp v191, v27, v145 row_shl:15 row_mask:0xf bank_mask:0xf
	v_fmac_f32_dpp v192, v12, v110 row_shl:15 row_mask:0xf bank_mask:0xf
	v_fmac_f32_dpp v193, v13, v111 row_shl:15 row_mask:0xf bank_mask:0xf
	v_fmac_f32_dpp v194, v14, v112 row_shl:15 row_mask:0xf bank_mask:0xf
	v_fmac_f32_dpp v195, v15, v113 row_shl:15 row_mask:0xf bank_mask:0xf
	v_fmac_f32_dpp v188, v24, v154 row_shl:14 row_mask:0xf bank_mask:0xf
	v_fmac_f32_dpp v189, v25, v155 row_shl:14 row_mask:0xf bank_mask:0xf
	v_fmac_f32_dpp v190, v26, v156 row_shl:14 row_mask:0xf bank_mask:0xf
	v_fmac_f32_dpp v191, v27, v157 row_shl:14 row_mask:0xf bank_mask:0xf
	v_fmac_f32_dpp v192, v12, v118 row_shl:14 row_mask:0xf bank_mask:0xf
	v_fmac_f32_dpp v193, v13, v119 row_shl:14 row_mask:0xf bank_mask:0xf
	v_fmac_f32_dpp v194, v14, v120 row_shl:14 row_mask:0xf bank_mask:0xf
	v_fmac_f32_dpp v195, v15, v121 row_shl:14 row_mask:0xf bank_mask:0xf
	v_pk_mul_f32 v[196:197], v[188:189], v[216:217] op_sel_hi:[1,0]
	v_pk_mul_f32 v[198:199], v[190:191], v[216:217] op_sel_hi:[1,0]
	v_exp_f32_e32 v196, v196
	v_exp_f32_e32 v197, v197
	v_exp_f32_e32 v198, v198
	v_exp_f32_e32 v199, v199
	v_pk_add_f32 v[196:197], v[196:197], v[214:215] op_sel_hi:[1,0]
	v_pk_add_f32 v[198:199], v[198:199], v[214:215] op_sel_hi:[1,0]
	v_rcp_f32_e32 v196, v196
	v_rcp_f32_e32 v197, v197
	v_rcp_f32_e32 v198, v198
	v_rcp_f32_e32 v199, v199
	v_pk_mul_f32 v[188:189], v[188:189], v[196:197]
	v_pk_mul_f32 v[190:191], v[190:191], v[198:199]
	v_pk_mul_f32 v[188:189], v[188:189], v[192:193]
	v_pk_mul_f32 v[190:191], v[190:191], v[194:195]
	v_cvt_pk_bf16_f32 v124, v188, v189
	v_cvt_pk_bf16_f32 v125, v190, v191
	v_add_u32_e32 v213, 0x108000, v215
	global_store_dwordx4 v213, v[122:125], s[96:97]
	v_pk_fma_f32 v[188:189], v[4:5], v[134:135], v[130:131]
	v_pk_fma_f32 v[190:191], v[6:7], v[136:137], v[132:133]
	v_pk_fma_f32 v[192:193], v[0:1], v[204:205], v[208:209]
	v_pk_fma_f32 v[194:195], v[2:3], v[206:207], v[210:211]
	v_fmac_f32_dpp v188, v4, v142 row_shr:1 row_mask:0xf bank_mask:0xf
	v_fmac_f32_dpp v189, v5, v143 row_shr:1 row_mask:0xf bank_mask:0xf
	v_fmac_f32_dpp v190, v6, v144 row_shr:1 row_mask:0xf bank_mask:0xf
	v_fmac_f32_dpp v191, v7, v145 row_shr:1 row_mask:0xf bank_mask:0xf
	v_fmac_f32_dpp v192, v0, v110 row_shr:1 row_mask:0xf bank_mask:0xf
	v_fmac_f32_dpp v193, v1, v111 row_shr:1 row_mask:0xf bank_mask:0xf
	v_fmac_f32_dpp v194, v2, v112 row_shr:1 row_mask:0xf bank_mask:0xf
	v_fmac_f32_dpp v195, v3, v113 row_shr:1 row_mask:0xf bank_mask:0xf
	v_fmac_f32_dpp v188, v4, v154 row_shr:2 row_mask:0xf bank_mask:0xf
	v_fmac_f32_dpp v189, v5, v155 row_shr:2 row_mask:0xf bank_mask:0xf
	v_fmac_f32_dpp v190, v6, v156 row_shr:2 row_mask:0xf bank_mask:0xf
	v_fmac_f32_dpp v191, v7, v157 row_shr:2 row_mask:0xf bank_mask:0xf
	v_fmac_f32_dpp v192, v0, v118 row_shr:2 row_mask:0xf bank_mask:0xf
	v_fmac_f32_dpp v193, v1, v119 row_shr:2 row_mask:0xf bank_mask:0xf
	v_fmac_f32_dpp v194, v2, v120 row_shr:2 row_mask:0xf bank_mask:0xf
	v_fmac_f32_dpp v195, v3, v121 row_shr:2 row_mask:0xf bank_mask:0xf
	v_fmac_f32_dpp v188, v20, v142 row_shl:15 row_mask:0xf bank_mask:0xf
	v_fmac_f32_dpp v189, v21, v143 row_shl:15 row_mask:0xf bank_mask:0xf
	v_fmac_f32_dpp v190, v22, v144 row_shl:15 row_mask:0xf bank_mask:0xf
	v_fmac_f32_dpp v191, v23, v145 row_shl:15 row_mask:0xf bank_mask:0xf
	v_fmac_f32_dpp v192, v8, v110 row_shl:15 row_mask:0xf bank_mask:0xf
	v_fmac_f32_dpp v193, v9, v111 row_shl:15 row_mask:0xf bank_mask:0xf
	v_fmac_f32_dpp v194, v10, v112 row_shl:15 row_mask:0xf bank_mask:0xf
	v_fmac_f32_dpp v195, v11, v113 row_shl:15 row_mask:0xf bank_mask:0xf
	v_fmac_f32_dpp v188, v20, v154 row_shl:14 row_mask:0xf bank_mask:0xf
	v_fmac_f32_dpp v189, v21, v155 row_shl:14 row_mask:0xf bank_mask:0xf
	v_fmac_f32_dpp v190, v22, v156 row_shl:14 row_mask:0xf bank_mask:0xf
	v_fmac_f32_dpp v191, v23, v157 row_shl:14 row_mask:0xf bank_mask:0xf
	v_fmac_f32_dpp v192, v8, v118 row_shl:14 row_mask:0xf bank_mask:0xf
	v_fmac_f32_dpp v193, v9, v119 row_shl:14 row_mask:0xf bank_mask:0xf
	v_fmac_f32_dpp v194, v10, v120 row_shl:14 row_mask:0xf bank_mask:0xf
	v_fmac_f32_dpp v195, v11, v121 row_shl:14 row_mask:0xf bank_mask:0xf
	v_pk_mul_f32 v[196:197], v[188:189], v[216:217] op_sel_hi:[1,0]
	v_pk_mul_f32 v[198:199], v[190:191], v[216:217] op_sel_hi:[1,0]
	v_exp_f32_e32 v196, v196
	v_exp_f32_e32 v197, v197
	v_exp_f32_e32 v198, v198
	v_exp_f32_e32 v199, v199
	v_pk_add_f32 v[196:197], v[196:197], v[214:215] op_sel_hi:[1,0]
	v_pk_add_f32 v[198:199], v[198:199], v[214:215] op_sel_hi:[1,0]
	v_rcp_f32_e32 v196, v196
	v_rcp_f32_e32 v197, v197
	v_rcp_f32_e32 v198, v198
	v_rcp_f32_e32 v199, v199
	v_pk_mul_f32 v[188:189], v[188:189], v[196:197]
	v_pk_mul_f32 v[190:191], v[190:191], v[198:199]
	v_pk_mul_f32 v[188:189], v[188:189], v[192:193]
	v_pk_mul_f32 v[190:191], v[190:191], v[194:195]
	v_cvt_pk_bf16_f32 v116, v188, v189
	v_cvt_pk_bf16_f32 v117, v190, v191
	v_add_u32_e32 v213, 0x134000, v215
	global_store_dwordx4 v213, v[114:117], s[96:97]
	s_branch .LBB0_836
